# DPP quad/half-mirror moves for the xor1/2/4 importance shuffles in the NSA compressed branch; remaining xor32 row-sum shuffles via permlane32 swap
# speedup vs baseline: 1.0494x; 1.0057x over previous
.LBB0_1108:
	s_or_b64 exec, exec, s[2:3]
	v_readlane_b32 s2, v251, 0
	s_lshr_b32 s1, s0, 4
	v_readlane_b32 s3, v251, 1
	s_and_b64 s[2:3], s[2:3], exec
	s_cselect_b32 s1, s0, s1
	s_lshr_b32 s0, s7, 1
	s_lshl_b32 s92, s1, 5
	s_lshl_b32 s1, s7, 3
	s_sub_i32 s95, 0x7e0, s92
	v_and_or_b32 v78, s1, 8, v159
	s_lshl_b32 s1, s0, 22
	v_readlane_b32 s2, v250, 21
	s_add_u32 s2, s2, s1
	v_readlane_b32 s1, v250, 22
	v_add_u32_e32 v152, s95, v213
	s_addc_u32 s3, s1, 0
	v_lshlrev_b32_e32 v92, 7, v78
	v_lshl_add_u64 v[0:1], s[2:3], 0, v[92:93]
	v_mov_b32_e32 v151, v93
	v_ashrrev_i32_e32 v153, 31, v152
	v_lshl_add_u64 v[0:1], v[0:1], 0, v[150:151]
	v_lshlrev_b64 v[2:3], 11, v[152:153]
	v_lshl_add_u64 v[2:3], v[0:1], 0, v[2:3]
	global_load_dwordx4 v[96:99], v[2:3], off
	v_or_b32_e32 v154, 2, v152
	v_ashrrev_i32_e32 v155, 31, v154
	v_lshlrev_b64 v[4:5], 11, v[154:155]
	v_lshl_add_u64 v[0:1], v[0:1], 0, v[4:5]
	global_load_dwordx4 v[100:103], v[2:3], off offset:64
	global_load_dwordx4 v[104:107], v[0:1], off
	global_load_dwordx4 v[108:111], v[0:1], off offset:64
	v_mov_b32_e32 v11, v196
	s_add_i32 s1, 0, 0x12000
	s_waitcnt lgkmcnt(0)
	s_barrier
	v_cmp_lt_i32_e32 vcc, v205, v198
	v_bfe_u32 v79, v11, 4, 2
	v_and_b32_e32 v42, 15, v11
	v_lshl_add_u32 v77, v79, 4, s1
	v_mad_u32_u24 v8, v42, s88, v77
	ds_read_b128 v[0:3], v8
	ds_read_b128 v[4:7], v8 offset:64
	ds_read_b128 v[12:15], v8 offset:2304
	ds_read_b128 v[16:19], v8 offset:2368
	ds_read_b128 v[20:23], v8 offset:4608
	ds_read_b128 v[24:27], v8 offset:4672
	ds_read_b128 v[28:31], v8 offset:6912
	ds_read_b128 v[32:35], v8 offset:6976
	ds_read_b128 v[36:39], v8 offset:9216
	ds_read_b128 v[44:47], v8 offset:9280
	ds_read_b128 v[48:51], v8 offset:11520
	ds_read_b128 v[52:55], v8 offset:11584
	v_cmp_ne_u32_e64 s[78:79], 3, v79
	v_cmp_eq_u32_e64 s[74:75], 0, v79
	v_readlane_b32 s1, v250, 20
	s_waitcnt vmcnt(3) lgkmcnt(1)
	v_mfma_f32_16x16x32_bf16 v[56:59], v[48:51], v[96:99], 0
	ds_read_b128 v[48:51], v8 offset:13824
	ds_read_b128 v[60:63], v8 offset:13888
	v_mfma_f32_16x16x32_bf16 v[0:3], v[0:3], v[96:99], 0
	s_waitcnt lgkmcnt(1)
	v_mfma_f32_16x16x32_bf16 v[64:67], v[48:51], v[96:99], 0
	ds_read_b128 v[48:51], v8 offset:16128
	ds_read_b128 v[68:71], v8 offset:16192
	v_cndmask_b32_e32 v8, v197, v205, vcc
	v_lshlrev_b32_e32 v151, 2, v8
	v_mfma_f32_16x16x32_bf16 v[12:15], v[12:15], v[96:99], 0
	v_lshlrev_b32_e32 v8, 6, v79
	v_add_u32_e32 v41, 0x4f, v8
	v_or_b32_e32 v40, 0x11f, v8
	v_mfma_f32_16x16x32_bf16 v[20:23], v[20:23], v[96:99], 0
	v_add_u32_e32 v76, 0x74f, v8
	v_mfma_f32_16x16x32_bf16 v[36:39], v[36:39], v[96:99], 0
	s_waitcnt vmcnt(2)
	v_mfma_f32_16x16x32_bf16 v[0:3], v[4:7], v[100:103], v[0:3]
	s_waitcnt lgkmcnt(1)
	v_mfma_f32_16x16x32_bf16 v[72:75], v[48:51], v[96:99], 0
	v_or_b32_e32 v50, 31, v8
	v_cmp_le_i32_e32 vcc, v50, v152
	v_or_b32_e32 v49, 0x12f, v8
	v_mfma_f32_16x16x32_bf16 v[4:7], v[16:19], v[100:103], v[12:15]
	s_nop 1
	v_cndmask_b32_e32 v0, v158, v0, vcc
	v_or_b32_e32 v51, 0x13f, v8
	v_mfma_f32_16x16x32_bf16 v[12:15], v[24:27], v[100:103], v[20:23]
	v_mfma_f32_16x16x32_bf16 v[20:23], v[44:47], v[100:103], v[36:39]
	s_nop 2
	v_or_b32_e32 v39, 47, v8
	v_or_b32_e32 v38, 63, v8
	v_cmp_le_i32_e32 vcc, v39, v152
	v_mfma_f32_16x16x32_bf16 v[28:31], v[28:31], v[96:99], 0
	s_nop 0
	v_cndmask_b32_e32 v1, v158, v1, vcc
	v_cmp_le_i32_e32 vcc, v38, v152
	v_mfma_f32_16x16x32_bf16 v[24:27], v[52:55], v[100:103], v[56:59]
	v_add_u32_e32 v52, 0x14f, v8
	v_cndmask_b32_e32 v2, v158, v2, vcc
	v_cmp_le_i32_e32 vcc, v41, v152
	v_or_b32_e32 v53, 0x21f, v8
	v_or_b32_e32 v54, 0x22f, v8
	v_cndmask_b32_e32 v3, v158, v3, vcc
	v_cmp_le_i32_e32 vcc, v40, v152
	v_mfma_f32_16x16x32_bf16 v[16:19], v[32:35], v[100:103], v[28:31]
	v_or_b32_e32 v55, 0x23f, v8
	v_cndmask_b32_e32 v9, v158, v4, vcc
	v_cmp_le_i32_e32 vcc, v49, v152
	v_add_u32_e32 v56, 0x24f, v8
	v_or_b32_e32 v57, 0x31f, v8
	v_cndmask_b32_e32 v10, v158, v5, vcc
	v_cmp_le_i32_e32 vcc, v51, v152
	v_or_b32_e32 v58, 0x32f, v8
	v_or_b32_e32 v59, 0x33f, v8
	v_cndmask_b32_e32 v6, v158, v6, vcc
	v_cmp_le_i32_e32 vcc, v52, v152
	v_mfma_f32_16x16x32_bf16 v[28:31], v[60:63], v[100:103], v[64:67]
	v_add_u32_e32 v60, 0x34f, v8
	v_cndmask_b32_e32 v7, v158, v7, vcc
	v_cmp_le_i32_e32 vcc, v53, v152
	v_or_b32_e32 v61, 0x41f, v8
	v_or_b32_e32 v62, 0x42f, v8
	v_cndmask_b32_e32 v36, v158, v12, vcc
	v_cmp_le_i32_e32 vcc, v54, v152
	v_or_b32_e32 v63, 0x43f, v8
	v_add_u32_e32 v64, 0x44f, v8
	v_cndmask_b32_e32 v37, v158, v13, vcc
	v_cmp_le_i32_e32 vcc, v55, v152
	v_max3_f32 v4, v0, s87, v1
	v_or_b32_e32 v65, 0x51f, v8
	v_cndmask_b32_e32 v43, v158, v14, vcc
	v_cmp_le_i32_e32 vcc, v56, v152
	v_max3_f32 v4, v4, v2, v3
	v_or_b32_e32 v66, 0x52f, v8
	v_cndmask_b32_e32 v44, v158, v15, vcc
	v_cmp_le_i32_e32 vcc, v57, v152
	v_max3_f32 v4, v4, v9, v10
	v_or_b32_e32 v67, 0x53f, v8
	v_cndmask_b32_e32 v16, v158, v16, vcc
	v_cmp_le_i32_e32 vcc, v58, v152
	s_waitcnt lgkmcnt(0)
	v_mfma_f32_16x16x32_bf16 v[32:35], v[68:71], v[100:103], v[72:75]
	v_max3_f32 v4, v4, v6, v7
	v_cndmask_b32_e32 v17, v158, v17, vcc
	v_cmp_le_i32_e32 vcc, v59, v152
	v_add_u32_e32 v68, 0x54f, v8
	v_max3_f32 v4, v4, v36, v37
	v_cndmask_b32_e32 v18, v158, v18, vcc
	v_cmp_le_i32_e32 vcc, v60, v152
	v_or_b32_e32 v69, 0x61f, v8
	v_max3_f32 v4, v4, v43, v44
	v_cndmask_b32_e32 v19, v158, v19, vcc
	v_cmp_le_i32_e32 vcc, v61, v152
	v_or_b32_e32 v70, 0x62f, v8
	v_max3_f32 v4, v4, v16, v17
	v_cndmask_b32_e32 v45, v158, v20, vcc
	v_cmp_le_i32_e32 vcc, v62, v152
	v_or_b32_e32 v71, 0x63f, v8
	v_max3_f32 v4, v4, v18, v19
	v_cndmask_b32_e32 v46, v158, v21, vcc
	v_cmp_le_i32_e32 vcc, v63, v152
	v_add_u32_e32 v72, 0x64f, v8
	v_max3_f32 v4, v4, v45, v46
	v_cndmask_b32_e32 v47, v158, v22, vcc
	v_cmp_le_i32_e32 vcc, v64, v152
	v_or_b32_e32 v73, 0x71f, v8
	v_or_b32_e32 v74, 0x72f, v8
	v_cndmask_b32_e32 v48, v158, v23, vcc
	v_cmp_le_i32_e32 vcc, v65, v152
	v_max3_f32 v4, v4, v47, v48
	v_or_b32_e32 v75, 0x73f, v8
	v_cndmask_b32_e32 v24, v158, v24, vcc
	v_cmp_le_i32_e32 vcc, v66, v152
	s_nop 1
	v_cndmask_b32_e32 v25, v158, v25, vcc
	v_cmp_le_i32_e32 vcc, v67, v152
	v_max3_f32 v4, v4, v24, v25
	s_nop 0
	v_cndmask_b32_e32 v80, v158, v26, vcc
	v_cmp_le_i32_e32 vcc, v68, v152
	s_nop 1
	v_cndmask_b32_e32 v81, v158, v27, vcc
	v_cmp_le_i32_e32 vcc, v69, v152
	v_max3_f32 v4, v4, v80, v81
	s_nop 0
	v_cndmask_b32_e32 v82, v158, v28, vcc
	v_cmp_le_i32_e32 vcc, v70, v152
	s_nop 1
	v_cndmask_b32_e32 v83, v158, v29, vcc
	v_cmp_le_i32_e32 vcc, v71, v152
	v_max3_f32 v4, v4, v82, v83
	s_nop 0
	v_cndmask_b32_e32 v84, v158, v30, vcc
	v_cmp_le_i32_e32 vcc, v72, v152
	s_nop 1
	v_cndmask_b32_e32 v85, v158, v31, vcc
	v_cmp_le_i32_e32 vcc, v73, v152
	v_max3_f32 v4, v4, v84, v85
	s_nop 0
	v_cndmask_b32_e32 v86, v158, v32, vcc
	v_cmp_le_i32_e32 vcc, v74, v152
	s_nop 1
	v_cndmask_b32_e32 v87, v158, v33, vcc
	v_cmp_le_i32_e32 vcc, v75, v152
	v_max3_f32 v4, v4, v86, v87
	s_nop 0
	v_cndmask_b32_e32 v34, v158, v34, vcc
	v_cmp_le_i32_e32 vcc, v76, v152
	s_and_b64 vcc, s[78:79], vcc
	s_nop 0
	v_cndmask_b32_e32 v35, v158, v35, vcc
	v_max3_f32 v4, v4, v34, v35
	ds_bpermute_b32 v5, v151, v4
	v_cmp_lt_i32_e32 vcc, v204, v198
	s_waitcnt lgkmcnt(0)
	v_max_f32_e32 v5, v5, v5
	v_cndmask_b32_e32 v8, v197, v204, vcc
	v_lshlrev_b32_e32 v217, 2, v8
	v_max_f32_e32 v4, v4, v5
	ds_bpermute_b32 v5, v217, v4
	v_cmp_lt_f32_e32 vcc, s86, v0
	s_waitcnt lgkmcnt(0)
	v_max_f32_e32 v5, v5, v5
	v_max_f32_e32 v88, v4, v5
	v_sub_f32_e32 v4, v0, v88
	v_exp_f32_e32 v4, v4
	v_sub_f32_e32 v5, v1, v88
	v_exp_f32_e32 v5, v5
	v_sub_f32_e32 v8, v3, v88
	v_cndmask_b32_e32 v4, 0, v4, vcc
	v_cmp_lt_f32_e32 vcc, s86, v1
	v_add_f32_e32 v0, 0, v4
	v_exp_f32_e32 v8, v8
	v_cndmask_b32_e32 v5, 0, v5, vcc
	v_add_f32_e32 v1, v5, v0
	v_sub_f32_e32 v0, v2, v88
	v_exp_f32_e32 v0, v0
	v_cmp_lt_f32_e32 vcc, s86, v2
	s_nop 1
	v_cndmask_b32_e32 v0, 0, v0, vcc
	v_cmp_lt_f32_e32 vcc, s86, v3
	v_sub_f32_e32 v3, v9, v88
	v_exp_f32_e32 v3, v3
	v_add_f32_e32 v2, v0, v1
	v_cndmask_b32_e32 v1, 0, v8, vcc
	v_sub_f32_e32 v8, v10, v88
	v_cmp_lt_f32_e32 vcc, s86, v9
	v_exp_f32_e32 v8, v8
	v_add_f32_e32 v2, v1, v2
	v_cndmask_b32_e32 v14, 0, v3, vcc
	v_sub_f32_e32 v3, v6, v88
	v_exp_f32_e32 v3, v3
	v_cmp_lt_f32_e32 vcc, s86, v10
	v_add_f32_e32 v2, v14, v2
	v_sub_f32_e32 v10, v35, v88
	v_cndmask_b32_e32 v15, 0, v8, vcc
	v_sub_f32_e32 v8, v7, v88
	v_cmp_lt_f32_e32 vcc, s86, v6
	v_exp_f32_e32 v8, v8
	v_sub_f32_e32 v6, v37, v88
	v_cndmask_b32_e32 v12, 0, v3, vcc
	v_sub_f32_e32 v3, v36, v88
	v_exp_f32_e32 v3, v3
	v_exp_f32_e32 v6, v6
	v_cmp_lt_f32_e32 vcc, s86, v7
	v_add_f32_e32 v2, v15, v2
	v_add_f32_e32 v2, v12, v2
	v_cndmask_b32_e32 v13, 0, v8, vcc
	v_cmp_lt_f32_e32 vcc, s86, v36
	v_add_f32_e32 v2, v13, v2
	v_exp_f32_e32 v10, v10
	v_cndmask_b32_e32 v22, 0, v3, vcc
	v_cmp_lt_f32_e32 vcc, s86, v37
	v_sub_f32_e32 v3, v43, v88
	v_exp_f32_e32 v3, v3
	v_cndmask_b32_e32 v23, 0, v6, vcc
	v_sub_f32_e32 v6, v44, v88
	v_exp_f32_e32 v6, v6
	v_cmp_lt_f32_e32 vcc, s86, v43
	v_add_f32_e32 v2, v22, v2
	v_add_f32_e32 v2, v23, v2
	v_cndmask_b32_e32 v20, 0, v3, vcc
	v_cmp_lt_f32_e32 vcc, s86, v44
	v_sub_f32_e32 v3, v16, v88
	v_exp_f32_e32 v3, v3
	v_cndmask_b32_e32 v21, 0, v6, vcc
	v_sub_f32_e32 v6, v17, v88
	v_exp_f32_e32 v6, v6
	v_cmp_lt_f32_e32 vcc, s86, v16
	v_add_f32_e32 v2, v20, v2
	v_add_f32_e32 v2, v21, v2
	v_cndmask_b32_e32 v30, 0, v3, vcc
	v_cmp_lt_f32_e32 vcc, s86, v17
	v_sub_f32_e32 v3, v18, v88
	v_exp_f32_e32 v3, v3
	v_cndmask_b32_e32 v31, 0, v6, vcc
	v_sub_f32_e32 v6, v19, v88
	v_exp_f32_e32 v6, v6
	v_cmp_lt_f32_e32 vcc, s86, v18
	v_add_f32_e32 v2, v30, v2
	v_add_f32_e32 v2, v31, v2
	v_cndmask_b32_e32 v26, 0, v3, vcc
	v_cmp_lt_f32_e32 vcc, s86, v19
	v_sub_f32_e32 v3, v45, v88
	v_exp_f32_e32 v3, v3
	v_cndmask_b32_e32 v27, 0, v6, vcc
	v_sub_f32_e32 v6, v46, v88
	v_exp_f32_e32 v6, v6
	v_cmp_lt_f32_e32 vcc, s86, v45
	v_add_f32_e32 v2, v26, v2
	v_add_f32_e32 v2, v27, v2
	v_cndmask_b32_e32 v28, 0, v3, vcc
	v_cmp_lt_f32_e32 vcc, s86, v46
	v_sub_f32_e32 v3, v47, v88
	v_exp_f32_e32 v3, v3
	v_cndmask_b32_e32 v29, 0, v6, vcc
	v_sub_f32_e32 v6, v48, v88
	v_exp_f32_e32 v6, v6
	v_cmp_lt_f32_e32 vcc, s86, v47
	v_add_f32_e32 v2, v28, v2
	v_add_f32_e32 v2, v29, v2
	v_cndmask_b32_e32 v32, 0, v3, vcc
	v_cmp_lt_f32_e32 vcc, s86, v48
	v_sub_f32_e32 v3, v24, v88
	v_exp_f32_e32 v3, v3
	v_cndmask_b32_e32 v33, 0, v6, vcc
	v_sub_f32_e32 v6, v25, v88
	v_exp_f32_e32 v6, v6
	v_cmp_lt_f32_e32 vcc, s86, v24
	v_add_f32_e32 v2, v32, v2
	v_add_f32_e32 v2, v33, v2
	v_cndmask_b32_e32 v18, 0, v3, vcc
	v_cmp_lt_f32_e32 vcc, s86, v25
	v_sub_f32_e32 v3, v80, v88
	v_exp_f32_e32 v3, v3
	v_cndmask_b32_e32 v19, 0, v6, vcc
	v_sub_f32_e32 v6, v81, v88
	v_exp_f32_e32 v6, v6
	v_cmp_lt_f32_e32 vcc, s86, v80
	v_add_f32_e32 v2, v18, v2
	v_add_f32_e32 v2, v19, v2
	v_cndmask_b32_e32 v24, 0, v3, vcc
	v_cmp_lt_f32_e32 vcc, s86, v81
	v_sub_f32_e32 v3, v82, v88
	v_exp_f32_e32 v3, v3
	v_cndmask_b32_e32 v25, 0, v6, vcc
	v_sub_f32_e32 v6, v83, v88
	v_exp_f32_e32 v6, v6
	v_cmp_lt_f32_e32 vcc, s86, v82
	v_add_f32_e32 v2, v24, v2
	v_add_f32_e32 v2, v25, v2
	v_cndmask_b32_e32 v8, 0, v3, vcc
	v_cmp_lt_f32_e32 vcc, s86, v83
	v_sub_f32_e32 v3, v84, v88
	v_exp_f32_e32 v3, v3
	v_cndmask_b32_e32 v9, 0, v6, vcc
	v_sub_f32_e32 v6, v85, v88
	v_exp_f32_e32 v6, v6
	v_add_f32_e32 v2, v8, v2
	v_cmp_lt_f32_e32 vcc, s86, v84
	v_add_f32_e32 v2, v9, v2
	v_add_u32_e32 v36, 48, v11
	v_cndmask_b32_e32 v16, 0, v3, vcc
	v_cmp_lt_f32_e32 vcc, s86, v85
	v_add_f32_e32 v2, v16, v2
	v_and_or_b32 v36, v36, 63, v210
	v_cndmask_b32_e32 v17, 0, v6, vcc
	v_add_f32_e32 v3, v17, v2
	v_sub_f32_e32 v2, v86, v88
	v_exp_f32_e32 v2, v2
	v_sub_f32_e32 v6, v87, v88
	v_exp_f32_e32 v6, v6
	v_cmp_lt_f32_e32 vcc, s86, v86
	v_lshlrev_b32_e32 v43, 2, v36
	s_nop 0
	v_cndmask_b32_e32 v2, 0, v2, vcc
	v_cmp_lt_f32_e32 vcc, s86, v87
	v_add_f32_e32 v7, v2, v3
	s_nop 0
	v_cndmask_b32_e32 v3, 0, v6, vcc
	v_sub_f32_e32 v6, v34, v88
	v_exp_f32_e32 v6, v6
	v_cmp_lt_f32_e32 vcc, s86, v34
	v_add_f32_e32 v7, v3, v7
	s_nop 0
	v_cndmask_b32_e32 v6, 0, v6, vcc
	v_cmp_lt_f32_e32 vcc, s86, v35
	v_add_f32_e32 v34, v6, v7
	v_bfe_u32 v35, v11, 3, 1
	v_cndmask_b32_e32 v7, 0, v10, vcc
	v_add_f32_e32 v10, v7, v34
	v_mov_b32_e32 v34, v10
	s_nop 1
	v_permlane16_swap_b32_e32 v34, v10
	v_cmp_lt_i32_e32 vcc, v199, v198
	v_or_b32_e32 v35, s1, v35
	s_movk_i32 s1, 0x84
	v_cndmask_b32_e32 v37, v197, v199, vcc
	s_waitcnt lgkmcnt(0)
	v_add_f32_e32 v10, v10, v34
	v_mov_b32_e32 v34, v10
	s_nop 1
	v_permlane32_swap_b32_e32 v34, v10
	v_lshlrev_b32_e32 v44, 2, v37
	v_mul_lo_u32 v35, v35, s1
	s_waitcnt lgkmcnt(0)
	v_add_f32_e32 v10, v10, v34
	v_max_f32_e32 v10, 0x1e3ce508, v10
	v_div_scale_f32 v34, s[2:3], v10, v10, 1.0
	v_rcp_f32_e32 v36, v34
	s_nop 0
	v_fma_f32 v37, -v34, v36, 1.0
	v_fmac_f32_e32 v36, v37, v36
	v_div_scale_f32 v37, vcc, 1.0, v10, 1.0
	v_mul_f32_e32 v45, v37, v36
	v_fma_f32 v46, -v34, v45, v37
	v_fmac_f32_e32 v45, v46, v36
	v_fma_f32 v34, -v34, v45, v37
	v_div_fmas_f32 v34, v34, v36, v45
	v_div_fixup_f32 v10, v34, v10, 1.0
	v_pk_mul_f32 v[0:1], v[0:1], v[10:11] op_sel_hi:[1,0]
	v_pk_mul_f32 v[4:5], v[4:5], v[10:11] op_sel_hi:[1,0]
	v_mul_f32_e32 v36, 0.5, v1
	ds_bpermute_b32 v34, v43, v36
	v_add_f32_e32 v37, v4, v5
	v_fma_f32 v45, 0.5, v1, v0
	v_add_f32_e32 v37, v37, v45
	v_cmp_lt_i32_e32 vcc, v201, v198
	s_waitcnt lgkmcnt(0)
	v_cndmask_b32_e64 v34, v34, 0, s[74:75]
	v_add_f32_e32 v34, v37, v34
	s_nop 1
	v_mov_b32_dpp v37, v34 quad_perm:[1,0,3,2] row_mask:0xf bank_mask:0xf
	v_cndmask_b32_e32 v45, v197, v201, vcc
	v_lshlrev_b32_e32 v45, 2, v45
	v_cmp_lt_i32_e32 vcc, v202, v198
	v_and_b32_e32 v11, 7, v11
	s_waitcnt lgkmcnt(0)
	v_add_f32_e32 v34, v34, v37
	s_nop 1
	v_mov_b32_dpp v37, v34 quad_perm:[2,3,0,1] row_mask:0xf bank_mask:0xf
	v_cndmask_b32_e32 v46, v197, v202, vcc
	v_lshlrev_b32_e32 v46, 2, v46
	v_cmp_eq_u32_e64 s[76:77], 0, v11
	s_waitcnt lgkmcnt(0)
	v_add_f32_e32 v11, v34, v37
	s_nop 1
	v_mov_b32_dpp v34, v11 row_half_mirror row_mask:0xf bank_mask:0xf
	v_lshl_add_u32 v37, v79, 2, s33
	v_add_u32_e32 v47, v37, v35
	s_and_saveexec_b64 s[2:3], s[76:77]
	s_cbranch_execz .LBB0_1110
	s_waitcnt lgkmcnt(0)
	v_add_f32_e32 v11, v11, v34
	ds_write_b32 v47, v11
.LBB0_1110:
	s_or_b64 exec, exec, s[2:3]
	v_mov_b32_e32 v11, v10
	s_waitcnt lgkmcnt(0)
	v_mov_b32_e32 v34, v10
	v_mov_b32_e32 v35, v10
	v_pk_mul_f32 v[12:13], v[12:13], v[34:35]
	v_pk_mul_f32 v[14:15], v[14:15], v[10:11]
	v_mul_f32_e32 v37, 0.5, v13
	v_add_f32_e32 v48, v14, v15
	v_fma_f32 v80, 0.5, v13, v12
	v_add_f32_e32 v48, v48, v80
	ds_bpermute_b32 v80, v43, v37
	ds_bpermute_b32 v36, v43, v36
	s_waitcnt lgkmcnt(0)
	v_cndmask_b32_e64 v36, v80, v36, s[74:75]
	v_add_f32_e32 v36, v48, v36
	s_nop 1
	v_mov_b32_dpp v48, v36 quad_perm:[1,0,3,2] row_mask:0xf bank_mask:0xf
	s_waitcnt lgkmcnt(0)
	v_add_f32_e32 v36, v36, v48
	s_nop 1
	v_mov_b32_dpp v48, v36 quad_perm:[2,3,0,1] row_mask:0xf bank_mask:0xf
	s_waitcnt lgkmcnt(0)
	v_add_f32_e32 v36, v36, v48
	s_nop 1
	v_mov_b32_dpp v48, v36 row_half_mirror row_mask:0xf bank_mask:0xf
	s_and_saveexec_b64 s[2:3], s[76:77]
	s_cbranch_execz .LBB0_1112
	s_waitcnt lgkmcnt(0)
	v_add_f32_e32 v36, v36, v48
	ds_write_b32 v47, v36 offset:16
.LBB0_1112:
	s_or_b64 exec, exec, s[2:3]
	v_pk_mul_f32 v[20:21], v[20:21], v[34:35]
	v_pk_mul_f32 v[22:23], v[22:23], v[10:11]
	v_mul_f32_e32 v36, 0.5, v21
	v_add_f32_e32 v34, v22, v23
	v_fma_f32 v35, 0.5, v21, v20
	v_add_f32_e32 v34, v34, v35
	ds_bpermute_b32 v35, v43, v36
	ds_bpermute_b32 v37, v43, v37
	s_waitcnt lgkmcnt(0)
	v_cndmask_b32_e64 v35, v35, v37, s[74:75]
	v_add_f32_e32 v34, v34, v35
	s_nop 1
	v_mov_b32_dpp v35, v34 quad_perm:[1,0,3,2] row_mask:0xf bank_mask:0xf
	s_waitcnt lgkmcnt(0)
	v_add_f32_e32 v34, v34, v35
	s_nop 1
	v_mov_b32_dpp v35, v34 quad_perm:[2,3,0,1] row_mask:0xf bank_mask:0xf
	s_waitcnt lgkmcnt(0)
	v_add_f32_e32 v34, v34, v35
	s_nop 1
	v_mov_b32_dpp v35, v34 row_half_mirror row_mask:0xf bank_mask:0xf
	s_and_saveexec_b64 s[2:3], s[76:77]
	s_cbranch_execz .LBB0_1114
	s_waitcnt lgkmcnt(0)
	v_add_f32_e32 v34, v34, v35
	ds_write_b32 v47, v34 offset:32
.LBB0_1114:
	s_or_b64 exec, exec, s[2:3]
	v_mov_b32_e32 v34, v10
	s_waitcnt lgkmcnt(0)
	v_mov_b32_e32 v35, v10
	v_pk_mul_f32 v[26:27], v[26:27], v[34:35]
	v_pk_mul_f32 v[30:31], v[30:31], v[10:11]
	v_mul_f32_e32 v37, 0.5, v27
	v_add_f32_e32 v48, v30, v31
	v_fma_f32 v80, 0.5, v27, v26
	v_add_f32_e32 v48, v48, v80
	ds_bpermute_b32 v80, v43, v37
	ds_bpermute_b32 v36, v43, v36
	s_waitcnt lgkmcnt(0)
	v_cndmask_b32_e64 v36, v80, v36, s[74:75]
	v_add_f32_e32 v36, v48, v36
	s_nop 1
	v_mov_b32_dpp v48, v36 quad_perm:[1,0,3,2] row_mask:0xf bank_mask:0xf
	s_waitcnt lgkmcnt(0)
	v_add_f32_e32 v36, v36, v48
	s_nop 1
	v_mov_b32_dpp v48, v36 quad_perm:[2,3,0,1] row_mask:0xf bank_mask:0xf
	s_waitcnt lgkmcnt(0)
	v_add_f32_e32 v36, v36, v48
	s_nop 1
	v_mov_b32_dpp v48, v36 row_half_mirror row_mask:0xf bank_mask:0xf
	s_and_saveexec_b64 s[2:3], s[76:77]
	s_cbranch_execz .LBB0_1116
	s_waitcnt lgkmcnt(0)
	v_add_f32_e32 v36, v36, v48
	ds_write_b32 v47, v36 offset:48
.LBB0_1116:
	s_or_b64 exec, exec, s[2:3]
	v_pk_mul_f32 v[32:33], v[32:33], v[34:35]
	v_pk_mul_f32 v[28:29], v[28:29], v[10:11]
	s_waitcnt lgkmcnt(0)
	v_mul_f32_e32 v48, 0.5, v33
	v_add_f32_e32 v34, v28, v29
	v_fma_f32 v35, 0.5, v33, v32
	v_add_f32_e32 v34, v34, v35
	ds_bpermute_b32 v35, v43, v48
	ds_bpermute_b32 v36, v43, v37
	s_waitcnt lgkmcnt(0)
	v_cndmask_b32_e64 v35, v35, v36, s[74:75]
	v_add_f32_e32 v34, v34, v35
	s_nop 1
	v_mov_b32_dpp v35, v34 quad_perm:[1,0,3,2] row_mask:0xf bank_mask:0xf
	s_waitcnt lgkmcnt(0)
	v_add_f32_e32 v34, v34, v35
	s_nop 1
	v_mov_b32_dpp v35, v34 quad_perm:[2,3,0,1] row_mask:0xf bank_mask:0xf
	s_waitcnt lgkmcnt(0)
	v_add_f32_e32 v34, v34, v35
	s_nop 1
	v_mov_b32_dpp v35, v34 row_half_mirror row_mask:0xf bank_mask:0xf
	s_and_saveexec_b64 s[2:3], s[76:77]
	s_cbranch_execz .LBB0_1118
	s_waitcnt lgkmcnt(0)
	v_add_f32_e32 v34, v34, v35
	ds_write_b32 v47, v34 offset:64
.LBB0_1118:
	s_or_b64 exec, exec, s[2:3]
	v_mov_b32_e32 v36, v10
	v_mov_b32_e32 v37, v10
	v_pk_mul_f32 v[24:25], v[24:25], v[36:37]
	s_waitcnt lgkmcnt(0)
	v_pk_mul_f32 v[34:35], v[18:19], v[10:11]
	v_mul_f32_e32 v18, 0.5, v25
	v_add_f32_e32 v19, v34, v35
	v_fma_f32 v80, 0.5, v25, v24
	v_add_f32_e32 v19, v19, v80
	ds_bpermute_b32 v80, v43, v18
	ds_bpermute_b32 v48, v43, v48
	s_waitcnt lgkmcnt(0)
	v_cndmask_b32_e64 v48, v80, v48, s[74:75]
	v_add_f32_e32 v19, v19, v48
	s_nop 1
	v_mov_b32_dpp v48, v19 quad_perm:[1,0,3,2] row_mask:0xf bank_mask:0xf
	s_waitcnt lgkmcnt(0)
	v_add_f32_e32 v19, v19, v48
	s_nop 1
	v_mov_b32_dpp v48, v19 quad_perm:[2,3,0,1] row_mask:0xf bank_mask:0xf
	s_waitcnt lgkmcnt(0)
	v_add_f32_e32 v19, v19, v48
	s_nop 1
	v_mov_b32_dpp v48, v19 row_half_mirror row_mask:0xf bank_mask:0xf
	s_and_saveexec_b64 s[2:3], s[76:77]
	s_cbranch_execz .LBB0_1120
	s_waitcnt lgkmcnt(0)
	v_add_f32_e32 v19, v19, v48
	ds_write_b32 v47, v19 offset:80
.LBB0_1120:
	s_or_b64 exec, exec, s[2:3]
	v_pk_mul_f32 v[36:37], v[16:17], v[36:37]
	v_pk_mul_f32 v[8:9], v[8:9], v[10:11]
	v_mul_f32_e32 v16, 0.5, v37
	v_add_f32_e32 v17, v8, v9
	v_fma_f32 v19, 0.5, v37, v36
	v_add_f32_e32 v17, v17, v19
	ds_bpermute_b32 v19, v43, v16
	ds_bpermute_b32 v18, v43, v18
	s_waitcnt lgkmcnt(0)
	v_cndmask_b32_e64 v18, v19, v18, s[74:75]
	v_add_f32_e32 v17, v17, v18
	s_nop 1
	v_mov_b32_dpp v18, v17 quad_perm:[1,0,3,2] row_mask:0xf bank_mask:0xf
	s_waitcnt lgkmcnt(0)
	v_add_f32_e32 v17, v17, v18
	s_nop 1
	v_mov_b32_dpp v18, v17 quad_perm:[2,3,0,1] row_mask:0xf bank_mask:0xf
	s_waitcnt lgkmcnt(0)
	v_add_f32_e32 v17, v17, v18
	s_nop 1
	v_mov_b32_dpp v18, v17 row_half_mirror row_mask:0xf bank_mask:0xf
	s_and_saveexec_b64 s[2:3], s[76:77]
	s_cbranch_execz .LBB0_1122
	s_waitcnt lgkmcnt(0)
	v_add_f32_e32 v17, v17, v18
	ds_write_b32 v47, v17 offset:96
.LBB0_1122:
	s_or_b64 exec, exec, s[2:3]
	s_waitcnt lgkmcnt(0)
	v_mov_b32_e32 v18, v10
	v_mov_b32_e32 v19, v10
	v_pk_mul_f32 v[6:7], v[6:7], v[18:19]
	ds_bpermute_b32 v16, v43, v16
	v_mul_f32_e32 v17, 0.5, v7
	ds_bpermute_b32 v17, v43, v17
	v_pk_mul_f32 v[2:3], v[2:3], v[10:11]
	v_fma_f32 v11, 0.5, v7, v6
	v_add_f32_e32 v10, v2, v3
	v_add_f32_e32 v10, v10, v11
	s_waitcnt lgkmcnt(0)
	v_cndmask_b32_e64 v11, v17, v16, s[74:75]
	v_add_f32_e32 v10, v10, v11
	s_nop 1
	v_mov_b32_dpp v11, v10 quad_perm:[1,0,3,2] row_mask:0xf bank_mask:0xf
	s_waitcnt lgkmcnt(0)
	v_add_f32_e32 v10, v10, v11
	s_nop 1
	v_mov_b32_dpp v11, v10 quad_perm:[2,3,0,1] row_mask:0xf bank_mask:0xf
	s_waitcnt lgkmcnt(0)
	v_add_f32_e32 v10, v10, v11
	s_nop 1
	v_mov_b32_dpp v11, v10 row_half_mirror row_mask:0xf bank_mask:0xf
	s_and_saveexec_b64 s[2:3], s[76:77]
	s_cbranch_execz .LBB0_1124
	s_waitcnt lgkmcnt(0)
	v_add_f32_e32 v10, v10, v11
	ds_write_b32 v47, v10 offset:112
.LBB0_1124:
	s_or_b64 exec, exec, s[2:3]
	s_lshl_b32 s96, s0, 11
	v_mul_u32_u24_e32 v10, 3, v78
	v_readlane_b32 s0, v250, 23
	v_lshlrev_b32_e32 v162, 2, v10
	v_mov_b32_e32 v163, v93
	v_readlane_b32 s1, v250, 24
	v_lshlrev_b32_e32 v218, 6, v78
	v_lshl_add_u32 v48, v79, 3, s83
	v_lshl_add_u64 v[18:19], s[0:1], 0, v[162:163]
	v_readlane_b32 s0, v250, 25
	v_lshlrev_b32_e32 v94, 2, v218
	v_mov_b32_e32 v95, v93
	v_readlane_b32 s1, v250, 26
	v_cvt_pk_bf16_f32 v82, v4, v5
	v_mad_u32_u24 v4, v42, s12, v48
	s_waitcnt lgkmcnt(0)
	v_lshl_add_u64 v[10:11], s[0:1], 0, v[94:95]
	v_lshlrev_b32_e32 v92, 4, v79
	v_add_u32_e32 v78, 0x1000, v4
	v_add_u32_e32 v79, 0x2000, v4
	v_add_u32_e32 v81, 0x3000, v4
	v_lshl_add_u64 v[16:17], v[10:11], 0, v[92:93]
	v_cvt_pk_bf16_f32 v85, v12, v13
	ds_read2_b64 v[10:13], v4 offset1:4
	ds_read2_b64 v[86:89], v78 offset0:32 offset1:36
	ds_read2_b64 v[112:115], v79 offset0:64 offset1:68
	ds_read2_b64 v[116:119], v81 offset0:96 offset1:100
	v_cvt_pk_bf16_f32 v83, v0, v1
	v_cvt_pk_bf16_f32 v84, v14, v15
	v_cvt_pk_bf16_f32 v2, v2, v3
	v_cvt_pk_bf16_f32 v3, v6, v7
	s_waitcnt lgkmcnt(3)
	v_mfma_f32_16x16x32_bf16 v[10:13], v[10:13], v[82:85], 0
	v_cvt_pk_bf16_f32 v0, v8, v9
	v_cvt_pk_bf16_f32 v1, v36, v37
	v_lshl_add_u64 v[156:157], v[152:153], 0, s[96:97]
	s_waitcnt lgkmcnt(2)
	v_mfma_f32_16x16x32_bf16 v[86:89], v[86:89], v[82:85], 0
	s_movk_i32 s2, 0xc0
	v_lshlrev_b64 v[164:165], 12, v[156:157]
	v_mul_u32_u24_e32 v80, 0x90, v42
	s_waitcnt lgkmcnt(1)
	v_mfma_f32_16x16x32_bf16 v[112:115], v[112:115], v[82:85], 0
	v_add_u32_e32 v36, v77, v80
	v_cmp_le_i32_e32 vcc, v50, v154
	s_waitcnt lgkmcnt(0)
	v_mfma_f32_16x16x32_bf16 v[82:85], v[116:119], v[82:85], 0
	v_cvt_pk_bf16_f32 v116, v22, v23
	v_cvt_pk_bf16_f32 v117, v20, v21
	ds_read2_b64 v[20:23], v4 offset0:8 offset1:12
	v_cvt_pk_bf16_f32 v118, v30, v31
	v_cvt_pk_bf16_f32 v119, v26, v27
	v_cvt_pk_bf16_f32 v27, v32, v33
	ds_read2_b64 v[30:33], v4 offset0:16 offset1:20
	s_waitcnt lgkmcnt(1)
	v_mfma_f32_16x16x32_bf16 v[10:13], v[20:23], v[116:119], v[10:13]
	ds_read2_b64 v[20:23], v78 offset0:40 offset1:44
	v_cvt_pk_bf16_f32 v26, v28, v29
	v_cvt_pk_bf16_f32 v28, v34, v35
	v_cvt_pk_bf16_f32 v29, v24, v25
	ds_read2_b64 v[4:7], v4 offset0:24 offset1:28
	s_waitcnt lgkmcnt(1)
	v_mfma_f32_16x16x32_bf16 v[20:23], v[20:23], v[116:119], v[86:89]
	s_nop 2
	ds_read2_b64 v[86:89], v79 offset0:72 offset1:76
	v_mfma_f32_16x16x32_bf16 v[10:13], v[30:33], v[26:29], v[10:13]
	ds_read2_b64 v[30:33], v78 offset0:48 offset1:52
	s_waitcnt lgkmcnt(0)
	v_mfma_f32_16x16x32_bf16 v[20:23], v[30:33], v[26:29], v[20:23]
	ds_read2_b64 v[30:33], v79 offset0:80 offset1:84
	v_mfma_f32_16x16x32_bf16 v[12:15], v[4:7], v[0:3], v[10:13]
	ds_read2_b64 v[4:7], v78 offset0:56 offset1:60
	v_mfma_f32_16x16x32_bf16 v[86:89], v[86:89], v[116:119], v[112:115]
	s_nop 2
	ds_read2_b64 v[112:115], v81 offset0:104 offset1:108
	s_waitcnt lgkmcnt(2)
	v_mfma_f32_16x16x32_bf16 v[30:33], v[30:33], v[26:29], v[86:89]
	s_nop 2
	ds_read2_b64 v[86:89], v81 offset0:112 offset1:116
	s_waitcnt lgkmcnt(2)
	v_mfma_f32_16x16x32_bf16 v[8:11], v[4:7], v[0:3], v[20:23]
	ds_read2_b64 v[4:7], v79 offset0:88 offset1:92
	s_nop 1
	ds_read2_b64 v[20:23], v81 offset0:120 offset1:124
	s_waitcnt lgkmcnt(3)
	v_mfma_f32_16x16x32_bf16 v[82:85], v[112:115], v[116:119], v[82:85]
	s_waitcnt lgkmcnt(2)
	v_mfma_f32_16x16x32_bf16 v[24:27], v[86:89], v[26:29], v[82:85]
	s_waitcnt lgkmcnt(1)
	v_mfma_f32_16x16x32_bf16 v[4:7], v[4:7], v[0:3], v[30:33]
	s_waitcnt lgkmcnt(0)
	v_mfma_f32_16x16x32_bf16 v[0:3], v[20:23], v[0:3], v[24:27]
	v_mad_u64_u32 v[20:21], s[0:1], v156, s2, v[18:19]
	v_mad_i32_i24 v21, v157, s2, v21
	global_load_dword v20, v[20:21], off
	v_lshl_add_u64 v[22:23], v[16:17], 0, v[164:165]
	s_waitcnt vmcnt(0)
	v_pk_mul_f32 v[14:15], v[14:15], v[20:21] op_sel_hi:[1,0]
	v_pk_mul_f32 v[12:13], v[12:13], v[20:21] op_sel_hi:[1,0]
	v_pk_mul_f32 v[10:11], v[10:11], v[20:21] op_sel_hi:[1,0]
	v_pk_mul_f32 v[8:9], v[8:9], v[20:21] op_sel_hi:[1,0]
	v_pk_mul_f32 v[6:7], v[6:7], v[20:21] op_sel_hi:[1,0]
	v_pk_mul_f32 v[4:5], v[4:5], v[20:21] op_sel_hi:[1,0]
	v_pk_mul_f32 v[2:3], v[2:3], v[20:21] op_sel_hi:[1,0]
	v_pk_mul_f32 v[0:1], v[0:1], v[20:21] op_sel_hi:[1,0]
	global_store_dwordx4 v[22:23], v[12:15], off
	global_store_dwordx4 v[22:23], v[8:11], off offset:64
	global_store_dwordx4 v[22:23], v[4:7], off offset:128
	global_store_dwordx4 v[22:23], v[0:3], off offset:192
	ds_read_b128 v[0:3], v36
	ds_read_b128 v[4:7], v36 offset:64
	s_waitcnt lgkmcnt(1)
	v_mfma_f32_16x16x32_bf16 v[0:3], v[0:3], v[104:107], 0
	ds_read_b128 v[8:11], v36 offset:2368
	ds_read_b128 v[12:15], v36 offset:4672
	ds_read_b128 v[20:23], v36 offset:6976
	s_waitcnt lgkmcnt(3)
	v_mfma_f32_16x16x32_bf16 v[0:3], v[4:7], v[108:111], v[0:3]
	ds_read_b128 v[4:7], v36 offset:2304
	ds_read_b128 v[24:27], v36 offset:9280
	ds_read_b128 v[28:31], v36 offset:11584
	s_waitcnt lgkmcnt(2)
	v_mfma_f32_16x16x32_bf16 v[4:7], v[4:7], v[104:107], 0
	ds_read_b128 v[32:35], v36 offset:13888
	ds_read_b128 v[78:81], v36 offset:16192
	s_nop 0
	v_cndmask_b32_e32 v0, v158, v0, vcc
	v_mfma_f32_16x16x32_bf16 v[4:7], v[8:11], v[108:111], v[4:7]
	ds_read_b128 v[8:11], v36 offset:4608
	v_cmp_le_i32_e32 vcc, v39, v154
	s_waitcnt lgkmcnt(0)
	v_mfma_f32_16x16x32_bf16 v[8:11], v[8:11], v[104:107], 0
	v_cndmask_b32_e32 v1, v158, v1, vcc
	v_cmp_le_i32_e32 vcc, v38, v154
	v_mfma_f32_16x16x32_bf16 v[8:11], v[12:15], v[108:111], v[8:11]
	ds_read_b128 v[12:15], v36 offset:6912
	v_cndmask_b32_e32 v2, v158, v2, vcc
	v_cmp_le_i32_e32 vcc, v41, v154
	s_waitcnt lgkmcnt(0)
	v_mfma_f32_16x16x32_bf16 v[12:15], v[12:15], v[104:107], 0
	v_cndmask_b32_e32 v3, v158, v3, vcc
	v_cmp_le_i32_e32 vcc, v40, v154
	v_mfma_f32_16x16x32_bf16 v[12:15], v[20:23], v[108:111], v[12:15]
	ds_read_b128 v[20:23], v36 offset:9216
	v_cndmask_b32_e32 v4, v158, v4, vcc
	v_cmp_le_i32_e32 vcc, v49, v154
	s_waitcnt lgkmcnt(0)
	v_mfma_f32_16x16x32_bf16 v[20:23], v[20:23], v[104:107], 0
	v_cndmask_b32_e32 v5, v158, v5, vcc
	v_cmp_le_i32_e32 vcc, v51, v154
	v_mfma_f32_16x16x32_bf16 v[20:23], v[24:27], v[108:111], v[20:23]
	ds_read_b128 v[24:27], v36 offset:11520
	s_waitcnt lgkmcnt(0)
	v_mfma_f32_16x16x32_bf16 v[24:27], v[24:27], v[104:107], 0
	v_mfma_f32_16x16x32_bf16 v[24:27], v[28:31], v[108:111], v[24:27]
	ds_read_b128 v[28:31], v36 offset:13824
	s_waitcnt lgkmcnt(0)
	v_mfma_f32_16x16x32_bf16 v[28:31], v[28:31], v[104:107], 0
	v_mfma_f32_16x16x32_bf16 v[32:35], v[32:35], v[108:111], v[28:31]
	s_nop 6
	ds_read_b128 v[28:31], v36 offset:16128
	s_waitcnt lgkmcnt(0)
	v_mfma_f32_16x16x32_bf16 v[28:31], v[28:31], v[104:107], 0
	v_mfma_f32_16x16x32_bf16 v[78:81], v[78:81], v[108:111], v[28:31]
	s_nop 6
	v_cndmask_b32_e32 v30, v158, v6, vcc
	v_cmp_le_i32_e32 vcc, v52, v154
	v_max3_f32 v28, v0, s87, v1
	v_max3_f32 v28, v28, v2, v3
	v_cndmask_b32_e32 v37, v158, v7, vcc
	v_cmp_le_i32_e32 vcc, v53, v154
	v_max3_f32 v28, v28, v4, v5
	v_max3_f32 v6, v28, v30, v37
	v_cndmask_b32_e32 v38, v158, v8, vcc
	v_cmp_le_i32_e32 vcc, v54, v154
	s_nop 1
	v_cndmask_b32_e32 v39, v158, v9, vcc
	v_cmp_le_i32_e32 vcc, v55, v154
	v_max3_f32 v6, v6, v38, v39
	s_nop 0
	v_cndmask_b32_e32 v10, v158, v10, vcc
	v_cmp_le_i32_e32 vcc, v56, v154
	s_nop 1
	v_cndmask_b32_e32 v11, v158, v11, vcc
	v_cmp_le_i32_e32 vcc, v57, v154
	v_max3_f32 v6, v6, v10, v11
	s_nop 0
	v_cndmask_b32_e32 v40, v158, v12, vcc
	v_cmp_le_i32_e32 vcc, v58, v154
	s_nop 1
	v_cndmask_b32_e32 v41, v158, v13, vcc
	v_cmp_le_i32_e32 vcc, v59, v154
	v_max3_f32 v6, v6, v40, v41
	s_nop 0
	v_cndmask_b32_e32 v14, v158, v14, vcc
	v_cmp_le_i32_e32 vcc, v60, v154
	s_nop 1
	v_cndmask_b32_e32 v15, v158, v15, vcc
	v_cmp_le_i32_e32 vcc, v61, v154
	v_max3_f32 v6, v6, v14, v15
	s_nop 0
	v_cndmask_b32_e32 v49, v158, v20, vcc
	v_cmp_le_i32_e32 vcc, v62, v154
	s_nop 1
	v_cndmask_b32_e32 v50, v158, v21, vcc
	v_cmp_le_i32_e32 vcc, v63, v154
	v_max3_f32 v6, v6, v49, v50
	s_nop 0
	v_cndmask_b32_e32 v22, v158, v22, vcc
	v_cmp_le_i32_e32 vcc, v64, v154
	s_nop 1
	v_cndmask_b32_e32 v23, v158, v23, vcc
	v_cmp_le_i32_e32 vcc, v65, v154
	v_max3_f32 v6, v6, v22, v23
	s_nop 0
	v_cndmask_b32_e32 v51, v158, v24, vcc
	v_cmp_le_i32_e32 vcc, v66, v154
	s_nop 1
	v_cndmask_b32_e32 v52, v158, v25, vcc
	v_cmp_le_i32_e32 vcc, v67, v154
	v_max3_f32 v6, v6, v51, v52
	s_nop 0
	v_cndmask_b32_e32 v53, v158, v26, vcc
	v_cmp_le_i32_e32 vcc, v68, v154
	s_nop 1
	v_cndmask_b32_e32 v31, v158, v27, vcc
	v_cmp_le_i32_e32 vcc, v69, v154
	v_max3_f32 v6, v6, v53, v31
	s_nop 0
	v_cndmask_b32_e32 v26, v158, v32, vcc
	v_cmp_le_i32_e32 vcc, v70, v154
	s_nop 1
	v_cndmask_b32_e32 v27, v158, v33, vcc
	v_cmp_le_i32_e32 vcc, v71, v154
	v_max3_f32 v6, v6, v26, v27
	s_nop 0
	v_cndmask_b32_e32 v32, v158, v34, vcc
	v_cmp_le_i32_e32 vcc, v72, v154
	s_nop 1
	v_cndmask_b32_e32 v33, v158, v35, vcc
	v_cmp_le_i32_e32 vcc, v73, v154
	v_max3_f32 v6, v6, v32, v33
	s_nop 0
	v_cndmask_b32_e32 v28, v158, v78, vcc
	v_cmp_le_i32_e32 vcc, v74, v154
	s_nop 1
	v_cndmask_b32_e32 v29, v158, v79, vcc
	v_cmp_le_i32_e32 vcc, v75, v154
	v_max3_f32 v6, v6, v28, v29
	s_nop 0
	v_cndmask_b32_e32 v34, v158, v80, vcc
	v_cmp_le_i32_e32 vcc, v76, v154
	s_and_b64 vcc, s[78:79], vcc
	s_nop 0
	v_cndmask_b32_e32 v35, v158, v81, vcc
	v_max3_f32 v6, v6, v34, v35
	ds_bpermute_b32 v7, v151, v6
	v_cmp_lt_f32_e32 vcc, s86, v0
	s_waitcnt lgkmcnt(0)
	v_max_f32_e32 v7, v7, v7
	v_max_f32_e32 v6, v6, v7
	ds_bpermute_b32 v7, v217, v6
	s_waitcnt lgkmcnt(0)
	v_max_f32_e32 v7, v7, v7
	v_max_f32_e32 v36, v6, v7
	v_sub_f32_e32 v0, v0, v36
	v_exp_f32_e32 v0, v0
	s_nop 0
	v_cndmask_b32_e32 v0, 0, v0, vcc
	v_cmp_lt_f32_e32 vcc, s86, v1
	v_sub_f32_e32 v1, v1, v36
	v_exp_f32_e32 v1, v1
	v_add_f32_e32 v6, 0, v0
	v_cndmask_b32_e32 v1, 0, v1, vcc
	v_cmp_lt_f32_e32 vcc, s86, v2
	v_sub_f32_e32 v2, v2, v36
	v_exp_f32_e32 v2, v2
	v_add_f32_e32 v7, v1, v6
	v_cndmask_b32_e32 v6, 0, v2, vcc
	v_cmp_lt_f32_e32 vcc, s86, v3
	v_sub_f32_e32 v3, v3, v36
	v_exp_f32_e32 v3, v3
	v_add_f32_e32 v2, v6, v7
	v_cndmask_b32_e32 v7, 0, v3, vcc
	v_add_f32_e32 v3, v7, v2
	v_sub_f32_e32 v2, v4, v36
	v_exp_f32_e32 v2, v2
	v_cmp_lt_f32_e32 vcc, s86, v4
	s_nop 1
	v_cndmask_b32_e32 v2, 0, v2, vcc
	v_add_f32_e32 v4, v2, v3
	v_sub_f32_e32 v3, v5, v36
	v_cmp_lt_f32_e32 vcc, s86, v5
	v_exp_f32_e32 v3, v3
	v_sub_f32_e32 v5, v30, v36
	v_exp_f32_e32 v5, v5
	v_cndmask_b32_e32 v3, 0, v3, vcc
	v_cmp_lt_f32_e32 vcc, s86, v30
	v_add_f32_e32 v4, v3, v4
	s_nop 0
	v_cndmask_b32_e32 v8, 0, v5, vcc
	v_sub_f32_e32 v5, v37, v36
	v_exp_f32_e32 v5, v5
	v_cmp_lt_f32_e32 vcc, s86, v37
	v_add_f32_e32 v4, v8, v4
	s_nop 0
	v_cndmask_b32_e32 v9, 0, v5, vcc
	v_add_f32_e32 v5, v9, v4
	v_sub_f32_e32 v4, v38, v36
	v_exp_f32_e32 v4, v4
	v_cmp_lt_f32_e32 vcc, s86, v38
	s_nop 1
	v_cndmask_b32_e32 v4, 0, v4, vcc
	v_add_f32_e32 v12, v4, v5
	v_sub_f32_e32 v5, v39, v36
	v_exp_f32_e32 v5, v5
	v_cmp_lt_f32_e32 vcc, s86, v39
	s_nop 1
	v_cndmask_b32_e32 v5, 0, v5, vcc
	v_cmp_lt_f32_e32 vcc, s86, v10
	v_sub_f32_e32 v10, v10, v36
	v_exp_f32_e32 v10, v10
	v_add_f32_e32 v13, v5, v12
	v_cndmask_b32_e32 v12, 0, v10, vcc
	v_cmp_lt_f32_e32 vcc, s86, v11
	v_sub_f32_e32 v11, v11, v36
	v_exp_f32_e32 v11, v11
	v_add_f32_e32 v10, v12, v13
	v_cndmask_b32_e32 v13, 0, v11, vcc
	v_add_f32_e32 v11, v13, v10
	v_sub_f32_e32 v10, v40, v36
	v_exp_f32_e32 v10, v10
	v_cmp_lt_f32_e32 vcc, s86, v40
	s_nop 1
	v_cndmask_b32_e32 v10, 0, v10, vcc
	v_add_f32_e32 v20, v10, v11
	v_sub_f32_e32 v11, v41, v36
	v_exp_f32_e32 v11, v11
	v_cmp_lt_f32_e32 vcc, s86, v41
	s_nop 1
	v_cndmask_b32_e32 v11, 0, v11, vcc
	v_cmp_lt_f32_e32 vcc, s86, v14
	v_sub_f32_e32 v14, v14, v36
	v_exp_f32_e32 v14, v14
	v_add_f32_e32 v21, v11, v20
	v_cndmask_b32_e32 v20, 0, v14, vcc
	v_cmp_lt_f32_e32 vcc, s86, v15
	v_sub_f32_e32 v15, v15, v36
	v_exp_f32_e32 v15, v15
	v_add_f32_e32 v14, v20, v21
	v_cndmask_b32_e32 v21, 0, v15, vcc
	v_add_f32_e32 v15, v21, v14
	v_sub_f32_e32 v14, v49, v36
	v_exp_f32_e32 v14, v14
	v_cmp_lt_f32_e32 vcc, s86, v49
	s_nop 1
	v_cndmask_b32_e32 v14, 0, v14, vcc
	v_add_f32_e32 v24, v14, v15
	v_sub_f32_e32 v15, v50, v36
	v_exp_f32_e32 v15, v15
	v_cmp_lt_f32_e32 vcc, s86, v50
	s_nop 1
	v_cndmask_b32_e32 v15, 0, v15, vcc
	v_cmp_lt_f32_e32 vcc, s86, v22
	v_sub_f32_e32 v22, v22, v36
	v_exp_f32_e32 v22, v22
	v_add_f32_e32 v25, v15, v24
	v_cndmask_b32_e32 v24, 0, v22, vcc
	v_cmp_lt_f32_e32 vcc, s86, v23
	v_sub_f32_e32 v23, v23, v36
	v_exp_f32_e32 v23, v23
	v_add_f32_e32 v22, v24, v25
	v_cndmask_b32_e32 v25, 0, v23, vcc
	v_add_f32_e32 v23, v25, v22
	v_sub_f32_e32 v22, v51, v36
	v_exp_f32_e32 v22, v22
	v_cmp_lt_f32_e32 vcc, s86, v51
	s_nop 1
	v_cndmask_b32_e32 v22, 0, v22, vcc
	v_add_f32_e32 v30, v22, v23
	v_sub_f32_e32 v23, v52, v36
	v_exp_f32_e32 v23, v23
	v_cmp_lt_f32_e32 vcc, s86, v52
	s_nop 1
	v_cndmask_b32_e32 v23, 0, v23, vcc
	v_add_f32_e32 v37, v23, v30
	v_sub_f32_e32 v30, v53, v36
	v_exp_f32_e32 v30, v30
	v_cmp_lt_f32_e32 vcc, s86, v53
	s_nop 1
	v_cndmask_b32_e32 v30, 0, v30, vcc
	v_cmp_lt_f32_e32 vcc, s86, v31
	v_sub_f32_e32 v31, v31, v36
	v_exp_f32_e32 v31, v31
	v_add_f32_e32 v37, v30, v37
	v_cndmask_b32_e32 v31, 0, v31, vcc
	v_cmp_lt_f32_e32 vcc, s86, v26
	v_sub_f32_e32 v26, v26, v36
	v_exp_f32_e32 v26, v26
	v_add_f32_e32 v37, v31, v37
	v_cndmask_b32_e32 v26, 0, v26, vcc
	v_cmp_lt_f32_e32 vcc, s86, v27
	v_sub_f32_e32 v27, v27, v36
	v_exp_f32_e32 v27, v27
	v_add_f32_e32 v37, v26, v37
	v_cndmask_b32_e32 v27, 0, v27, vcc
	v_cmp_lt_f32_e32 vcc, s86, v32
	v_sub_f32_e32 v32, v32, v36
	v_exp_f32_e32 v32, v32
	v_add_f32_e32 v37, v27, v37
	v_cndmask_b32_e32 v32, 0, v32, vcc
	v_cmp_lt_f32_e32 vcc, s86, v33
	v_sub_f32_e32 v33, v33, v36
	v_exp_f32_e32 v33, v33
	v_add_f32_e32 v37, v32, v37
	v_cndmask_b32_e32 v33, 0, v33, vcc
	v_cmp_lt_f32_e32 vcc, s86, v28
	v_sub_f32_e32 v28, v28, v36
	v_exp_f32_e32 v28, v28
	v_add_f32_e32 v37, v33, v37
	v_cndmask_b32_e32 v28, 0, v28, vcc
	v_cmp_lt_f32_e32 vcc, s86, v29
	v_sub_f32_e32 v29, v29, v36
	v_exp_f32_e32 v29, v29
	v_add_f32_e32 v37, v28, v37
	v_cndmask_b32_e32 v29, 0, v29, vcc
	v_cmp_lt_f32_e32 vcc, s86, v34
	v_sub_f32_e32 v34, v34, v36
	v_exp_f32_e32 v34, v34
	v_add_f32_e32 v37, v29, v37
	v_cndmask_b32_e32 v34, 0, v34, vcc
	v_cmp_lt_f32_e32 vcc, s86, v35
	v_sub_f32_e32 v35, v35, v36
	v_exp_f32_e32 v35, v35
	v_add_f32_e32 v37, v34, v37
	v_cndmask_b32_e32 v35, 0, v35, vcc
	v_add_f32_e32 v36, v35, v37
	v_mov_b32_e32 v37, v36
	s_nop 1
	v_permlane16_swap_b32_e32 v37, v36
	s_waitcnt lgkmcnt(0)
	v_add_f32_e32 v36, v36, v37
	v_mov_b32_e32 v37, v36
	s_nop 1
	v_permlane32_swap_b32_e32 v37, v36
	s_waitcnt lgkmcnt(0)
	v_add_f32_e32 v36, v36, v37
	v_max_f32_e32 v36, 0x1e3ce508, v36
	v_div_scale_f32 v37, s[0:1], v36, v36, 1.0
	v_rcp_f32_e32 v38, v37
	s_nop 0
	v_fma_f32 v39, -v37, v38, 1.0
	v_fmac_f32_e32 v38, v39, v38
	v_div_scale_f32 v39, vcc, 1.0, v36, 1.0
	v_mul_f32_e32 v40, v39, v38
	v_fma_f32 v41, -v37, v40, v39
	v_fmac_f32_e32 v40, v41, v38
	v_fma_f32 v37, -v37, v40, v39
	v_div_fmas_f32 v37, v37, v38, v40
	v_div_fixup_f32 v36, v37, v36, 1.0
	v_pk_mul_f32 v[6:7], v[6:7], v[36:37] op_sel_hi:[1,0]
	v_pk_mul_f32 v[0:1], v[0:1], v[36:37] op_sel_hi:[1,0]
	v_mul_f32_e32 v49, 0.5, v7
	v_add_f32_e32 v37, v0, v1
	v_fma_f32 v38, 0.5, v7, v6
	v_add_f32_e32 v37, v37, v38
	ds_bpermute_b32 v38, v43, v49
	s_waitcnt lgkmcnt(0)
	v_cndmask_b32_e64 v38, v38, 0, s[74:75]
	v_add_f32_e32 v37, v37, v38
	s_nop 1
	v_mov_b32_dpp v38, v37 quad_perm:[1,0,3,2] row_mask:0xf bank_mask:0xf
	s_waitcnt lgkmcnt(0)
	v_add_f32_e32 v37, v37, v38
	s_nop 1
	v_mov_b32_dpp v38, v37 quad_perm:[2,3,0,1] row_mask:0xf bank_mask:0xf
	s_waitcnt lgkmcnt(0)
	v_add_f32_e32 v37, v37, v38
	s_nop 1
	v_mov_b32_dpp v38, v37 row_half_mirror row_mask:0xf bank_mask:0xf
	s_and_saveexec_b64 s[2:3], s[76:77]
	s_cbranch_execz .LBB0_1126
	s_waitcnt lgkmcnt(0)
	v_add_f32_e32 v37, v37, v38
	ds_write_b32 v47, v37 offset:264
.LBB0_1126:
	s_or_b64 exec, exec, s[2:3]
	v_mov_b32_e32 v37, v36
	v_mov_b32_e32 v40, v36
	v_mov_b32_e32 v41, v36
	v_pk_mul_f32 v[8:9], v[8:9], v[40:41]
	s_waitcnt lgkmcnt(0)
	v_pk_mul_f32 v[38:39], v[2:3], v[36:37]
	v_mul_f32_e32 v50, 0.5, v9
	v_add_f32_e32 v2, v38, v39
	v_fma_f32 v3, 0.5, v9, v8
	v_add_f32_e32 v2, v2, v3
	ds_bpermute_b32 v3, v43, v50
	ds_bpermute_b32 v49, v43, v49
	s_waitcnt lgkmcnt(0)
	v_cndmask_b32_e64 v3, v3, v49, s[74:75]
	v_add_f32_e32 v2, v2, v3
	s_nop 1
	v_mov_b32_dpp v3, v2 quad_perm:[1,0,3,2] row_mask:0xf bank_mask:0xf
	s_waitcnt lgkmcnt(0)
	v_add_f32_e32 v2, v2, v3
	s_nop 1
	v_mov_b32_dpp v3, v2 quad_perm:[2,3,0,1] row_mask:0xf bank_mask:0xf
	s_waitcnt lgkmcnt(0)
	v_add_f32_e32 v2, v2, v3
	s_nop 1
	v_mov_b32_dpp v3, v2 row_half_mirror row_mask:0xf bank_mask:0xf
	s_and_saveexec_b64 s[2:3], s[76:77]
	s_cbranch_execz .LBB0_1128
	s_waitcnt lgkmcnt(0)
	v_add_f32_e32 v2, v2, v3
	ds_write_b32 v47, v2 offset:280
.LBB0_1128:
	s_or_b64 exec, exec, s[2:3]
	s_waitcnt lgkmcnt(0)
	v_pk_mul_f32 v[2:3], v[12:13], v[40:41]
	v_pk_mul_f32 v[4:5], v[4:5], v[36:37]
	v_mul_f32_e32 v49, 0.5, v3
	v_add_f32_e32 v12, v4, v5
	v_fma_f32 v13, 0.5, v3, v2
	v_add_f32_e32 v12, v12, v13
	ds_bpermute_b32 v13, v43, v49
	ds_bpermute_b32 v40, v43, v50
	s_waitcnt lgkmcnt(0)
	v_cndmask_b32_e64 v13, v13, v40, s[74:75]
	v_add_f32_e32 v12, v12, v13
	s_nop 1
	v_mov_b32_dpp v13, v12 quad_perm:[1,0,3,2] row_mask:0xf bank_mask:0xf
	s_waitcnt lgkmcnt(0)
	v_add_f32_e32 v12, v12, v13
	s_nop 1
	v_mov_b32_dpp v13, v12 quad_perm:[2,3,0,1] row_mask:0xf bank_mask:0xf
	s_waitcnt lgkmcnt(0)
	v_add_f32_e32 v12, v12, v13
	s_nop 1
	v_mov_b32_dpp v13, v12 row_half_mirror row_mask:0xf bank_mask:0xf
	s_and_saveexec_b64 s[2:3], s[76:77]
	s_cbranch_execz .LBB0_1130
	s_waitcnt lgkmcnt(0)
	v_add_f32_e32 v12, v12, v13
	ds_write_b32 v47, v12 offset:296
.LBB0_1130:
	s_or_b64 exec, exec, s[2:3]
	v_mov_b32_e32 v40, v36
	v_mov_b32_e32 v41, v36
	s_waitcnt lgkmcnt(0)
	v_pk_mul_f32 v[12:13], v[20:21], v[40:41]
	v_pk_mul_f32 v[10:11], v[10:11], v[36:37]
	v_mul_f32_e32 v50, 0.5, v13
	v_add_f32_e32 v20, v10, v11
	v_fma_f32 v21, 0.5, v13, v12
	v_add_f32_e32 v20, v20, v21
	ds_bpermute_b32 v21, v43, v50
	ds_bpermute_b32 v49, v43, v49
	s_waitcnt lgkmcnt(0)
	v_cndmask_b32_e64 v21, v21, v49, s[74:75]
	v_add_f32_e32 v20, v20, v21
	s_nop 1
	v_mov_b32_dpp v21, v20 quad_perm:[1,0,3,2] row_mask:0xf bank_mask:0xf
	s_waitcnt lgkmcnt(0)
	v_add_f32_e32 v20, v20, v21
	s_nop 1
	v_mov_b32_dpp v21, v20 quad_perm:[2,3,0,1] row_mask:0xf bank_mask:0xf
	s_waitcnt lgkmcnt(0)
	v_add_f32_e32 v20, v20, v21
	s_nop 1
	v_mov_b32_dpp v21, v20 row_half_mirror row_mask:0xf bank_mask:0xf
	s_and_saveexec_b64 s[2:3], s[76:77]
	s_cbranch_execz .LBB0_1132
	s_waitcnt lgkmcnt(0)
	v_add_f32_e32 v20, v20, v21
	ds_write_b32 v47, v20 offset:312
.LBB0_1132:
	s_or_b64 exec, exec, s[2:3]
	s_waitcnt lgkmcnt(0)
	v_pk_mul_f32 v[20:21], v[24:25], v[40:41]
	v_pk_mul_f32 v[14:15], v[14:15], v[36:37]
	v_mul_f32_e32 v49, 0.5, v21
	v_add_f32_e32 v24, v14, v15
	v_fma_f32 v25, 0.5, v21, v20
	v_add_f32_e32 v24, v24, v25
	ds_bpermute_b32 v25, v43, v49
	ds_bpermute_b32 v40, v43, v50
	s_waitcnt lgkmcnt(0)
	v_cndmask_b32_e64 v25, v25, v40, s[74:75]
	v_add_f32_e32 v24, v24, v25
	s_nop 1
	v_mov_b32_dpp v25, v24 quad_perm:[1,0,3,2] row_mask:0xf bank_mask:0xf
	s_waitcnt lgkmcnt(0)
	v_add_f32_e32 v24, v24, v25
	s_nop 1
	v_mov_b32_dpp v25, v24 quad_perm:[2,3,0,1] row_mask:0xf bank_mask:0xf
	s_waitcnt lgkmcnt(0)
	v_add_f32_e32 v24, v24, v25
	s_nop 1
	v_mov_b32_dpp v25, v24 row_half_mirror row_mask:0xf bank_mask:0xf
	s_and_saveexec_b64 s[2:3], s[76:77]
	s_cbranch_execz .LBB0_1134
	s_waitcnt lgkmcnt(0)
	v_add_f32_e32 v24, v24, v25
	ds_write_b32 v47, v24 offset:328
.LBB0_1134:
	s_or_b64 exec, exec, s[2:3]
	v_mov_b32_e32 v40, v36
	v_mov_b32_e32 v41, v36
	s_waitcnt lgkmcnt(0)
	v_pk_mul_f32 v[24:25], v[30:31], v[40:41]
	v_pk_mul_f32 v[22:23], v[22:23], v[36:37]
	v_mul_f32_e32 v50, 0.5, v25
	v_add_f32_e32 v30, v22, v23
	v_fma_f32 v31, 0.5, v25, v24
	v_add_f32_e32 v30, v30, v31
	ds_bpermute_b32 v31, v43, v50
	ds_bpermute_b32 v49, v43, v49
	s_waitcnt lgkmcnt(0)
	v_cndmask_b32_e64 v31, v31, v49, s[74:75]
	v_add_f32_e32 v30, v30, v31
	s_nop 1
	v_mov_b32_dpp v31, v30 quad_perm:[1,0,3,2] row_mask:0xf bank_mask:0xf
	s_waitcnt lgkmcnt(0)
	v_add_f32_e32 v30, v30, v31
	s_nop 1
	v_mov_b32_dpp v31, v30 quad_perm:[2,3,0,1] row_mask:0xf bank_mask:0xf
	s_waitcnt lgkmcnt(0)
	v_add_f32_e32 v30, v30, v31
	s_nop 1
	v_mov_b32_dpp v31, v30 row_half_mirror row_mask:0xf bank_mask:0xf
	s_and_saveexec_b64 s[2:3], s[76:77]
	s_cbranch_execz .LBB0_1136
	s_waitcnt lgkmcnt(0)
	v_add_f32_e32 v30, v30, v31
	ds_write_b32 v47, v30 offset:344
.LBB0_1136:
	s_or_b64 exec, exec, s[2:3]
	s_waitcnt lgkmcnt(0)
	v_pk_mul_f32 v[30:31], v[32:33], v[40:41]
	v_pk_mul_f32 v[26:27], v[26:27], v[36:37]
	v_mul_f32_e32 v40, 0.5, v31
	v_add_f32_e32 v32, v26, v27
	v_fma_f32 v33, 0.5, v31, v30
	v_add_f32_e32 v32, v32, v33
	ds_bpermute_b32 v33, v43, v40
	ds_bpermute_b32 v41, v43, v50
	s_waitcnt lgkmcnt(0)
	v_cndmask_b32_e64 v33, v33, v41, s[74:75]
	v_add_f32_e32 v32, v32, v33
	s_nop 1
	v_mov_b32_dpp v33, v32 quad_perm:[1,0,3,2] row_mask:0xf bank_mask:0xf
	s_waitcnt lgkmcnt(0)
	v_add_f32_e32 v32, v32, v33
	s_nop 1
	v_mov_b32_dpp v33, v32 quad_perm:[2,3,0,1] row_mask:0xf bank_mask:0xf
	s_waitcnt lgkmcnt(0)
	v_add_f32_e32 v32, v32, v33
	s_nop 1
	v_mov_b32_dpp v33, v32 row_half_mirror row_mask:0xf bank_mask:0xf
	s_and_saveexec_b64 s[2:3], s[76:77]
	s_cbranch_execz .LBB0_1138
	s_waitcnt lgkmcnt(0)
	v_add_f32_e32 v32, v32, v33
	ds_write_b32 v47, v32 offset:360
.LBB0_1138:
	s_or_b64 exec, exec, s[2:3]
	v_mov_b32_e32 v32, v36
	s_waitcnt lgkmcnt(0)
	v_mov_b32_e32 v33, v36
	v_pk_mul_f32 v[32:33], v[34:35], v[32:33]
	ds_bpermute_b32 v35, v43, v40
	v_mul_f32_e32 v34, 0.5, v33
	ds_bpermute_b32 v34, v43, v34
	v_pk_mul_f32 v[28:29], v[28:29], v[36:37]
	v_fma_f32 v37, 0.5, v33, v32
	v_add_f32_e32 v36, v28, v29
	v_add_f32_e32 v36, v36, v37
	s_waitcnt lgkmcnt(0)
	v_cndmask_b32_e64 v34, v34, v35, s[74:75]
	v_add_f32_e32 v34, v36, v34
	s_nop 1
	v_mov_b32_dpp v35, v34 quad_perm:[1,0,3,2] row_mask:0xf bank_mask:0xf
	s_waitcnt lgkmcnt(0)
	v_add_f32_e32 v34, v34, v35
	s_nop 1
	v_mov_b32_dpp v35, v34 quad_perm:[2,3,0,1] row_mask:0xf bank_mask:0xf
	s_waitcnt lgkmcnt(0)
	v_add_f32_e32 v34, v34, v35
	s_nop 1
	v_mov_b32_dpp v35, v34 row_half_mirror row_mask:0xf bank_mask:0xf
	s_and_saveexec_b64 s[2:3], s[76:77]
	s_cbranch_execz .LBB0_1140
	s_waitcnt lgkmcnt(0)
	v_add_f32_e32 v34, v34, v35
	ds_write_b32 v47, v34 offset:376

.LBB0_1284:
	s_lshl_b32 s13, s14, 6
	s_lshl_b32 s14, 1, s14
	s_mul_i32 s2, s0, 0x4800
	v_and_b32_e32 v32, s14, v172
	s_add_i32 s96, s2, 0
	v_cmp_ne_u32_e32 vcc, 0, v32
	s_cmp_eq_u64 vcc, 0
	s_cselect_b64 s[2:3], -1, 0
	s_cmp_gt_i32 s13, s76
	s_cselect_b64 s[74:75], -1, 0
	s_or_b64 s[2:3], s[2:3], s[74:75]
	v_mov_b32_e32 v133, v196
	s_and_b64 vcc, exec, s[2:3]
	s_cbranch_vccnz .LBB0_1306
	v_cmp_eq_u32_e32 vcc, 0, v32
	s_or_b32 s15, s13, 63
	v_cmp_le_i32_e64 s[74:75], s15, v152
	v_cndmask_b32_e32 v138, 0, v211, vcc
	v_cmp_ge_u32_e64 s[2:3], s13, v138
	s_and_b64 s[2:3], s[2:3], s[74:75]
	v_and_b32_e32 v139, 63, v133
	v_cndmask_b32_e64 v32, 0, 1, s[2:3]
	v_cmp_ne_u32_e64 s[2:3], 0, v32
	v_and_b32_e32 v137, 15, v133
	v_and_b32_e32 v32, 48, v133
	v_or_b32_e32 v135, 48, v139
	s_mov_b64 s[74:75], -1
	s_cmp_lg_u64 s[2:3], exec
	v_add_u32_e32 v136, s96, v32
	v_mul_u32_u24_e32 v134, 0x90, v137
	v_mul_u32_u24_e32 v132, 0x90, v135
	s_cbranch_scc0 .LBB0_1299
	v_mad_u32_u24 v32, v137, s88, v136
	ds_read_b128 v[52:55], v32
	ds_read_b128 v[56:59], v32 offset:64
	ds_read_b128 v[60:63], v32 offset:2304
	ds_read_b128 v[64:67], v32 offset:2368
	ds_read_b128 v[68:71], v32 offset:4608
	ds_read_b128 v[72:75], v32 offset:4672
	v_mad_u32_u24 v32, v135, s88, v136
	ds_read_b128 v[76:79], v32
	ds_read_b128 v[48:51], v32 offset:64
	s_cmp_gt_i32 s15, s78
	s_mov_b64 s[2:3], -1
	s_cbranch_scc1 .LBB0_1292
	s_waitcnt lgkmcnt(7)
	v_mfma_f32_16x16x32_bf16 v[32:35], v[52:55], v[96:99], 0
	s_waitcnt lgkmcnt(5)
	v_mfma_f32_16x16x32_bf16 v[36:39], v[60:63], v[96:99], 0
	s_waitcnt lgkmcnt(3)
	v_mfma_f32_16x16x32_bf16 v[40:43], v[68:71], v[96:99], 0
	s_waitcnt lgkmcnt(1)
	v_mfma_f32_16x16x32_bf16 v[44:47], v[76:79], v[96:99], 0
	v_mfma_f32_16x16x32_bf16 v[32:35], v[56:59], v[100:103], v[32:35]
	v_mfma_f32_16x16x32_bf16 v[36:39], v[64:67], v[100:103], v[36:39]
	v_mfma_f32_16x16x32_bf16 v[40:43], v[72:75], v[100:103], v[40:43]
	s_waitcnt lgkmcnt(0)
	v_mfma_f32_16x16x32_bf16 v[44:47], v[48:51], v[100:103], v[44:47]
	s_nop 7
	s_nop 7
	s_nop 0
	v_max3_f32 v80, v158, v32, v33
	s_nop 0
	v_max3_f32 v80, v80, v34, v35
	s_nop 0
	v_max3_f32 v80, v80, v36, v37
	s_nop 0
	v_max3_f32 v80, v80, v38, v39
	s_nop 0
	v_max3_f32 v80, v80, v40, v41
	s_nop 0
	v_max3_f32 v80, v80, v42, v43
	s_nop 0
	v_max3_f32 v80, v80, v44, v45
	s_nop 0
	v_max3_f32 v80, v80, v46, v47
	s_nop 0
	v_cndmask_b32_e32 v80, v80, v158, vcc
	v_mov_b32_e32 v81, v80
	s_nop 1
	v_permlane16_swap_b32_e32 v81, v80
	s_waitcnt lgkmcnt(0)
	v_max3_f32 v80, v80, v81, v158
	v_mov_b32_e32 v81, v80
	s_nop 1
	v_permlane32_swap_b32_e32 v81, v80
	s_waitcnt lgkmcnt(0)
	v_max3_f32 v80, v80, v81, v158
	s_nop 0
	v_max3_f32 v163, v155, v80, v158
	s_nop 0
	v_cndmask_b32_e32 v84, v163, v212, vcc
	v_sub_f32_e32 v35, v35, v84
	v_sub_f32_e32 v34, v34, v84
	v_sub_f32_e32 v33, v33, v84
	v_sub_f32_e32 v32, v32, v84
	v_sub_f32_e32 v39, v39, v84
	v_sub_f32_e32 v38, v38, v84
	v_exp_f32_e32 v88, v32
	v_exp_f32_e32 v89, v33
	v_exp_f32_e32 v90, v34
	v_exp_f32_e32 v91, v35
	v_sub_f32_e32 v32, v37, v84
	v_sub_f32_e32 v33, v36, v84
	v_exp_f32_e32 v128, v33
	v_exp_f32_e32 v130, v38
	v_exp_f32_e32 v131, v39
	v_exp_f32_e32 v129, v32
	v_sub_f32_e32 v36, v43, v84
	v_sub_f32_e32 v37, v42, v84
	v_sub_f32_e32 v38, v41, v84
	v_sub_f32_e32 v39, v40, v84
	v_exp_f32_e32 v80, v39
	v_exp_f32_e32 v81, v38
	v_exp_f32_e32 v82, v37
	v_exp_f32_e32 v83, v36
	v_sub_f32_e32 v36, v47, v84
	v_sub_f32_e32 v37, v46, v84
	v_sub_f32_e32 v38, v45, v84
	v_sub_f32_e32 v39, v44, v84
	v_exp_f32_e32 v84, v39
	v_exp_f32_e32 v86, v37
	v_exp_f32_e32 v87, v36
	v_exp_f32_e32 v85, v38
	v_pk_add_f32 v[32:33], v[88:89], 0 op_sel_hi:[1,0]
	v_pk_add_f32 v[34:35], v[90:91], 0 op_sel_hi:[1,0]
	v_pk_add_f32 v[32:33], v[128:129], v[32:33]
	v_pk_add_f32 v[34:35], v[130:131], v[34:35]
	v_pk_add_f32 v[32:33], v[80:81], v[32:33]
	v_pk_add_f32 v[34:35], v[82:83], v[34:35]
	v_pk_add_f32 v[32:33], v[84:85], v[32:33]
	v_pk_add_f32 v[34:35], v[86:87], v[34:35]
	v_add_f32_e32 v32, v32, v33
	v_add_f32_e32 v33, v34, v35
	v_add_f32_e32 v32, v32, v33
	v_mov_b32_e32 v33, v32
	s_nop 1
	v_permlane16_swap_b32_e32 v33, v32
	v_sub_f32_e32 v34, v155, v163
	v_exp_f32_e32 v92, v34
	s_waitcnt lgkmcnt(0)
	v_add_f32_e32 v140, v32, v33
	v_mov_b32_e32 v141, v140
	s_nop 1
	v_permlane32_swap_b32_e32 v141, v140
	v_cmp_eq_f32_e32 vcc, 1.0, v92
	s_cmp_lg_u64 vcc, exec
	s_cbranch_scc0 .LBB0_1289
	v_pk_mul_f32 v[46:47], v[18:19], v[92:93] op_sel_hi:[1,0]
	v_pk_mul_f32 v[44:45], v[16:17], v[92:93] op_sel_hi:[1,0]
	v_pk_mul_f32 v[42:43], v[22:23], v[92:93] op_sel_hi:[1,0]
	v_pk_mul_f32 v[40:41], v[20:21], v[92:93] op_sel_hi:[1,0]
	v_pk_mul_f32 v[38:39], v[26:27], v[92:93] op_sel_hi:[1,0]
	v_pk_mul_f32 v[36:37], v[24:25], v[92:93] op_sel_hi:[1,0]
	v_pk_mul_f32 v[34:35], v[30:31], v[92:93] op_sel_hi:[1,0]
	v_pk_mul_f32 v[32:33], v[28:29], v[92:93] op_sel_hi:[1,0]
	s_mov_b64 s[2:3], 0

.LBB0_1292:
	s_and_b64 vcc, exec, s[2:3]
	s_cbranch_vccz .LBB0_1298
	s_waitcnt lgkmcnt(1)
	v_mfma_f32_16x16x32_bf16 v[44:47], v[76:79], v[96:99], 0
	v_mfma_f32_16x16x32_bf16 v[32:35], v[52:55], v[96:99], 0
	v_lshrrev_b32_e32 v52, 4, v139
	v_mfma_f32_16x16x32_bf16 v[36:39], v[60:63], v[96:99], 0
	v_mfma_f32_16x16x32_bf16 v[40:43], v[68:71], v[96:99], 0
	s_waitcnt lgkmcnt(0)
	v_mfma_f32_16x16x32_bf16 v[44:47], v[48:51], v[100:103], v[44:47]
	v_lshl_or_b32 v48, v52, 2, s13
	v_cmp_ge_u32_e32 vcc, v48, v138
	v_cmp_le_i32_e64 s[2:3], v48, v152
	v_mfma_f32_16x16x32_bf16 v[32:35], v[56:59], v[100:103], v[32:35]
	s_and_b64 vcc, vcc, s[2:3]
	v_or_b32_e32 v49, 1, v48
	v_cmp_lt_i32_e64 s[2:3], v48, v152
	v_mfma_f32_16x16x32_bf16 v[36:39], v[64:67], v[100:103], v[36:39]
	v_or_b32_e32 v50, 2, v48
	v_mfma_f32_16x16x32_bf16 v[40:43], v[72:75], v[100:103], v[40:43]
	s_nop 7
	s_nop 7
	s_nop 1
	v_cndmask_b32_e32 v32, v158, v32, vcc
	v_cmp_ge_u32_e32 vcc, v49, v138
	s_and_b64 vcc, s[2:3], vcc
	v_cmp_le_i32_e64 s[2:3], v50, v152
	v_cndmask_b32_e32 v33, v158, v33, vcc
	v_cmp_ge_u32_e32 vcc, v50, v138
	s_and_b64 vcc, vcc, s[2:3]
	v_or_b32_e32 v50, 3, v48
	v_cndmask_b32_e32 v34, v158, v34, vcc
	v_cmp_ge_u32_e32 vcc, v50, v138
	v_cmp_le_i32_e64 s[2:3], v50, v152
	s_and_b64 vcc, vcc, s[2:3]
	v_or_b32_e32 v50, 16, v48
	v_cndmask_b32_e32 v35, v158, v35, vcc
	v_cmp_ge_u32_e32 vcc, v50, v138
	v_cmp_le_i32_e64 s[2:3], v50, v152
	s_and_b64 vcc, vcc, s[2:3]
	v_or_b32_e32 v50, 17, v48
	v_cndmask_b32_e32 v36, v158, v36, vcc
	v_cmp_ge_u32_e32 vcc, v50, v138
	v_cmp_le_i32_e64 s[2:3], v50, v152
	s_and_b64 vcc, vcc, s[2:3]
	v_or_b32_e32 v50, 18, v48
	v_cndmask_b32_e32 v37, v158, v37, vcc
	v_cmp_ge_u32_e32 vcc, v50, v138
	v_cmp_le_i32_e64 s[2:3], v50, v152
	s_and_b64 vcc, vcc, s[2:3]
	v_or_b32_e32 v50, 19, v48
	v_cndmask_b32_e32 v38, v158, v38, vcc
	v_cmp_ge_u32_e32 vcc, v50, v138
	v_cmp_le_i32_e64 s[2:3], v50, v152
	s_and_b64 vcc, vcc, s[2:3]
	v_or_b32_e32 v50, 32, v48
	v_cndmask_b32_e32 v39, v158, v39, vcc
	v_cmp_ge_u32_e32 vcc, v50, v138
	v_cmp_le_i32_e64 s[2:3], v50, v152
	s_and_b64 vcc, vcc, s[2:3]
	v_or_b32_e32 v50, 33, v48
	v_cndmask_b32_e32 v40, v158, v40, vcc
	v_cmp_ge_u32_e32 vcc, v50, v138
	v_cmp_le_i32_e64 s[2:3], v50, v152
	s_and_b64 vcc, vcc, s[2:3]
	v_or_b32_e32 v50, 34, v48
	v_cndmask_b32_e32 v41, v158, v41, vcc
	v_cmp_ge_u32_e32 vcc, v50, v138
	v_cmp_le_i32_e64 s[2:3], v50, v152
	s_and_b64 vcc, vcc, s[2:3]
	v_or_b32_e32 v50, 35, v48
	v_cndmask_b32_e32 v42, v158, v42, vcc
	v_cmp_ge_u32_e32 vcc, v50, v138
	v_cmp_le_i32_e64 s[2:3], v50, v152
	s_and_b64 vcc, vcc, s[2:3]
	v_or_b32_e32 v50, 48, v48
	v_cndmask_b32_e32 v43, v158, v43, vcc
	v_cmp_ge_u32_e32 vcc, v50, v138
	v_cmp_le_i32_e64 s[2:3], v50, v152
	s_and_b64 vcc, vcc, s[2:3]
	v_or_b32_e32 v50, 49, v48
	v_max3_f32 v49, v32, s87, v33
	v_cndmask_b32_e32 v44, v158, v44, vcc
	v_cmp_ge_u32_e32 vcc, v50, v138
	v_cmp_le_i32_e64 s[2:3], v50, v152
	v_max3_f32 v49, v49, v34, v35
	s_and_b64 vcc, vcc, s[2:3]
	v_or_b32_e32 v50, 50, v48
	v_max3_f32 v49, v49, v36, v37
	v_cndmask_b32_e32 v45, v158, v45, vcc
	v_cmp_ge_u32_e32 vcc, v50, v138
	v_cmp_le_i32_e64 s[2:3], v50, v152
	v_max3_f32 v49, v49, v38, v39
	s_and_b64 vcc, vcc, s[2:3]
	v_or_b32_e32 v48, 51, v48
	v_max3_f32 v49, v49, v40, v41
	v_cndmask_b32_e32 v46, v158, v46, vcc
	v_cmp_ge_u32_e32 vcc, v48, v138
	v_cmp_le_i32_e64 s[2:3], v48, v152
	v_max3_f32 v49, v49, v42, v43
	s_and_b64 vcc, vcc, s[2:3]
	v_max3_f32 v49, v49, v44, v45
	v_cndmask_b32_e32 v47, v158, v47, vcc
	v_max3_f32 v48, v49, v46, v47
	v_mov_b32_e32 v49, v48
	s_nop 1
	v_permlane16_swap_b32_e32 v49, v48
	s_waitcnt lgkmcnt(0)
	v_max3_f32 v48, v48, v49, v158
	v_mov_b32_e32 v49, v48
	s_nop 1
	v_permlane32_swap_b32_e32 v49, v48
	s_waitcnt lgkmcnt(0)
	v_max3_f32 v48, v48, v49, v158
	v_cmp_lt_f32_e32 vcc, s86, v32
	v_max3_f32 v163, v155, v48, v158
	s_mov_b64 s[2:3], -1
	v_sub_f32_e32 v48, v32, v163
	v_exp_f32_e32 v48, v48
	v_sub_f32_e32 v49, v33, v163
	v_exp_f32_e32 v49, v49
	v_cndmask_b32_e32 v56, 0, v48, vcc
	v_cmp_lt_f32_e32 vcc, s86, v33
	v_sub_f32_e32 v33, v34, v163
	v_exp_f32_e32 v33, v33
	v_cndmask_b32_e32 v57, 0, v49, vcc
	v_sub_f32_e32 v48, v35, v163
	v_cmp_lt_f32_e32 vcc, s86, v34
	v_exp_f32_e32 v48, v48
	v_sub_f32_e32 v34, v37, v163
	v_cndmask_b32_e32 v60, 0, v33, vcc
	v_sub_f32_e32 v33, v36, v163
	v_exp_f32_e32 v33, v33
	v_exp_f32_e32 v34, v34
	v_cmp_lt_f32_e32 vcc, s86, v35
	v_add_f32_e32 v32, 0, v56
	v_add_f32_e32 v32, v57, v32
	v_cndmask_b32_e32 v61, 0, v48, vcc
	v_cmp_lt_f32_e32 vcc, s86, v36
	v_add_f32_e32 v32, v60, v32
	v_add_f32_e32 v32, v61, v32
	v_cndmask_b32_e32 v62, 0, v33, vcc
	v_cmp_lt_f32_e32 vcc, s86, v37
	v_sub_f32_e32 v33, v38, v163
	v_exp_f32_e32 v33, v33
	v_cndmask_b32_e32 v63, 0, v34, vcc
	v_sub_f32_e32 v34, v39, v163
	v_exp_f32_e32 v34, v34
	v_cmp_lt_f32_e32 vcc, s86, v38
	v_add_f32_e32 v32, v62, v32
	v_add_f32_e32 v32, v63, v32
	v_cndmask_b32_e32 v64, 0, v33, vcc
	v_cmp_lt_f32_e32 vcc, s86, v39
	v_sub_f32_e32 v33, v40, v163
	v_exp_f32_e32 v33, v33
	v_cndmask_b32_e32 v65, 0, v34, vcc
	v_sub_f32_e32 v34, v41, v163
	v_exp_f32_e32 v34, v34
	v_cmp_lt_f32_e32 vcc, s86, v40
	v_add_f32_e32 v32, v64, v32
	v_add_f32_e32 v32, v65, v32
	v_cndmask_b32_e32 v49, 0, v33, vcc
	v_cmp_lt_f32_e32 vcc, s86, v41
	v_sub_f32_e32 v33, v42, v163
	v_exp_f32_e32 v33, v33
	v_cndmask_b32_e32 v50, 0, v34, vcc
	v_sub_f32_e32 v34, v43, v163
	v_exp_f32_e32 v34, v34
	v_cmp_lt_f32_e32 vcc, s86, v42
	v_add_f32_e32 v32, v49, v32
	v_add_f32_e32 v32, v50, v32
	v_cndmask_b32_e32 v51, 0, v33, vcc
	v_cmp_lt_f32_e32 vcc, s86, v43
	v_sub_f32_e32 v33, v44, v163
	v_exp_f32_e32 v33, v33
	v_cndmask_b32_e32 v53, 0, v34, vcc
	v_sub_f32_e32 v34, v45, v163
	v_exp_f32_e32 v34, v34
	v_cmp_lt_f32_e32 vcc, s86, v44
	v_add_f32_e32 v32, v51, v32
	v_add_f32_e32 v32, v53, v32
	v_cndmask_b32_e32 v54, 0, v33, vcc
	v_cmp_lt_f32_e32 vcc, s86, v45
	v_sub_f32_e32 v33, v46, v163
	v_exp_f32_e32 v33, v33
	v_cndmask_b32_e32 v55, 0, v34, vcc
	v_sub_f32_e32 v34, v47, v163
	v_exp_f32_e32 v34, v34
	v_add_f32_e32 v32, v54, v32
	v_cmp_lt_f32_e32 vcc, s86, v46
	v_add_f32_e32 v32, v55, v32
	s_nop 0
	v_cndmask_b32_e32 v58, 0, v33, vcc
	v_cmp_lt_f32_e32 vcc, s86, v47
	v_add_f32_e32 v32, v58, v32
	s_nop 0
	v_cndmask_b32_e32 v59, 0, v34, vcc
	v_add_f32_e32 v32, v59, v32
	v_mov_b32_e32 v33, v32
	s_nop 1
	v_permlane16_swap_b32_e32 v33, v32
	v_sub_f32_e32 v34, v155, v163
	v_exp_f32_e32 v48, v34
	s_waitcnt lgkmcnt(0)
	v_add_f32_e32 v66, v32, v33
	v_mov_b32_e32 v67, v66
	s_nop 1
	v_permlane32_swap_b32_e32 v67, v66
	v_cmp_eq_f32_e32 vcc, 1.0, v48
	s_cmp_lg_u64 vcc, exec
	s_cbranch_scc0 .LBB0_1295
	v_pk_mul_f32 v[46:47], v[18:19], v[48:49] op_sel_hi:[1,0]
	v_pk_mul_f32 v[44:45], v[16:17], v[48:49] op_sel_hi:[1,0]
	v_pk_mul_f32 v[42:43], v[22:23], v[48:49] op_sel_hi:[1,0]
	v_pk_mul_f32 v[40:41], v[20:21], v[48:49] op_sel_hi:[1,0]
	v_pk_mul_f32 v[38:39], v[26:27], v[48:49] op_sel_hi:[1,0]
	v_pk_mul_f32 v[36:37], v[24:25], v[48:49] op_sel_hi:[1,0]
	v_pk_mul_f32 v[34:35], v[30:31], v[48:49] op_sel_hi:[1,0]
	v_pk_mul_f32 v[32:33], v[28:29], v[48:49] op_sel_hi:[1,0]
	s_mov_b64 s[2:3], 0

.LBB0_1307:
	v_and_b32_e32 v16, s14, v173
	v_cmp_ne_u32_e32 vcc, 0, v16
	s_cmp_eq_u64 vcc, 0
	s_cselect_b64 s[2:3], -1, 0
	s_cmp_gt_i32 s13, s77
	s_cselect_b64 s[14:15], -1, 0
	s_or_b64 s[2:3], s[2:3], s[14:15]
	v_mov_b32_e32 v181, v196
	s_and_b64 vcc, exec, s[2:3]
	s_cbranch_vccnz .LBB0_1330
	v_cmp_eq_u32_e32 vcc, 0, v16
	s_or_b32 s14, s13, 63
	v_cmp_le_i32_e64 s[74:75], s14, v154
	v_cndmask_b32_e32 v186, 0, v211, vcc
	v_cmp_ge_u32_e64 s[2:3], s13, v186
	s_and_b64 s[2:3], s[2:3], s[74:75]
	v_and_b32_e32 v187, 63, v181
	v_cndmask_b32_e64 v16, 0, 1, s[2:3]
	v_cmp_ne_u32_e64 s[2:3], 0, v16
	v_and_b32_e32 v185, 15, v181
	v_and_b32_e32 v16, 48, v181
	v_or_b32_e32 v183, 48, v187
	s_mov_b64 s[74:75], -1
	s_cmp_lg_u64 s[2:3], exec
	v_add_u32_e32 v184, s96, v16
	v_mul_u32_u24_e32 v182, 0x90, v185
	v_mul_u32_u24_e32 v155, 0x90, v183
	s_cbranch_scc0 .LBB0_1322
	v_mad_u32_u24 v16, v185, s88, v184
	ds_read_b128 v[20:23], v16
	ds_read_b128 v[24:27], v16 offset:64
	s_waitcnt lgkmcnt(3)
	ds_read_b128 v[76:79], v16 offset:2304
	ds_read_b128 v[80:83], v16 offset:2368
	ds_read_b128 v[84:87], v16 offset:4608
	ds_read_b128 v[88:91], v16 offset:4672
	v_mad_u32_u24 v16, v183, s88, v184
	ds_read_b128 v[128:131], v16
	ds_read_b128 v[16:19], v16 offset:64
	s_cmp_gt_i32 s14, s93
	s_mov_b64 s[2:3], -1
	s_cbranch_scc1 .LBB0_1315
	s_waitcnt lgkmcnt(7)
	v_mfma_f32_16x16x32_bf16 v[44:47], v[20:23], v[104:107], 0
	s_waitcnt lgkmcnt(5)
	v_mfma_f32_16x16x32_bf16 v[48:51], v[76:79], v[104:107], 0
	s_waitcnt lgkmcnt(3)
	v_mfma_f32_16x16x32_bf16 v[52:55], v[84:87], v[104:107], 0
	s_waitcnt lgkmcnt(1)
	v_mfma_f32_16x16x32_bf16 v[56:59], v[128:131], v[104:107], 0
	v_mfma_f32_16x16x32_bf16 v[44:47], v[24:27], v[108:111], v[44:47]
	v_mfma_f32_16x16x32_bf16 v[48:51], v[80:83], v[108:111], v[48:51]
	v_mfma_f32_16x16x32_bf16 v[52:55], v[88:91], v[108:111], v[52:55]
	s_waitcnt lgkmcnt(0)
	v_mfma_f32_16x16x32_bf16 v[56:59], v[16:19], v[108:111], v[56:59]
	s_nop 7
	s_nop 7
	s_nop 0
	v_max3_f32 v92, v158, v44, v45
	s_nop 0
	v_max3_f32 v92, v92, v46, v47
	s_nop 0
	v_max3_f32 v92, v92, v48, v49
	s_nop 0
	v_max3_f32 v92, v92, v50, v51
	s_nop 0
	v_max3_f32 v92, v92, v52, v53
	s_nop 0
	v_max3_f32 v92, v92, v54, v55
	s_nop 0
	v_max3_f32 v92, v92, v56, v57
	s_nop 0
	v_max3_f32 v92, v92, v58, v59
	s_nop 0
	v_cndmask_b32_e32 v92, v92, v158, vcc
	v_mov_b32_e32 v132, v92
	s_nop 1
	v_permlane16_swap_b32_e32 v132, v92
	s_waitcnt lgkmcnt(0)
	v_max3_f32 v92, v92, v132, v158
	v_mov_b32_e32 v132, v92
	s_nop 1
	v_permlane32_swap_b32_e32 v132, v92
	s_waitcnt lgkmcnt(0)
	v_max3_f32 v92, v92, v132, v158
	s_nop 0
	v_max3_f32 v175, v153, v92, v158
	s_nop 0
	v_cndmask_b32_e32 v92, v175, v212, vcc
	v_sub_f32_e32 v47, v47, v92
	v_sub_f32_e32 v46, v46, v92
	v_sub_f32_e32 v45, v45, v92
	v_sub_f32_e32 v44, v44, v92
	v_sub_f32_e32 v51, v51, v92
	v_sub_f32_e32 v50, v50, v92
	v_exp_f32_e32 v140, v44
	v_exp_f32_e32 v141, v45
	v_exp_f32_e32 v142, v46
	v_exp_f32_e32 v143, v47
	v_sub_f32_e32 v44, v49, v92
	v_sub_f32_e32 v45, v48, v92
	v_exp_f32_e32 v144, v45
	v_exp_f32_e32 v146, v50
	v_exp_f32_e32 v147, v51
	v_exp_f32_e32 v145, v44
	v_sub_f32_e32 v48, v55, v92
	v_sub_f32_e32 v49, v54, v92
	v_sub_f32_e32 v50, v53, v92
	v_sub_f32_e32 v51, v52, v92
	v_exp_f32_e32 v132, v51
	v_exp_f32_e32 v133, v50
	v_exp_f32_e32 v134, v49
	v_exp_f32_e32 v135, v48
	v_sub_f32_e32 v48, v59, v92
	v_sub_f32_e32 v49, v58, v92
	v_sub_f32_e32 v50, v57, v92
	v_sub_f32_e32 v51, v56, v92
	v_exp_f32_e32 v136, v51
	v_exp_f32_e32 v138, v49
	v_exp_f32_e32 v139, v48
	v_exp_f32_e32 v137, v50
	v_pk_add_f32 v[44:45], v[140:141], 0 op_sel_hi:[1,0]
	v_pk_add_f32 v[46:47], v[142:143], 0 op_sel_hi:[1,0]
	v_pk_add_f32 v[44:45], v[144:145], v[44:45]
	v_pk_add_f32 v[46:47], v[146:147], v[46:47]
	v_pk_add_f32 v[44:45], v[132:133], v[44:45]
	v_pk_add_f32 v[46:47], v[134:135], v[46:47]
	v_pk_add_f32 v[44:45], v[136:137], v[44:45]
	v_pk_add_f32 v[46:47], v[138:139], v[46:47]
	v_add_f32_e32 v44, v44, v45
	v_add_f32_e32 v45, v46, v47
	v_add_f32_e32 v44, v44, v45
	v_mov_b32_e32 v45, v44
	s_nop 1
	v_permlane16_swap_b32_e32 v45, v44
	v_sub_f32_e32 v46, v153, v175
	v_exp_f32_e32 v92, v46
	s_waitcnt lgkmcnt(0)
	v_add_f32_e32 v188, v44, v45
	v_mov_b32_e32 v189, v188
	s_nop 1
	v_permlane32_swap_b32_e32 v189, v188
	v_cmp_eq_f32_e32 vcc, 1.0, v92
	s_cmp_lg_u64 vcc, exec
	s_cbranch_scc0 .LBB0_1312
	v_pk_mul_f32 v[58:59], v[2:3], v[92:93] op_sel_hi:[1,0]
	v_pk_mul_f32 v[56:57], v[0:1], v[92:93] op_sel_hi:[1,0]
	v_pk_mul_f32 v[54:55], v[6:7], v[92:93] op_sel_hi:[1,0]
	v_pk_mul_f32 v[52:53], v[4:5], v[92:93] op_sel_hi:[1,0]
	v_pk_mul_f32 v[50:51], v[10:11], v[92:93] op_sel_hi:[1,0]
	v_pk_mul_f32 v[48:49], v[8:9], v[92:93] op_sel_hi:[1,0]
	v_pk_mul_f32 v[46:47], v[14:15], v[92:93] op_sel_hi:[1,0]
	v_pk_mul_f32 v[44:45], v[12:13], v[92:93] op_sel_hi:[1,0]
	s_mov_b64 s[2:3], 0

.LBB0_1315:
	s_and_b64 vcc, exec, s[2:3]
	s_cbranch_vccz .LBB0_1321
	s_waitcnt lgkmcnt(7)
	v_mfma_f32_16x16x32_bf16 v[20:23], v[20:23], v[104:107], 0
	v_lshrrev_b32_e32 v49, 4, v187
	v_lshl_or_b32 v48, v49, 2, s13
	v_cmp_ge_u32_e32 vcc, v48, v186
	s_waitcnt lgkmcnt(6)
	v_mfma_f32_16x16x32_bf16 v[20:23], v[24:27], v[108:111], v[20:23]
	v_cmp_le_i32_e64 s[2:3], v48, v154
	s_and_b64 vcc, vcc, s[2:3]
	v_cmp_lt_i32_e64 s[2:3], v48, v154
	s_waitcnt lgkmcnt(5)
	v_mfma_f32_16x16x32_bf16 v[24:27], v[76:79], v[104:107], 0
	s_waitcnt lgkmcnt(3)
	v_mfma_f32_16x16x32_bf16 v[44:47], v[84:87], v[104:107], 0
	s_waitcnt lgkmcnt(1)
	v_mfma_f32_16x16x32_bf16 v[50:53], v[128:131], v[104:107], 0
	v_mfma_f32_16x16x32_bf16 v[24:27], v[80:83], v[108:111], v[24:27]
	v_mfma_f32_16x16x32_bf16 v[44:47], v[88:91], v[108:111], v[44:47]
	s_waitcnt lgkmcnt(0)
	v_mfma_f32_16x16x32_bf16 v[16:19], v[16:19], v[108:111], v[50:53]
	s_nop 7
	s_nop 7
	s_nop 0
	v_cndmask_b32_e32 v20, v158, v20, vcc
	s_nop 1
	v_or_b32_e32 v50, 1, v48
	v_cmp_ge_u32_e32 vcc, v50, v186
	s_and_b64 vcc, s[2:3], vcc
	v_or_b32_e32 v51, 2, v48
	v_cndmask_b32_e32 v21, v158, v21, vcc
	v_cmp_ge_u32_e32 vcc, v51, v186
	v_cmp_le_i32_e64 s[2:3], v48, v152
	s_and_b64 vcc, s[2:3], vcc
	v_or_b32_e32 v51, 3, v48
	v_cndmask_b32_e32 v22, v158, v22, vcc
	v_cmp_ge_u32_e32 vcc, v51, v186
	v_cmp_le_i32_e64 s[2:3], v51, v154
	s_and_b64 vcc, vcc, s[2:3]
	v_or_b32_e32 v51, 16, v48
	v_cndmask_b32_e32 v23, v158, v23, vcc
	v_cmp_ge_u32_e32 vcc, v51, v186
	v_cmp_le_i32_e64 s[2:3], v51, v154
	s_and_b64 vcc, vcc, s[2:3]
	v_or_b32_e32 v51, 17, v48
	v_cndmask_b32_e32 v24, v158, v24, vcc
	v_cmp_ge_u32_e32 vcc, v51, v186
	v_cmp_le_i32_e64 s[2:3], v51, v154
	s_and_b64 vcc, vcc, s[2:3]
	v_or_b32_e32 v51, 18, v48
	v_cndmask_b32_e32 v25, v158, v25, vcc
	v_cmp_ge_u32_e32 vcc, v51, v186
	v_cmp_le_i32_e64 s[2:3], v51, v154
	s_and_b64 vcc, vcc, s[2:3]
	v_or_b32_e32 v51, 19, v48
	v_cndmask_b32_e32 v26, v158, v26, vcc
	v_cmp_ge_u32_e32 vcc, v51, v186
	v_cmp_le_i32_e64 s[2:3], v51, v154
	s_and_b64 vcc, vcc, s[2:3]
	v_or_b32_e32 v51, 32, v48
	v_cndmask_b32_e32 v27, v158, v27, vcc
	v_cmp_ge_u32_e32 vcc, v51, v186
	v_cmp_le_i32_e64 s[2:3], v51, v154
	s_and_b64 vcc, vcc, s[2:3]
	v_or_b32_e32 v51, 33, v48
	v_cndmask_b32_e32 v44, v158, v44, vcc
	v_cmp_ge_u32_e32 vcc, v51, v186
	v_cmp_le_i32_e64 s[2:3], v51, v154
	s_and_b64 vcc, vcc, s[2:3]
	v_or_b32_e32 v51, 34, v48
	v_cndmask_b32_e32 v45, v158, v45, vcc
	v_cmp_ge_u32_e32 vcc, v51, v186
	v_cmp_le_i32_e64 s[2:3], v51, v154
	s_and_b64 vcc, vcc, s[2:3]
	v_or_b32_e32 v51, 35, v48
	v_cndmask_b32_e32 v46, v158, v46, vcc
	v_cmp_ge_u32_e32 vcc, v51, v186
	v_cmp_le_i32_e64 s[2:3], v51, v154
	s_and_b64 vcc, vcc, s[2:3]
	v_or_b32_e32 v51, 48, v48
	v_cndmask_b32_e32 v47, v158, v47, vcc
	v_cmp_ge_u32_e32 vcc, v51, v186
	v_cmp_le_i32_e64 s[2:3], v51, v154
	s_and_b64 vcc, vcc, s[2:3]
	v_or_b32_e32 v51, 49, v48
	v_max3_f32 v50, v20, s87, v21
	v_cndmask_b32_e32 v16, v158, v16, vcc
	v_cmp_ge_u32_e32 vcc, v51, v186
	v_cmp_le_i32_e64 s[2:3], v51, v154
	v_max3_f32 v50, v50, v22, v23
	s_and_b64 vcc, vcc, s[2:3]
	v_or_b32_e32 v51, 50, v48
	v_max3_f32 v50, v50, v24, v25
	v_cndmask_b32_e32 v17, v158, v17, vcc
	v_cmp_ge_u32_e32 vcc, v51, v186
	v_cmp_le_i32_e64 s[2:3], v51, v154
	v_max3_f32 v50, v50, v26, v27
	s_and_b64 vcc, vcc, s[2:3]
	v_or_b32_e32 v48, 51, v48
	v_max3_f32 v50, v50, v44, v45
	v_cndmask_b32_e32 v18, v158, v18, vcc
	v_cmp_ge_u32_e32 vcc, v48, v186
	v_cmp_le_i32_e64 s[2:3], v48, v154
	v_max3_f32 v50, v50, v46, v47
	s_and_b64 vcc, vcc, s[2:3]
	v_max3_f32 v50, v50, v16, v17
	v_cndmask_b32_e32 v19, v158, v19, vcc
	v_max3_f32 v48, v50, v18, v19
	v_mov_b32_e32 v50, v48
	s_nop 1
	v_permlane16_swap_b32_e32 v50, v48
	s_waitcnt lgkmcnt(0)
	v_max3_f32 v48, v48, v50, v158
	v_mov_b32_e32 v50, v48
	s_nop 1
	v_permlane32_swap_b32_e32 v50, v48
	s_waitcnt lgkmcnt(0)
	v_max3_f32 v48, v48, v50, v158
	v_cmp_lt_f32_e32 vcc, s86, v20
	v_max3_f32 v175, v153, v48, v158
	s_mov_b64 s[2:3], -1
	v_sub_f32_e32 v48, v20, v175
	v_exp_f32_e32 v48, v48
	v_sub_f32_e32 v50, v21, v175
	v_exp_f32_e32 v50, v50
	v_cndmask_b32_e32 v56, 0, v48, vcc
	v_cmp_lt_f32_e32 vcc, s86, v21
	v_sub_f32_e32 v21, v22, v175
	v_exp_f32_e32 v21, v21
	v_cndmask_b32_e32 v57, 0, v50, vcc
	v_sub_f32_e32 v48, v23, v175
	v_cmp_lt_f32_e32 vcc, s86, v22
	v_exp_f32_e32 v48, v48
	v_sub_f32_e32 v22, v25, v175
	v_cndmask_b32_e32 v76, 0, v21, vcc
	v_sub_f32_e32 v21, v24, v175
	v_exp_f32_e32 v21, v21
	v_cmp_lt_f32_e32 vcc, s86, v23
	v_exp_f32_e32 v22, v22
	v_add_f32_e32 v20, 0, v56
	v_cndmask_b32_e32 v77, 0, v48, vcc
	v_cmp_lt_f32_e32 vcc, s86, v24
	v_add_f32_e32 v20, v57, v20
	v_add_f32_e32 v20, v76, v20
	v_cndmask_b32_e32 v78, 0, v21, vcc
	v_sub_f32_e32 v21, v26, v175
	v_exp_f32_e32 v21, v21
	v_cmp_lt_f32_e32 vcc, s86, v25
	v_add_f32_e32 v20, v77, v20
	v_add_f32_e32 v20, v78, v20
	v_cndmask_b32_e32 v79, 0, v22, vcc
	v_sub_f32_e32 v22, v27, v175
	v_cmp_lt_f32_e32 vcc, s86, v26
	v_exp_f32_e32 v22, v22
	v_add_f32_e32 v20, v79, v20
	v_cndmask_b32_e32 v80, 0, v21, vcc
	v_sub_f32_e32 v21, v44, v175
	v_exp_f32_e32 v21, v21
	v_cmp_lt_f32_e32 vcc, s86, v27
	v_add_f32_e32 v20, v80, v20
	s_nop 0
	v_cndmask_b32_e32 v81, 0, v22, vcc
	v_sub_f32_e32 v22, v45, v175
	v_cmp_lt_f32_e32 vcc, s86, v44
	v_exp_f32_e32 v22, v22
	v_add_f32_e32 v20, v81, v20
	v_cndmask_b32_e32 v50, 0, v21, vcc
	v_sub_f32_e32 v21, v46, v175
	v_exp_f32_e32 v21, v21
	v_cmp_lt_f32_e32 vcc, s86, v45
	v_add_f32_e32 v20, v50, v20
	s_nop 0
	v_cndmask_b32_e32 v51, 0, v22, vcc
	v_sub_f32_e32 v22, v47, v175
	v_cmp_lt_f32_e32 vcc, s86, v46
	v_exp_f32_e32 v22, v22
	v_add_f32_e32 v20, v51, v20
	v_cndmask_b32_e32 v52, 0, v21, vcc
	v_sub_f32_e32 v21, v16, v175
	v_exp_f32_e32 v21, v21
	v_cmp_lt_f32_e32 vcc, s86, v47
	v_add_f32_e32 v20, v52, v20
	s_nop 0
	v_cndmask_b32_e32 v53, 0, v22, vcc
	v_sub_f32_e32 v22, v17, v175
	v_cmp_lt_f32_e32 vcc, s86, v16
	v_add_f32_e32 v20, v53, v20
	v_exp_f32_e32 v22, v22
	v_cndmask_b32_e32 v54, 0, v21, vcc
	v_cmp_lt_f32_e32 vcc, s86, v17
	v_sub_f32_e32 v17, v18, v175
	v_add_f32_e32 v16, v54, v20
	v_exp_f32_e32 v17, v17
	v_sub_f32_e32 v20, v19, v175
	v_exp_f32_e32 v20, v20
	v_cndmask_b32_e32 v55, 0, v22, vcc
	v_cmp_lt_f32_e32 vcc, s86, v18
	v_add_f32_e32 v16, v55, v16
	v_sub_f32_e32 v18, v153, v175
	v_cndmask_b32_e32 v58, 0, v17, vcc
	v_cmp_lt_f32_e32 vcc, s86, v19
	v_add_f32_e32 v16, v58, v16
	v_exp_f32_e32 v48, v18
	v_cndmask_b32_e32 v59, 0, v20, vcc
	v_add_f32_e32 v16, v59, v16
	v_mov_b32_e32 v17, v16
	s_nop 1
	v_permlane16_swap_b32_e32 v17, v16
	v_cmp_eq_f32_e32 vcc, 1.0, v48
	s_cmp_lg_u64 vcc, exec
	s_waitcnt lgkmcnt(0)
	v_add_f32_e32 v82, v16, v17
	v_mov_b32_e32 v83, v82
	s_nop 1
	v_permlane32_swap_b32_e32 v83, v82
	s_cbranch_scc0 .LBB0_1318
	v_pk_mul_f32 v[46:47], v[2:3], v[48:49] op_sel_hi:[1,0]
	v_pk_mul_f32 v[44:45], v[0:1], v[48:49] op_sel_hi:[1,0]
	v_pk_mul_f32 v[26:27], v[6:7], v[48:49] op_sel_hi:[1,0]
	v_pk_mul_f32 v[24:25], v[4:5], v[48:49] op_sel_hi:[1,0]
	v_pk_mul_f32 v[22:23], v[10:11], v[48:49] op_sel_hi:[1,0]
	v_pk_mul_f32 v[20:21], v[8:9], v[48:49] op_sel_hi:[1,0]
	v_pk_mul_f32 v[18:19], v[14:15], v[48:49] op_sel_hi:[1,0]
	v_pk_mul_f32 v[16:17], v[12:13], v[48:49] op_sel_hi:[1,0]
	s_mov_b64 s[2:3], 0

.LBB0_1331:
	s_lshl_b32 s13, s4, 6
	s_lshl_b32 s4, 1, s4
	v_and_b32_e32 v0, s4, v172
	v_cmp_ne_u32_e32 vcc, 0, v0
	s_cmp_eq_u64 vcc, 0
	s_cselect_b64 s[2:3], -1, 0
	s_cmp_gt_i32 s13, s76
	s_cselect_b64 s[14:15], -1, 0
	s_or_b64 s[2:3], s[2:3], s[14:15]
	v_mov_b32_e32 v222, v196
	s_and_b64 vcc, exec, s[2:3]
	s_cbranch_vccnz .LBB0_1353
	v_cmp_eq_u32_e32 vcc, 0, v0
	s_or_b32 s14, s13, 63
	v_cmp_le_i32_e64 s[74:75], s14, v152
	v_cndmask_b32_e32 v227, 0, v211, vcc
	v_cmp_ge_u32_e64 s[2:3], s13, v227
	s_and_b64 s[2:3], s[2:3], s[74:75]
	v_and_b32_e32 v228, 63, v222
	v_cndmask_b32_e64 v0, 0, 1, s[2:3]
	v_cmp_ne_u32_e64 s[2:3], 0, v0
	v_and_b32_e32 v226, 15, v222
	v_and_b32_e32 v0, 48, v222
	v_or_b32_e32 v224, 48, v228
	s_mov_b64 s[74:75], -1
	s_cmp_lg_u64 s[2:3], exec
	v_add_u32_e32 v225, s96, v0
	v_mul_u32_u24_e32 v223, 0x90, v226
	v_mul_u32_u24_e32 v153, 0x90, v224
	s_cbranch_scc0 .LBB0_1346
	v_mad_u32_u24 v0, v226, s88, v225
	ds_read_b128 v[4:7], v0 offset:9216
	ds_read_b128 v[8:11], v0 offset:9280
	ds_read_b128 v[56:59], v0 offset:11520
	ds_read_b128 v[128:131], v0 offset:11584
	ds_read_b128 v[132:135], v0 offset:13824
	ds_read_b128 v[136:139], v0 offset:13888
	v_mad_u32_u24 v0, v224, s88, v225
	ds_read_b128 v[140:143], v0 offset:9216
	ds_read_b128 v[0:3], v0 offset:9280
	s_cmp_gt_i32 s14, s78
	s_mov_b64 s[2:3], -1
	s_cbranch_scc1 .LBB0_1339
	s_waitcnt lgkmcnt(7)
	v_mfma_f32_16x16x32_bf16 v[16:19], v[4:7], v[96:99], 0
	s_waitcnt lgkmcnt(5)
	v_mfma_f32_16x16x32_bf16 v[20:23], v[56:59], v[96:99], 0
	s_waitcnt lgkmcnt(3)
	v_mfma_f32_16x16x32_bf16 v[24:27], v[132:135], v[96:99], 0
	s_waitcnt lgkmcnt(1)
	v_mfma_f32_16x16x32_bf16 v[144:147], v[140:143], v[96:99], 0
	v_mfma_f32_16x16x32_bf16 v[16:19], v[8:11], v[100:103], v[16:19]
	v_mfma_f32_16x16x32_bf16 v[20:23], v[128:131], v[100:103], v[20:23]
	v_mfma_f32_16x16x32_bf16 v[24:27], v[136:139], v[100:103], v[24:27]
	s_waitcnt lgkmcnt(0)
	v_mfma_f32_16x16x32_bf16 v[144:147], v[0:3], v[100:103], v[144:147]
	s_nop 7
	s_nop 7
	s_nop 0
	v_max3_f32 v92, v158, v16, v17
	s_nop 0
	v_max3_f32 v92, v92, v18, v19
	s_nop 0
	v_max3_f32 v92, v92, v20, v21
	s_nop 0
	v_max3_f32 v92, v92, v22, v23
	s_nop 0
	v_max3_f32 v92, v92, v24, v25
	s_nop 0
	v_max3_f32 v92, v92, v26, v27
	s_nop 0
	v_max3_f32 v92, v92, v144, v145
	s_nop 0
	v_max3_f32 v92, v92, v146, v147
	s_nop 0
	v_cndmask_b32_e32 v92, v92, v158, vcc
	v_mov_b32_e32 v155, v92
	s_nop 1
	v_permlane16_swap_b32_e32 v155, v92
	s_waitcnt lgkmcnt(0)
	v_max3_f32 v92, v92, v155, v158
	v_mov_b32_e32 v155, v92
	s_nop 1
	v_permlane32_swap_b32_e32 v155, v92
	s_waitcnt lgkmcnt(0)
	v_max3_f32 v92, v92, v155, v158
	s_nop 0
	v_max3_f32 v155, v163, v92, v158
	s_nop 0
	v_cndmask_b32_e32 v92, v155, v212, vcc
	v_sub_f32_e32 v19, v19, v92
	v_sub_f32_e32 v18, v18, v92
	v_sub_f32_e32 v17, v17, v92
	v_sub_f32_e32 v16, v16, v92
	v_sub_f32_e32 v23, v23, v92
	v_sub_f32_e32 v22, v22, v92
	v_exp_f32_e32 v188, v16
	v_exp_f32_e32 v189, v17
	v_exp_f32_e32 v190, v18
	v_exp_f32_e32 v191, v19
	v_sub_f32_e32 v16, v21, v92
	v_sub_f32_e32 v17, v20, v92
	v_exp_f32_e32 v192, v17
	v_exp_f32_e32 v194, v22
	v_exp_f32_e32 v195, v23
	v_exp_f32_e32 v193, v16
	v_sub_f32_e32 v20, v27, v92
	v_sub_f32_e32 v21, v26, v92
	v_sub_f32_e32 v22, v25, v92
	v_sub_f32_e32 v23, v24, v92
	v_exp_f32_e32 v180, v23
	v_exp_f32_e32 v181, v22
	v_exp_f32_e32 v182, v21
	v_exp_f32_e32 v183, v20
	v_sub_f32_e32 v20, v147, v92
	v_sub_f32_e32 v21, v146, v92
	v_sub_f32_e32 v22, v145, v92
	v_sub_f32_e32 v23, v144, v92
	v_exp_f32_e32 v184, v23
	v_exp_f32_e32 v186, v21
	v_exp_f32_e32 v187, v20
	v_exp_f32_e32 v185, v22
	v_pk_add_f32 v[16:17], v[188:189], 0 op_sel_hi:[1,0]
	v_pk_add_f32 v[18:19], v[190:191], 0 op_sel_hi:[1,0]
	v_pk_add_f32 v[16:17], v[192:193], v[16:17]
	v_pk_add_f32 v[18:19], v[194:195], v[18:19]
	v_pk_add_f32 v[16:17], v[180:181], v[16:17]
	v_pk_add_f32 v[18:19], v[182:183], v[18:19]
	v_pk_add_f32 v[16:17], v[184:185], v[16:17]
	v_pk_add_f32 v[18:19], v[186:187], v[18:19]
	v_add_f32_e32 v16, v16, v17
	v_add_f32_e32 v17, v18, v19
	v_add_f32_e32 v16, v16, v17
	v_mov_b32_e32 v17, v16
	s_nop 1
	v_permlane16_swap_b32_e32 v17, v16
	v_sub_f32_e32 v18, v163, v155
	v_exp_f32_e32 v92, v18
	s_waitcnt lgkmcnt(0)
	v_add_f32_e32 v219, v16, v17
	v_mov_b32_e32 v229, v219
	s_nop 1
	v_permlane32_swap_b32_e32 v229, v219
	v_cmp_eq_f32_e32 vcc, 1.0, v92
	s_cmp_lg_u64 vcc, exec
	s_cbranch_scc0 .LBB0_1336
	v_pk_mul_f32 v[146:147], v[62:63], v[92:93] op_sel_hi:[1,0]
	v_pk_mul_f32 v[144:145], v[60:61], v[92:93] op_sel_hi:[1,0]
	v_pk_mul_f32 v[26:27], v[66:67], v[92:93] op_sel_hi:[1,0]
	v_pk_mul_f32 v[24:25], v[64:65], v[92:93] op_sel_hi:[1,0]
	v_pk_mul_f32 v[22:23], v[70:71], v[92:93] op_sel_hi:[1,0]
	v_pk_mul_f32 v[20:21], v[68:69], v[92:93] op_sel_hi:[1,0]
	v_pk_mul_f32 v[18:19], v[74:75], v[92:93] op_sel_hi:[1,0]
	v_pk_mul_f32 v[16:17], v[72:73], v[92:93] op_sel_hi:[1,0]
	s_mov_b64 s[2:3], 0

.LBB0_1339:
	s_and_b64 vcc, exec, s[2:3]
	s_cbranch_vccz .LBB0_1345
	s_waitcnt lgkmcnt(7)
	v_mfma_f32_16x16x32_bf16 v[4:7], v[4:7], v[96:99], 0
	v_lshrrev_b32_e32 v21, 4, v228
	v_lshl_or_b32 v20, v21, 2, s13
	v_cmp_ge_u32_e32 vcc, v20, v227
	s_waitcnt lgkmcnt(6)
	v_mfma_f32_16x16x32_bf16 v[4:7], v[8:11], v[100:103], v[4:7]
	v_cmp_le_i32_e64 s[2:3], v20, v152
	s_and_b64 vcc, vcc, s[2:3]
	v_cmp_lt_i32_e64 s[2:3], v20, v152
	s_waitcnt lgkmcnt(5)
	v_mfma_f32_16x16x32_bf16 v[8:11], v[56:59], v[96:99], 0
	s_waitcnt lgkmcnt(3)
	v_mfma_f32_16x16x32_bf16 v[16:19], v[132:135], v[96:99], 0
	s_waitcnt lgkmcnt(1)
	v_mfma_f32_16x16x32_bf16 v[22:25], v[140:143], v[96:99], 0
	v_mfma_f32_16x16x32_bf16 v[8:11], v[128:131], v[100:103], v[8:11]
	v_mfma_f32_16x16x32_bf16 v[16:19], v[136:139], v[100:103], v[16:19]
	s_waitcnt lgkmcnt(0)
	v_mfma_f32_16x16x32_bf16 v[0:3], v[0:3], v[100:103], v[22:25]
	s_nop 7
	s_nop 7
	s_nop 0
	v_cndmask_b32_e32 v4, v158, v4, vcc
	s_nop 1
	v_or_b32_e32 v22, 1, v20
	v_cmp_ge_u32_e32 vcc, v22, v227
	s_and_b64 vcc, s[2:3], vcc
	v_or_b32_e32 v23, 2, v20
	v_cndmask_b32_e32 v5, v158, v5, vcc
	v_cmp_ge_u32_e32 vcc, v23, v227
	v_cmp_le_i32_e64 s[2:3], v23, v152
	s_and_b64 vcc, vcc, s[2:3]
	v_or_b32_e32 v23, 3, v20
	v_cndmask_b32_e32 v6, v158, v6, vcc
	v_cmp_ge_u32_e32 vcc, v23, v227
	v_cmp_le_i32_e64 s[2:3], v23, v152
	s_and_b64 vcc, vcc, s[2:3]
	v_or_b32_e32 v23, 16, v20
	v_cndmask_b32_e32 v7, v158, v7, vcc
	v_cmp_ge_u32_e32 vcc, v23, v227
	v_cmp_le_i32_e64 s[2:3], v23, v152
	s_and_b64 vcc, vcc, s[2:3]
	v_or_b32_e32 v23, 17, v20
	v_cndmask_b32_e32 v8, v158, v8, vcc
	v_cmp_ge_u32_e32 vcc, v23, v227
	v_cmp_le_i32_e64 s[2:3], v23, v152
	s_and_b64 vcc, vcc, s[2:3]
	v_or_b32_e32 v23, 18, v20
	v_cndmask_b32_e32 v9, v158, v9, vcc
	v_cmp_ge_u32_e32 vcc, v23, v227
	v_cmp_le_i32_e64 s[2:3], v23, v152
	s_and_b64 vcc, vcc, s[2:3]
	v_or_b32_e32 v23, 19, v20
	v_cndmask_b32_e32 v10, v158, v10, vcc
	v_cmp_ge_u32_e32 vcc, v23, v227
	v_cmp_le_i32_e64 s[2:3], v23, v152
	s_and_b64 vcc, vcc, s[2:3]
	v_or_b32_e32 v23, 32, v20
	v_cndmask_b32_e32 v11, v158, v11, vcc
	v_cmp_ge_u32_e32 vcc, v23, v227
	v_cmp_le_i32_e64 s[2:3], v23, v152
	s_and_b64 vcc, vcc, s[2:3]
	v_or_b32_e32 v23, 33, v20
	v_cndmask_b32_e32 v16, v158, v16, vcc
	v_cmp_ge_u32_e32 vcc, v23, v227
	v_cmp_le_i32_e64 s[2:3], v23, v152
	s_and_b64 vcc, vcc, s[2:3]
	v_or_b32_e32 v23, 34, v20
	v_cndmask_b32_e32 v17, v158, v17, vcc
	v_cmp_ge_u32_e32 vcc, v23, v227
	v_cmp_le_i32_e64 s[2:3], v23, v152
	s_and_b64 vcc, vcc, s[2:3]
	v_or_b32_e32 v23, 35, v20
	v_cndmask_b32_e32 v18, v158, v18, vcc
	v_cmp_ge_u32_e32 vcc, v23, v227
	v_cmp_le_i32_e64 s[2:3], v23, v152
	s_and_b64 vcc, vcc, s[2:3]
	v_or_b32_e32 v23, 48, v20
	v_cndmask_b32_e32 v19, v158, v19, vcc
	v_cmp_ge_u32_e32 vcc, v23, v227
	v_cmp_le_i32_e64 s[2:3], v23, v152
	s_and_b64 vcc, vcc, s[2:3]
	v_or_b32_e32 v23, 49, v20
	v_max3_f32 v22, v4, s87, v5
	v_cndmask_b32_e32 v0, v158, v0, vcc
	v_cmp_ge_u32_e32 vcc, v23, v227
	v_cmp_le_i32_e64 s[2:3], v23, v152
	v_max3_f32 v22, v22, v6, v7
	s_and_b64 vcc, vcc, s[2:3]
	v_or_b32_e32 v23, 50, v20
	v_max3_f32 v22, v22, v8, v9
	v_cndmask_b32_e32 v1, v158, v1, vcc
	v_cmp_ge_u32_e32 vcc, v23, v227
	v_cmp_le_i32_e64 s[2:3], v23, v152
	v_max3_f32 v22, v22, v10, v11
	s_and_b64 vcc, vcc, s[2:3]
	v_or_b32_e32 v20, 51, v20
	v_max3_f32 v22, v22, v16, v17
	v_cndmask_b32_e32 v2, v158, v2, vcc
	v_cmp_ge_u32_e32 vcc, v20, v227
	v_cmp_le_i32_e64 s[2:3], v20, v152
	v_max3_f32 v22, v22, v18, v19
	s_and_b64 vcc, vcc, s[2:3]
	v_max3_f32 v22, v22, v0, v1
	v_cndmask_b32_e32 v3, v158, v3, vcc
	v_max3_f32 v20, v22, v2, v3
	v_mov_b32_e32 v22, v20
	s_nop 1
	v_permlane16_swap_b32_e32 v22, v20
	s_waitcnt lgkmcnt(0)
	v_max3_f32 v20, v20, v22, v158
	v_mov_b32_e32 v22, v20
	s_nop 1
	v_permlane32_swap_b32_e32 v22, v20
	s_waitcnt lgkmcnt(0)
	v_max3_f32 v20, v20, v22, v158
	v_cmp_lt_f32_e32 vcc, s86, v4
	v_max3_f32 v155, v163, v20, v158
	s_mov_b64 s[2:3], -1
	v_sub_f32_e32 v20, v4, v155
	v_exp_f32_e32 v20, v20
	v_sub_f32_e32 v22, v5, v155
	v_exp_f32_e32 v22, v22
	v_cndmask_b32_e32 v56, 0, v20, vcc
	v_cmp_lt_f32_e32 vcc, s86, v5
	v_sub_f32_e32 v5, v6, v155
	v_exp_f32_e32 v5, v5
	v_cndmask_b32_e32 v57, 0, v22, vcc
	v_sub_f32_e32 v20, v7, v155
	v_cmp_lt_f32_e32 vcc, s86, v6
	v_exp_f32_e32 v20, v20
	v_sub_f32_e32 v6, v9, v155
	v_cndmask_b32_e32 v92, 0, v5, vcc
	v_sub_f32_e32 v5, v8, v155
	v_exp_f32_e32 v5, v5
	v_cmp_lt_f32_e32 vcc, s86, v7
	v_exp_f32_e32 v6, v6
	v_add_f32_e32 v4, 0, v56
	v_cndmask_b32_e32 v128, 0, v20, vcc
	v_cmp_lt_f32_e32 vcc, s86, v8
	v_add_f32_e32 v4, v57, v4
	v_add_f32_e32 v4, v92, v4
	v_cndmask_b32_e32 v129, 0, v5, vcc
	v_sub_f32_e32 v5, v10, v155
	v_exp_f32_e32 v5, v5
	v_cmp_lt_f32_e32 vcc, s86, v9
	v_add_f32_e32 v4, v128, v4
	v_add_f32_e32 v4, v129, v4
	v_cndmask_b32_e32 v130, 0, v6, vcc
	v_sub_f32_e32 v6, v11, v155
	v_cmp_lt_f32_e32 vcc, s86, v10
	v_exp_f32_e32 v6, v6
	v_add_f32_e32 v4, v130, v4
	v_cndmask_b32_e32 v131, 0, v5, vcc
	v_sub_f32_e32 v5, v16, v155
	v_exp_f32_e32 v5, v5
	v_cmp_lt_f32_e32 vcc, s86, v11
	v_add_f32_e32 v4, v131, v4
	s_nop 0
	v_cndmask_b32_e32 v132, 0, v6, vcc
	v_sub_f32_e32 v6, v17, v155
	v_cmp_lt_f32_e32 vcc, s86, v16
	v_exp_f32_e32 v6, v6
	v_add_f32_e32 v4, v132, v4
	v_cndmask_b32_e32 v22, 0, v5, vcc
	v_sub_f32_e32 v5, v18, v155
	v_exp_f32_e32 v5, v5
	v_cmp_lt_f32_e32 vcc, s86, v17
	v_add_f32_e32 v4, v22, v4
	s_nop 0
	v_cndmask_b32_e32 v23, 0, v6, vcc
	v_sub_f32_e32 v6, v19, v155
	v_cmp_lt_f32_e32 vcc, s86, v18
	v_exp_f32_e32 v6, v6
	v_add_f32_e32 v4, v23, v4
	v_cndmask_b32_e32 v24, 0, v5, vcc
	v_sub_f32_e32 v5, v0, v155
	v_exp_f32_e32 v5, v5
	v_cmp_lt_f32_e32 vcc, s86, v19
	v_add_f32_e32 v4, v24, v4
	s_nop 0
	v_cndmask_b32_e32 v25, 0, v6, vcc
	v_sub_f32_e32 v6, v1, v155
	v_cmp_lt_f32_e32 vcc, s86, v0
	v_add_f32_e32 v4, v25, v4
	v_exp_f32_e32 v6, v6
	v_cndmask_b32_e32 v26, 0, v5, vcc
	v_cmp_lt_f32_e32 vcc, s86, v1
	v_sub_f32_e32 v1, v2, v155
	v_add_f32_e32 v0, v26, v4
	v_exp_f32_e32 v1, v1
	v_sub_f32_e32 v4, v3, v155
	v_exp_f32_e32 v4, v4
	v_cndmask_b32_e32 v27, 0, v6, vcc
	v_cmp_lt_f32_e32 vcc, s86, v2
	v_add_f32_e32 v0, v27, v0
	v_sub_f32_e32 v2, v163, v155
	v_cndmask_b32_e32 v58, 0, v1, vcc
	v_cmp_lt_f32_e32 vcc, s86, v3
	v_add_f32_e32 v0, v58, v0
	v_exp_f32_e32 v20, v2
	v_cndmask_b32_e32 v59, 0, v4, vcc
	v_add_f32_e32 v0, v59, v0
	v_mov_b32_e32 v1, v0
	s_nop 1
	v_permlane16_swap_b32_e32 v1, v0
	v_cmp_eq_f32_e32 vcc, 1.0, v20
	s_cmp_lg_u64 vcc, exec
	s_waitcnt lgkmcnt(0)
	v_add_f32_e32 v133, v0, v1
	v_mov_b32_e32 v134, v133
	s_nop 1
	v_permlane32_swap_b32_e32 v134, v133
	s_cbranch_scc0 .LBB0_1342
	v_pk_mul_f32 v[18:19], v[62:63], v[20:21] op_sel_hi:[1,0]
	v_pk_mul_f32 v[16:17], v[60:61], v[20:21] op_sel_hi:[1,0]
	v_pk_mul_f32 v[10:11], v[66:67], v[20:21] op_sel_hi:[1,0]
	v_pk_mul_f32 v[8:9], v[64:65], v[20:21] op_sel_hi:[1,0]
	v_pk_mul_f32 v[6:7], v[70:71], v[20:21] op_sel_hi:[1,0]
	v_pk_mul_f32 v[4:5], v[68:69], v[20:21] op_sel_hi:[1,0]
	v_pk_mul_f32 v[2:3], v[74:75], v[20:21] op_sel_hi:[1,0]
	v_pk_mul_f32 v[0:1], v[72:73], v[20:21] op_sel_hi:[1,0]
	s_mov_b64 s[2:3], 0

.LBB0_1346:
	s_andn2_b64 vcc, exec, s[74:75]
	s_cbranch_vccnz .LBB0_1352
	v_mad_u32_u24 v16, v226, s88, v225
	s_waitcnt lgkmcnt(0)
	ds_read_b128 v[0:3], v16 offset:9216
	ds_read_b128 v[8:11], v16 offset:9280
	ds_read_b128 v[4:7], v16 offset:11520
	v_mad_u32_u24 v20, v224, s88, v225
	s_mov_b64 s[2:3], -1
	s_waitcnt lgkmcnt(2)
	v_mfma_f32_16x16x32_bf16 v[0:3], v[0:3], v[96:99], 0
	s_waitcnt lgkmcnt(1)
	v_mfma_f32_16x16x32_bf16 v[0:3], v[8:11], v[100:103], v[0:3]
	ds_read_b128 v[8:11], v16 offset:11584
	s_waitcnt lgkmcnt(1)
	v_mfma_f32_16x16x32_bf16 v[4:7], v[4:7], v[96:99], 0
	s_waitcnt lgkmcnt(0)
	v_mfma_f32_16x16x32_bf16 v[4:7], v[8:11], v[100:103], v[4:7]
	ds_read_b128 v[8:11], v16 offset:13824
	ds_read_b128 v[16:19], v16 offset:13888
	s_waitcnt lgkmcnt(1)
	v_mfma_f32_16x16x32_bf16 v[8:11], v[8:11], v[96:99], 0
	s_waitcnt lgkmcnt(0)
	v_mfma_f32_16x16x32_bf16 v[8:11], v[16:19], v[100:103], v[8:11]
	ds_read_b128 v[16:19], v20 offset:9216
	ds_read_b128 v[20:23], v20 offset:9280
	s_waitcnt lgkmcnt(1)
	v_mfma_f32_16x16x32_bf16 v[16:19], v[16:19], v[96:99], 0
	s_waitcnt lgkmcnt(0)
	v_mfma_f32_16x16x32_bf16 v[16:19], v[20:23], v[100:103], v[16:19]
	s_nop 7
	s_nop 7
	s_nop 0
	v_max3_f32 v20, v158, v0, v1
	s_nop 0
	v_max3_f32 v20, v20, v2, v3
	s_nop 0
	v_max3_f32 v20, v20, v4, v5
	s_nop 0
	v_max3_f32 v20, v20, v6, v7
	s_nop 0
	v_max3_f32 v20, v20, v8, v9
	s_nop 0
	v_max3_f32 v20, v20, v10, v11
	s_nop 0
	v_max3_f32 v20, v20, v16, v17
	s_nop 0
	v_max3_f32 v20, v20, v18, v19
	v_mov_b32_e32 v21, v20
	s_nop 1
	v_permlane16_swap_b32_e32 v21, v20
	s_waitcnt lgkmcnt(0)
	v_max3_f32 v20, v20, v21, v158
	v_mov_b32_e32 v21, v20
	s_nop 1
	v_permlane32_swap_b32_e32 v21, v20
	s_waitcnt lgkmcnt(0)
	v_max3_f32 v20, v20, v21, v158
	s_nop 0
	v_max3_f32 v155, v163, v20, v158
	s_nop 0
	v_sub_f32_e32 v3, v3, v155
	v_sub_f32_e32 v2, v2, v155
	v_sub_f32_e32 v1, v1, v155
	v_sub_f32_e32 v0, v0, v155
	v_sub_f32_e32 v7, v7, v155
	v_sub_f32_e32 v6, v6, v155
	v_exp_f32_e32 v56, v0
	v_exp_f32_e32 v57, v1
	v_exp_f32_e32 v58, v2
	v_exp_f32_e32 v59, v3
	v_sub_f32_e32 v0, v5, v155
	v_sub_f32_e32 v1, v4, v155
	v_exp_f32_e32 v128, v1
	v_exp_f32_e32 v130, v6
	v_exp_f32_e32 v131, v7
	v_exp_f32_e32 v129, v0
	v_sub_f32_e32 v4, v11, v155
	v_sub_f32_e32 v5, v10, v155
	v_sub_f32_e32 v6, v9, v155
	v_sub_f32_e32 v7, v8, v155
	v_exp_f32_e32 v20, v7
	v_exp_f32_e32 v21, v6
	v_exp_f32_e32 v22, v5
	v_exp_f32_e32 v23, v4
	v_sub_f32_e32 v4, v19, v155
	v_sub_f32_e32 v5, v18, v155
	v_sub_f32_e32 v6, v17, v155
	v_sub_f32_e32 v7, v16, v155
	v_exp_f32_e32 v24, v7
	v_exp_f32_e32 v26, v5
	v_exp_f32_e32 v27, v4
	v_exp_f32_e32 v25, v6
	v_pk_add_f32 v[0:1], v[56:57], 0 op_sel_hi:[1,0]
	v_pk_add_f32 v[2:3], v[58:59], 0 op_sel_hi:[1,0]
	v_pk_add_f32 v[0:1], v[128:129], v[0:1]
	v_pk_add_f32 v[2:3], v[130:131], v[2:3]
	v_pk_add_f32 v[0:1], v[20:21], v[0:1]
	v_pk_add_f32 v[2:3], v[22:23], v[2:3]
	v_pk_add_f32 v[0:1], v[24:25], v[0:1]
	v_pk_add_f32 v[2:3], v[26:27], v[2:3]
	v_add_f32_e32 v0, v0, v1
	v_add_f32_e32 v1, v2, v3
	v_add_f32_e32 v0, v0, v1
	v_mov_b32_e32 v1, v0
	s_nop 1
	v_permlane16_swap_b32_e32 v1, v0
	v_sub_f32_e32 v2, v163, v155
	v_exp_f32_e32 v92, v2
	s_waitcnt lgkmcnt(0)
	v_add_f32_e32 v132, v0, v1
	v_mov_b32_e32 v133, v132
	s_nop 1
	v_permlane32_swap_b32_e32 v133, v132
	v_cmp_eq_f32_e32 vcc, 1.0, v92
	s_cmp_lg_u64 vcc, exec
	s_cbranch_scc0 .LBB0_1349
	v_pk_mul_f32 v[18:19], v[62:63], v[92:93] op_sel_hi:[1,0]
	v_pk_mul_f32 v[16:17], v[60:61], v[92:93] op_sel_hi:[1,0]
	v_pk_mul_f32 v[10:11], v[66:67], v[92:93] op_sel_hi:[1,0]
	v_pk_mul_f32 v[8:9], v[64:65], v[92:93] op_sel_hi:[1,0]
	v_pk_mul_f32 v[6:7], v[70:71], v[92:93] op_sel_hi:[1,0]
	v_pk_mul_f32 v[4:5], v[68:69], v[92:93] op_sel_hi:[1,0]
	v_pk_mul_f32 v[2:3], v[74:75], v[92:93] op_sel_hi:[1,0]
	v_pk_mul_f32 v[0:1], v[72:73], v[92:93] op_sel_hi:[1,0]
	s_mov_b64 s[2:3], 0

.LBB0_1354:
	s_waitcnt lgkmcnt(0)
	v_and_b32_e32 v0, s4, v173
	v_cmp_ne_u32_e32 vcc, 0, v0
	s_cmp_eq_u64 vcc, 0
	s_cselect_b64 s[2:3], -1, 0
	s_cmp_gt_i32 s13, s77
	s_cselect_b64 s[14:15], -1, 0
	s_or_b64 s[2:3], s[2:3], s[14:15]
	v_mov_b32_e32 v181, v196
	s_and_b64 vcc, exec, s[2:3]
	s_cbranch_vccnz .LBB0_1376
	v_cmp_eq_u32_e32 vcc, 0, v0
	s_or_b32 s4, s13, 63
	v_cmp_le_i32_e64 s[74:75], s4, v154
	v_cndmask_b32_e32 v186, 0, v211, vcc
	v_cmp_ge_u32_e64 s[2:3], s13, v186
	s_and_b64 s[2:3], s[2:3], s[74:75]
	v_and_b32_e32 v187, 63, v181
	v_cndmask_b32_e64 v0, 0, 1, s[2:3]
	v_cmp_ne_u32_e64 s[2:3], 0, v0
	v_and_b32_e32 v185, 15, v181
	v_and_b32_e32 v0, 48, v181
	v_or_b32_e32 v183, 48, v187
	s_mov_b64 s[74:75], -1
	s_cmp_lg_u64 s[2:3], exec
	v_add_u32_e32 v184, s96, v0
	v_mul_u32_u24_e32 v182, 0x90, v185
	v_mul_u32_u24_e32 v163, 0x90, v183
	s_cbranch_scc0 .LBB0_1369
	v_mad_u32_u24 v0, v185, s88, v184
	ds_read_b128 v[36:39], v0 offset:9216
	ds_read_b128 v[40:43], v0 offset:9280
	ds_read_b128 v[56:59], v0 offset:11520
	ds_read_b128 v[60:63], v0 offset:11584
	ds_read_b128 v[64:67], v0 offset:13824
	ds_read_b128 v[68:71], v0 offset:13888
	v_mad_u32_u24 v0, v183, s88, v184
	ds_read_b128 v[72:75], v0 offset:9216
	ds_read_b128 v[32:35], v0 offset:9280
	s_cmp_gt_i32 s4, s93
	s_mov_b64 s[2:3], -1
	s_cbranch_scc1 .LBB0_1362
	s_waitcnt lgkmcnt(7)
	v_mfma_f32_16x16x32_bf16 v[0:3], v[36:39], v[104:107], 0
	s_waitcnt lgkmcnt(5)
	v_mfma_f32_16x16x32_bf16 v[4:7], v[56:59], v[104:107], 0
	s_waitcnt lgkmcnt(3)
	v_mfma_f32_16x16x32_bf16 v[8:11], v[64:67], v[104:107], 0
	s_waitcnt lgkmcnt(1)
	v_mfma_f32_16x16x32_bf16 v[128:131], v[72:75], v[104:107], 0
	v_mfma_f32_16x16x32_bf16 v[0:3], v[40:43], v[108:111], v[0:3]
	v_mfma_f32_16x16x32_bf16 v[4:7], v[60:63], v[108:111], v[4:7]
	v_mfma_f32_16x16x32_bf16 v[8:11], v[68:71], v[108:111], v[8:11]
	s_waitcnt lgkmcnt(0)
	v_mfma_f32_16x16x32_bf16 v[128:131], v[32:35], v[108:111], v[128:131]
	s_nop 7
	s_nop 7
	s_nop 0
	v_max3_f32 v92, v158, v0, v1
	s_nop 0
	v_max3_f32 v92, v92, v2, v3
	s_nop 0
	v_max3_f32 v92, v92, v4, v5
	s_nop 0
	v_max3_f32 v92, v92, v6, v7
	s_nop 0
	v_max3_f32 v92, v92, v8, v9
	s_nop 0
	v_max3_f32 v92, v92, v10, v11
	s_nop 0
	v_max3_f32 v92, v92, v128, v129
	s_nop 0
	v_max3_f32 v92, v92, v130, v131
	s_nop 0
	v_cndmask_b32_e32 v92, v92, v158, vcc
	v_mov_b32_e32 v132, v92
	s_nop 1
	v_permlane16_swap_b32_e32 v132, v92
	s_waitcnt lgkmcnt(0)
	v_max3_f32 v92, v92, v132, v158
	v_mov_b32_e32 v132, v92
	s_nop 1
	v_permlane32_swap_b32_e32 v132, v92
	s_waitcnt lgkmcnt(0)
	v_max3_f32 v92, v92, v132, v158
	s_nop 0
	v_max3_f32 v153, v175, v92, v158
	s_nop 0
	v_cndmask_b32_e32 v92, v153, v212, vcc
	v_sub_f32_e32 v3, v3, v92
	v_sub_f32_e32 v2, v2, v92
	v_sub_f32_e32 v1, v1, v92
	v_sub_f32_e32 v0, v0, v92
	v_sub_f32_e32 v7, v7, v92
	v_sub_f32_e32 v6, v6, v92
	v_exp_f32_e32 v140, v0
	v_exp_f32_e32 v141, v1
	v_exp_f32_e32 v142, v2
	v_exp_f32_e32 v143, v3
	v_sub_f32_e32 v0, v5, v92
	v_sub_f32_e32 v1, v4, v92
	v_exp_f32_e32 v144, v1
	v_exp_f32_e32 v146, v6
	v_exp_f32_e32 v147, v7
	v_exp_f32_e32 v145, v0
	v_sub_f32_e32 v4, v11, v92
	v_sub_f32_e32 v5, v10, v92
	v_sub_f32_e32 v6, v9, v92
	v_sub_f32_e32 v7, v8, v92
	v_exp_f32_e32 v132, v7
	v_exp_f32_e32 v133, v6
	v_exp_f32_e32 v134, v5
	v_exp_f32_e32 v135, v4
	v_sub_f32_e32 v4, v131, v92
	v_sub_f32_e32 v5, v130, v92
	v_sub_f32_e32 v6, v129, v92
	v_sub_f32_e32 v7, v128, v92
	v_exp_f32_e32 v136, v7
	v_exp_f32_e32 v138, v5
	v_exp_f32_e32 v139, v4
	v_exp_f32_e32 v137, v6
	v_pk_add_f32 v[0:1], v[140:141], 0 op_sel_hi:[1,0]
	v_pk_add_f32 v[2:3], v[142:143], 0 op_sel_hi:[1,0]
	v_pk_add_f32 v[0:1], v[144:145], v[0:1]
	v_pk_add_f32 v[2:3], v[146:147], v[2:3]
	v_pk_add_f32 v[0:1], v[132:133], v[0:1]
	v_pk_add_f32 v[2:3], v[134:135], v[2:3]
	v_pk_add_f32 v[0:1], v[136:137], v[0:1]
	v_pk_add_f32 v[2:3], v[138:139], v[2:3]
	v_add_f32_e32 v0, v0, v1
	v_add_f32_e32 v1, v2, v3
	v_add_f32_e32 v0, v0, v1
	v_mov_b32_e32 v1, v0
	s_nop 1
	v_permlane16_swap_b32_e32 v1, v0
	v_sub_f32_e32 v2, v175, v153
	v_exp_f32_e32 v92, v2
	s_waitcnt lgkmcnt(0)
	v_add_f32_e32 v180, v0, v1
	v_mov_b32_e32 v188, v180
	s_nop 1
	v_permlane32_swap_b32_e32 v188, v180
	v_cmp_eq_f32_e32 vcc, 1.0, v92
	s_cmp_lg_u64 vcc, exec
	s_cbranch_scc0 .LBB0_1359
	v_pk_mul_f32 v[130:131], v[78:79], v[92:93] op_sel_hi:[1,0]
	v_pk_mul_f32 v[128:129], v[76:77], v[92:93] op_sel_hi:[1,0]
	v_pk_mul_f32 v[10:11], v[82:83], v[92:93] op_sel_hi:[1,0]
	v_pk_mul_f32 v[8:9], v[80:81], v[92:93] op_sel_hi:[1,0]
	v_pk_mul_f32 v[6:7], v[86:87], v[92:93] op_sel_hi:[1,0]
	v_pk_mul_f32 v[4:5], v[84:85], v[92:93] op_sel_hi:[1,0]
	v_pk_mul_f32 v[2:3], v[90:91], v[92:93] op_sel_hi:[1,0]
	v_pk_mul_f32 v[0:1], v[88:89], v[92:93] op_sel_hi:[1,0]
	s_mov_b64 s[2:3], 0

.LBB0_1362:
	s_and_b64 vcc, exec, s[2:3]
	s_cbranch_vccz .LBB0_1368
	s_waitcnt lgkmcnt(7)
	v_mfma_f32_16x16x32_bf16 v[0:3], v[36:39], v[104:107], 0
	v_lshrrev_b32_e32 v37, 4, v187
	v_lshl_or_b32 v36, v37, 2, s13
	v_cmp_ge_u32_e32 vcc, v36, v186
	s_waitcnt lgkmcnt(6)
	v_mfma_f32_16x16x32_bf16 v[0:3], v[40:43], v[108:111], v[0:3]
	v_cmp_le_i32_e64 s[2:3], v36, v154
	s_and_b64 vcc, vcc, s[2:3]
	v_cmp_lt_i32_e64 s[2:3], v36, v154
	s_waitcnt lgkmcnt(5)
	v_mfma_f32_16x16x32_bf16 v[4:7], v[56:59], v[104:107], 0
	s_waitcnt lgkmcnt(3)
	v_mfma_f32_16x16x32_bf16 v[8:11], v[64:67], v[104:107], 0
	s_waitcnt lgkmcnt(1)
	v_mfma_f32_16x16x32_bf16 v[38:41], v[72:75], v[104:107], 0
	v_mfma_f32_16x16x32_bf16 v[4:7], v[60:63], v[108:111], v[4:7]
	v_mfma_f32_16x16x32_bf16 v[8:11], v[68:71], v[108:111], v[8:11]
	s_waitcnt lgkmcnt(0)
	v_mfma_f32_16x16x32_bf16 v[32:35], v[32:35], v[108:111], v[38:41]
	s_nop 7
	s_nop 7
	s_nop 0
	v_cndmask_b32_e32 v0, v158, v0, vcc
	s_nop 1
	v_or_b32_e32 v38, 1, v36
	v_cmp_ge_u32_e32 vcc, v38, v186
	s_and_b64 vcc, s[2:3], vcc
	v_or_b32_e32 v39, 2, v36
	v_cndmask_b32_e32 v1, v158, v1, vcc
	v_cmp_ge_u32_e32 vcc, v39, v186
	v_cmp_le_i32_e64 s[2:3], v36, v152
	s_and_b64 vcc, s[2:3], vcc
	v_or_b32_e32 v39, 3, v36
	v_cndmask_b32_e32 v2, v158, v2, vcc
	v_cmp_ge_u32_e32 vcc, v39, v186
	v_cmp_le_i32_e64 s[2:3], v39, v154
	s_and_b64 vcc, vcc, s[2:3]
	v_or_b32_e32 v39, 16, v36
	v_cndmask_b32_e32 v3, v158, v3, vcc
	v_cmp_ge_u32_e32 vcc, v39, v186
	v_cmp_le_i32_e64 s[2:3], v39, v154
	s_and_b64 vcc, vcc, s[2:3]
	v_or_b32_e32 v39, 17, v36
	v_cndmask_b32_e32 v4, v158, v4, vcc
	v_cmp_ge_u32_e32 vcc, v39, v186
	v_cmp_le_i32_e64 s[2:3], v39, v154
	s_and_b64 vcc, vcc, s[2:3]
	v_or_b32_e32 v39, 18, v36
	v_cndmask_b32_e32 v5, v158, v5, vcc
	v_cmp_ge_u32_e32 vcc, v39, v186
	v_cmp_le_i32_e64 s[2:3], v39, v154
	s_and_b64 vcc, vcc, s[2:3]
	v_or_b32_e32 v39, 19, v36
	v_cndmask_b32_e32 v6, v158, v6, vcc
	v_cmp_ge_u32_e32 vcc, v39, v186
	v_cmp_le_i32_e64 s[2:3], v39, v154
	s_and_b64 vcc, vcc, s[2:3]
	v_or_b32_e32 v39, 32, v36
	v_cndmask_b32_e32 v7, v158, v7, vcc
	v_cmp_ge_u32_e32 vcc, v39, v186
	v_cmp_le_i32_e64 s[2:3], v39, v154
	s_and_b64 vcc, vcc, s[2:3]
	v_or_b32_e32 v39, 33, v36
	v_cndmask_b32_e32 v8, v158, v8, vcc
	v_cmp_ge_u32_e32 vcc, v39, v186
	v_cmp_le_i32_e64 s[2:3], v39, v154
	s_and_b64 vcc, vcc, s[2:3]
	v_or_b32_e32 v39, 34, v36
	v_cndmask_b32_e32 v9, v158, v9, vcc
	v_cmp_ge_u32_e32 vcc, v39, v186
	v_cmp_le_i32_e64 s[2:3], v39, v154
	s_and_b64 vcc, vcc, s[2:3]
	v_or_b32_e32 v39, 35, v36
	v_cndmask_b32_e32 v10, v158, v10, vcc
	v_cmp_ge_u32_e32 vcc, v39, v186
	v_cmp_le_i32_e64 s[2:3], v39, v154
	s_and_b64 vcc, vcc, s[2:3]
	v_or_b32_e32 v39, 48, v36
	v_cndmask_b32_e32 v11, v158, v11, vcc
	v_cmp_ge_u32_e32 vcc, v39, v186
	v_cmp_le_i32_e64 s[2:3], v39, v154
	s_and_b64 vcc, vcc, s[2:3]
	v_or_b32_e32 v39, 49, v36
	v_max3_f32 v38, v0, s87, v1
	v_cndmask_b32_e32 v32, v158, v32, vcc
	v_cmp_ge_u32_e32 vcc, v39, v186
	v_cmp_le_i32_e64 s[2:3], v39, v154
	v_max3_f32 v38, v38, v2, v3
	s_and_b64 vcc, vcc, s[2:3]
	v_or_b32_e32 v39, 50, v36
	v_max3_f32 v38, v38, v4, v5
	v_cndmask_b32_e32 v33, v158, v33, vcc
	v_cmp_ge_u32_e32 vcc, v39, v186
	v_cmp_le_i32_e64 s[2:3], v39, v154
	v_max3_f32 v38, v38, v6, v7
	s_and_b64 vcc, vcc, s[2:3]
	v_or_b32_e32 v36, 51, v36
	v_max3_f32 v38, v38, v8, v9
	v_cndmask_b32_e32 v34, v158, v34, vcc
	v_cmp_ge_u32_e32 vcc, v36, v186
	v_cmp_le_i32_e64 s[2:3], v36, v154
	v_max3_f32 v38, v38, v10, v11
	s_and_b64 vcc, vcc, s[2:3]
	v_max3_f32 v38, v38, v32, v33
	v_cndmask_b32_e32 v35, v158, v35, vcc
	v_max3_f32 v36, v38, v34, v35
	v_mov_b32_e32 v38, v36
	s_nop 1
	v_permlane16_swap_b32_e32 v38, v36
	s_waitcnt lgkmcnt(0)
	v_max3_f32 v36, v36, v38, v158
	v_mov_b32_e32 v38, v36
	s_nop 1
	v_permlane32_swap_b32_e32 v38, v36
	s_waitcnt lgkmcnt(0)
	v_max3_f32 v36, v36, v38, v158
	v_cmp_lt_f32_e32 vcc, s86, v0
	v_max3_f32 v153, v175, v36, v158
	s_mov_b64 s[2:3], -1
	v_sub_f32_e32 v36, v0, v153
	v_exp_f32_e32 v36, v36
	v_sub_f32_e32 v38, v1, v153
	v_exp_f32_e32 v38, v38
	v_cndmask_b32_e32 v56, 0, v36, vcc
	v_cmp_lt_f32_e32 vcc, s86, v1
	v_sub_f32_e32 v1, v2, v153
	v_exp_f32_e32 v1, v1
	v_cndmask_b32_e32 v57, 0, v38, vcc
	v_sub_f32_e32 v36, v3, v153
	v_cmp_lt_f32_e32 vcc, s86, v2
	v_exp_f32_e32 v36, v36
	v_sub_f32_e32 v2, v5, v153
	v_cndmask_b32_e32 v60, 0, v1, vcc
	v_sub_f32_e32 v1, v4, v153
	v_exp_f32_e32 v1, v1
	v_exp_f32_e32 v2, v2
	v_cmp_lt_f32_e32 vcc, s86, v3
	v_add_f32_e32 v0, 0, v56
	v_add_f32_e32 v0, v57, v0
	v_cndmask_b32_e32 v61, 0, v36, vcc
	v_cmp_lt_f32_e32 vcc, s86, v4
	v_add_f32_e32 v0, v60, v0
	v_add_f32_e32 v0, v61, v0
	v_cndmask_b32_e32 v62, 0, v1, vcc
	v_cmp_lt_f32_e32 vcc, s86, v5
	v_sub_f32_e32 v1, v6, v153
	v_exp_f32_e32 v1, v1
	v_cndmask_b32_e32 v63, 0, v2, vcc
	v_sub_f32_e32 v2, v7, v153
	v_exp_f32_e32 v2, v2
	v_cmp_lt_f32_e32 vcc, s86, v6
	v_add_f32_e32 v0, v62, v0
	v_add_f32_e32 v0, v63, v0
	v_cndmask_b32_e32 v64, 0, v1, vcc
	v_cmp_lt_f32_e32 vcc, s86, v7
	v_sub_f32_e32 v1, v8, v153
	v_exp_f32_e32 v1, v1
	v_cndmask_b32_e32 v65, 0, v2, vcc
	v_sub_f32_e32 v2, v9, v153
	v_exp_f32_e32 v2, v2
	v_cmp_lt_f32_e32 vcc, s86, v8
	v_add_f32_e32 v0, v64, v0
	v_add_f32_e32 v0, v65, v0
	v_cndmask_b32_e32 v38, 0, v1, vcc
	v_cmp_lt_f32_e32 vcc, s86, v9
	v_sub_f32_e32 v1, v10, v153
	v_exp_f32_e32 v1, v1
	v_cndmask_b32_e32 v39, 0, v2, vcc
	v_sub_f32_e32 v2, v11, v153
	v_exp_f32_e32 v2, v2
	v_cmp_lt_f32_e32 vcc, s86, v10
	v_add_f32_e32 v0, v38, v0
	v_add_f32_e32 v0, v39, v0
	v_cndmask_b32_e32 v40, 0, v1, vcc
	v_cmp_lt_f32_e32 vcc, s86, v11
	v_sub_f32_e32 v1, v32, v153
	v_exp_f32_e32 v1, v1
	v_cndmask_b32_e32 v41, 0, v2, vcc
	v_sub_f32_e32 v2, v33, v153
	v_exp_f32_e32 v2, v2
	v_cmp_lt_f32_e32 vcc, s86, v32
	v_add_f32_e32 v0, v40, v0
	v_add_f32_e32 v0, v41, v0
	v_cndmask_b32_e32 v42, 0, v1, vcc
	v_cmp_lt_f32_e32 vcc, s86, v33
	v_sub_f32_e32 v1, v34, v153
	v_exp_f32_e32 v1, v1
	v_cndmask_b32_e32 v43, 0, v2, vcc
	v_sub_f32_e32 v2, v35, v153
	v_exp_f32_e32 v2, v2
	v_add_f32_e32 v0, v42, v0
	v_cmp_lt_f32_e32 vcc, s86, v34
	v_add_f32_e32 v0, v43, v0
	s_nop 0
	v_cndmask_b32_e32 v58, 0, v1, vcc
	v_cmp_lt_f32_e32 vcc, s86, v35
	v_add_f32_e32 v0, v58, v0
	s_nop 0
	v_cndmask_b32_e32 v59, 0, v2, vcc
	v_add_f32_e32 v0, v59, v0
	v_mov_b32_e32 v1, v0
	s_nop 1
	v_permlane16_swap_b32_e32 v1, v0
	v_sub_f32_e32 v2, v175, v153
	v_exp_f32_e32 v36, v2
	s_waitcnt lgkmcnt(0)
	v_add_f32_e32 v66, v0, v1
	v_mov_b32_e32 v67, v66
	s_nop 1
	v_permlane32_swap_b32_e32 v67, v66
	v_cmp_eq_f32_e32 vcc, 1.0, v36
	s_cmp_lg_u64 vcc, exec
	s_cbranch_scc0 .LBB0_1365
	v_pk_mul_f32 v[34:35], v[78:79], v[36:37] op_sel_hi:[1,0]
	v_pk_mul_f32 v[32:33], v[76:77], v[36:37] op_sel_hi:[1,0]
	v_pk_mul_f32 v[10:11], v[82:83], v[36:37] op_sel_hi:[1,0]
	v_pk_mul_f32 v[8:9], v[80:81], v[36:37] op_sel_hi:[1,0]
	v_pk_mul_f32 v[6:7], v[86:87], v[36:37] op_sel_hi:[1,0]
	v_pk_mul_f32 v[4:5], v[84:85], v[36:37] op_sel_hi:[1,0]
	v_pk_mul_f32 v[2:3], v[90:91], v[36:37] op_sel_hi:[1,0]
	v_pk_mul_f32 v[0:1], v[88:89], v[36:37] op_sel_hi:[1,0]
	s_mov_b64 s[2:3], 0

.LBB0_1395:
	s_mul_i32 s2, s1, 0x4800
	s_lshl_b32 s14, s14, 6
	s_add_i32 s13, s2, 0
	s_or_b32 s15, s14, 63
	s_cmp_lt_i32 s15, s0
	s_cselect_b64 s[2:3], -1, 0
	s_cmp_gt_i32 s14, s76
	s_cselect_b64 s[92:93], -1, 0
	s_or_b64 s[2:3], s[92:93], s[2:3]
	v_mov_b32_e32 v136, v196
	s_and_b64 vcc, exec, s[2:3]
	s_cbranch_vccnz .LBB0_1405
	v_cmp_ge_i32_e32 vcc, s14, v130
	v_cmp_le_i32_e64 s[2:3], s15, v152
	s_and_b64 s[2:3], vcc, s[2:3]
	v_and_b32_e32 v80, 15, v136
	v_cndmask_b32_e64 v48, 0, 1, s[2:3]
	v_cmp_ne_u32_e32 vcc, 0, v48
	v_and_b32_e32 v48, 48, v136
	v_add_u32_e32 v72, s13, v48
	v_mad_u32_u24 v68, v80, s88, v72
	ds_read_b128 v[48:51], v68
	ds_read_b128 v[52:55], v68 offset:64
	ds_read_b128 v[56:59], v68 offset:2304
	ds_read_b128 v[60:63], v68 offset:2368
	ds_read_b128 v[64:67], v68 offset:4608
	ds_read_b128 v[68:71], v68 offset:4672
	v_and_b32_e32 v92, 63, v136
	v_or_b32_e32 v81, 48, v92
	v_mad_u32_u24 v76, v81, s88, v72
	ds_read_b128 v[72:75], v76
	ds_read_b128 v[76:79], v76 offset:64
	s_cmp_lg_u64 vcc, exec
	v_mul_u32_u24_e32 v137, 0x90, v80
	v_mul_u32_u24_e32 v134, 0x90, v81
	s_mov_b64 s[2:3], -1
	s_cbranch_scc0 .LBB0_1400
	s_waitcnt lgkmcnt(7)
	v_mfma_f32_16x16x32_bf16 v[80:83], v[48:51], v[96:99], 0
	v_lshrrev_b32_e32 v139, 4, v92
	v_lshl_or_b32 v92, v139, 2, s14
	v_cmp_ge_i32_e32 vcc, v92, v130
	s_waitcnt lgkmcnt(5)
	v_mfma_f32_16x16x32_bf16 v[84:87], v[56:59], v[96:99], 0
	v_cmp_le_i32_e64 s[2:3], v92, v152
	s_and_b64 vcc, vcc, s[2:3]
	v_or_b32_e32 v135, 1, v92
	s_waitcnt lgkmcnt(3)
	v_mfma_f32_16x16x32_bf16 v[88:91], v[64:67], v[96:99], 0
	v_cmp_lt_i32_e64 s[2:3], v92, v152
	v_or_b32_e32 v138, 2, v92
	s_waitcnt lgkmcnt(1)
	v_mfma_f32_16x16x32_bf16 v[112:115], v[72:75], v[96:99], 0
	v_mfma_f32_16x16x32_bf16 v[80:83], v[52:55], v[100:103], v[80:83]
	v_mfma_f32_16x16x32_bf16 v[84:87], v[60:63], v[100:103], v[84:87]
	v_mfma_f32_16x16x32_bf16 v[88:91], v[68:71], v[100:103], v[88:91]
	s_waitcnt lgkmcnt(0)
	v_mfma_f32_16x16x32_bf16 v[112:115], v[76:79], v[100:103], v[112:115]
	s_nop 7
	s_nop 7
	s_nop 3
	v_cndmask_b32_e32 v80, v158, v80, vcc
	v_cmp_ge_i32_e32 vcc, v135, v130
	s_and_b64 vcc, s[2:3], vcc
	v_cmp_le_i32_e64 s[2:3], v138, v152
	v_cndmask_b32_e32 v81, v158, v81, vcc
	v_cmp_ge_i32_e32 vcc, v138, v130
	s_and_b64 vcc, vcc, s[2:3]
	v_or_b32_e32 v138, 3, v92
	v_cndmask_b32_e32 v82, v158, v82, vcc
	v_cmp_ge_i32_e32 vcc, v138, v130
	v_cmp_le_i32_e64 s[2:3], v138, v152
	s_and_b64 vcc, vcc, s[2:3]
	v_or_b32_e32 v138, 16, v92
	v_cndmask_b32_e32 v83, v158, v83, vcc
	v_cmp_ge_i32_e32 vcc, v138, v130
	v_cmp_le_i32_e64 s[2:3], v138, v152
	s_and_b64 vcc, vcc, s[2:3]
	v_or_b32_e32 v138, 17, v92
	v_cndmask_b32_e32 v84, v158, v84, vcc
	v_cmp_ge_i32_e32 vcc, v138, v130
	v_cmp_le_i32_e64 s[2:3], v138, v152
	s_and_b64 vcc, vcc, s[2:3]
	v_or_b32_e32 v138, 18, v92
	v_cndmask_b32_e32 v85, v158, v85, vcc
	v_cmp_ge_i32_e32 vcc, v138, v130
	v_cmp_le_i32_e64 s[2:3], v138, v152
	s_and_b64 vcc, vcc, s[2:3]
	v_or_b32_e32 v138, 19, v92
	v_cndmask_b32_e32 v86, v158, v86, vcc
	v_cmp_ge_i32_e32 vcc, v138, v130
	v_cmp_le_i32_e64 s[2:3], v138, v152
	s_and_b64 vcc, vcc, s[2:3]
	v_or_b32_e32 v138, 32, v92
	v_cndmask_b32_e32 v87, v158, v87, vcc
	v_cmp_ge_i32_e32 vcc, v138, v130
	v_cmp_le_i32_e64 s[2:3], v138, v152
	s_and_b64 vcc, vcc, s[2:3]
	v_or_b32_e32 v138, 33, v92
	v_cndmask_b32_e32 v88, v158, v88, vcc
	v_cmp_ge_i32_e32 vcc, v138, v130
	v_cmp_le_i32_e64 s[2:3], v138, v152
	s_and_b64 vcc, vcc, s[2:3]
	v_or_b32_e32 v138, 34, v92
	v_cndmask_b32_e32 v89, v158, v89, vcc
	v_cmp_ge_i32_e32 vcc, v138, v130
	v_cmp_le_i32_e64 s[2:3], v138, v152
	s_and_b64 vcc, vcc, s[2:3]
	v_or_b32_e32 v138, 35, v92
	v_cndmask_b32_e32 v90, v158, v90, vcc
	v_cmp_ge_i32_e32 vcc, v138, v130
	v_cmp_le_i32_e64 s[2:3], v138, v152
	s_and_b64 vcc, vcc, s[2:3]
	v_or_b32_e32 v138, 48, v92
	v_cndmask_b32_e32 v91, v158, v91, vcc
	v_cmp_ge_i32_e32 vcc, v138, v130
	v_cmp_le_i32_e64 s[2:3], v138, v152
	s_and_b64 vcc, vcc, s[2:3]
	v_or_b32_e32 v138, 49, v92
	v_max3_f32 v135, v80, s87, v81
	v_cndmask_b32_e32 v112, v158, v112, vcc
	v_cmp_ge_i32_e32 vcc, v138, v130
	v_cmp_le_i32_e64 s[2:3], v138, v152
	v_max3_f32 v135, v135, v82, v83
	s_and_b64 vcc, vcc, s[2:3]
	v_or_b32_e32 v138, 50, v92
	v_max3_f32 v135, v135, v84, v85
	v_cndmask_b32_e32 v113, v158, v113, vcc
	v_cmp_ge_i32_e32 vcc, v138, v130
	v_cmp_le_i32_e64 s[2:3], v138, v152
	v_max3_f32 v135, v135, v86, v87
	s_and_b64 vcc, vcc, s[2:3]
	v_or_b32_e32 v92, 51, v92
	v_max3_f32 v135, v135, v88, v89
	v_cndmask_b32_e32 v114, v158, v114, vcc
	v_cmp_ge_i32_e32 vcc, v92, v130
	v_cmp_le_i32_e64 s[2:3], v92, v152
	v_max3_f32 v135, v135, v90, v91
	s_and_b64 vcc, vcc, s[2:3]
	v_max3_f32 v135, v135, v112, v113
	v_cndmask_b32_e32 v92, v158, v115, vcc
	v_max3_f32 v115, v135, v114, v92
	v_mov_b32_e32 v135, v115
	s_nop 1
	v_permlane16_swap_b32_e32 v135, v115
	s_waitcnt lgkmcnt(0)
	v_max3_f32 v115, v115, v135, v158
	v_mov_b32_e32 v135, v115
	s_nop 1
	v_permlane32_swap_b32_e32 v135, v115
	s_waitcnt lgkmcnt(0)
	v_max3_f32 v115, v115, v135, v158
	v_cmp_lt_f32_e32 vcc, s86, v80
	v_max3_f32 v135, v133, v115, v158
	s_nop 0
	v_sub_f32_e32 v115, v80, v135
	v_exp_f32_e32 v115, v115
	v_sub_f32_e32 v138, v81, v135
	v_exp_f32_e32 v138, v138
	v_cndmask_b32_e32 v146, 0, v115, vcc
	v_cmp_lt_f32_e32 vcc, s86, v81
	v_sub_f32_e32 v81, v82, v135
	v_exp_f32_e32 v81, v81
	v_cndmask_b32_e32 v153, 0, v138, vcc
	v_sub_f32_e32 v115, v83, v135
	v_cmp_lt_f32_e32 vcc, s86, v82
	v_exp_f32_e32 v115, v115
	v_sub_f32_e32 v82, v85, v135
	v_cndmask_b32_e32 v162, 0, v81, vcc
	v_sub_f32_e32 v81, v84, v135
	v_exp_f32_e32 v81, v81
	v_exp_f32_e32 v82, v82
	v_cmp_lt_f32_e32 vcc, s86, v83
	v_add_f32_e32 v80, 0, v146
	v_add_f32_e32 v80, v153, v80
	v_cndmask_b32_e32 v163, 0, v115, vcc
	v_cmp_lt_f32_e32 vcc, s86, v84
	v_add_f32_e32 v80, v162, v80
	v_add_f32_e32 v80, v163, v80
	v_cndmask_b32_e32 v164, 0, v81, vcc
	v_cmp_lt_f32_e32 vcc, s86, v85
	v_sub_f32_e32 v81, v86, v135
	v_exp_f32_e32 v81, v81
	v_cndmask_b32_e32 v165, 0, v82, vcc
	v_sub_f32_e32 v82, v87, v135
	v_exp_f32_e32 v82, v82
	v_cmp_lt_f32_e32 vcc, s86, v86
	v_add_f32_e32 v80, v164, v80
	v_add_f32_e32 v80, v165, v80
	v_cndmask_b32_e32 v166, 0, v81, vcc
	v_cmp_lt_f32_e32 vcc, s86, v87
	v_sub_f32_e32 v81, v88, v135
	v_exp_f32_e32 v81, v81
	v_cndmask_b32_e32 v167, 0, v82, vcc
	v_sub_f32_e32 v82, v89, v135
	v_exp_f32_e32 v82, v82
	v_cmp_lt_f32_e32 vcc, s86, v88
	v_add_f32_e32 v80, v166, v80
	v_add_f32_e32 v80, v167, v80
	v_cndmask_b32_e32 v140, 0, v81, vcc
	v_cmp_lt_f32_e32 vcc, s86, v89
	v_sub_f32_e32 v81, v90, v135
	v_exp_f32_e32 v81, v81
	v_cndmask_b32_e32 v141, 0, v82, vcc
	v_sub_f32_e32 v82, v91, v135
	v_exp_f32_e32 v82, v82
	v_cmp_lt_f32_e32 vcc, s86, v90
	v_add_f32_e32 v80, v140, v80
	v_add_f32_e32 v80, v141, v80
	v_cndmask_b32_e32 v142, 0, v81, vcc
	v_cmp_lt_f32_e32 vcc, s86, v91
	v_sub_f32_e32 v81, v112, v135
	v_exp_f32_e32 v81, v81
	v_cndmask_b32_e32 v143, 0, v82, vcc
	v_sub_f32_e32 v82, v113, v135
	v_exp_f32_e32 v82, v82
	v_cmp_lt_f32_e32 vcc, s86, v112
	v_add_f32_e32 v80, v142, v80
	v_add_f32_e32 v80, v143, v80
	v_cndmask_b32_e32 v144, 0, v81, vcc
	v_cmp_lt_f32_e32 vcc, s86, v113
	v_sub_f32_e32 v81, v114, v135
	v_exp_f32_e32 v81, v81
	v_cndmask_b32_e32 v145, 0, v82, vcc
	v_sub_f32_e32 v82, v92, v135
	v_exp_f32_e32 v82, v82
	v_add_f32_e32 v80, v144, v80
	v_cmp_lt_f32_e32 vcc, s86, v114
	v_add_f32_e32 v80, v145, v80
	v_mov_b64_e32 v[86:87], v[14:15]
	v_cndmask_b32_e32 v147, 0, v81, vcc
	v_cmp_lt_f32_e32 vcc, s86, v92
	v_add_f32_e32 v80, v147, v80
	v_mov_b64_e32 v[90:91], v[22:23]
	v_cndmask_b32_e32 v155, 0, v82, vcc
	v_add_f32_e32 v80, v155, v80
	v_mov_b32_e32 v81, v80
	s_nop 1
	v_permlane16_swap_b32_e32 v81, v80
	v_sub_f32_e32 v82, v133, v135
	v_exp_f32_e32 v92, v82
	v_mov_b64_e32 v[114:115], v[46:47]
	v_mov_b64_e32 v[84:85], v[12:13]
	s_waitcnt lgkmcnt(0)
	v_add_f32_e32 v138, v80, v81
	v_mov_b32_e32 v168, v138
	s_nop 1
	v_permlane32_swap_b32_e32 v168, v138
	v_cmp_eq_f32_e32 vcc, 1.0, v92
	v_mov_b64_e32 v[82:83], v[6:7]
	s_cmp_eq_u64 vcc, exec
	v_mov_b64_e32 v[80:81], v[4:5]
	v_mov_b64_e32 v[88:89], v[20:21]
	v_mov_b64_e32 v[112:113], v[44:45]
	s_cbranch_scc1 .LBB0_1399
	v_pk_mul_f32 v[114:115], v[46:47], v[92:93] op_sel_hi:[1,0]
	v_pk_mul_f32 v[112:113], v[44:45], v[92:93] op_sel_hi:[1,0]
	v_pk_mul_f32 v[90:91], v[22:23], v[92:93] op_sel_hi:[1,0]
	v_pk_mul_f32 v[88:89], v[20:21], v[92:93] op_sel_hi:[1,0]
	v_pk_mul_f32 v[86:87], v[14:15], v[92:93] op_sel_hi:[1,0]
	v_pk_mul_f32 v[84:85], v[12:13], v[92:93] op_sel_hi:[1,0]
	v_pk_mul_f32 v[82:83], v[6:7], v[92:93] op_sel_hi:[1,0]
	v_pk_mul_f32 v[80:81], v[4:5], v[92:93] op_sel_hi:[1,0]

.LBB0_1405:
	s_cmp_lt_i32 s15, s78
	s_cselect_b64 s[2:3], -1, 0
	s_cmp_gt_i32 s14, s77
	s_cselect_b64 s[92:93], -1, 0
	s_or_b64 s[2:3], s[92:93], s[2:3]
	v_mov_b32_e32 v136, v196
	s_and_b64 vcc, exec, s[2:3]
	s_cbranch_vccnz .LBB0_1415
	v_cmp_ge_i32_e32 vcc, s14, v131
	v_cmp_le_i32_e64 s[2:3], s15, v154
	s_and_b64 s[2:3], vcc, s[2:3]
	v_and_b32_e32 v80, 15, v136
	s_waitcnt lgkmcnt(7)
	v_cndmask_b32_e64 v48, 0, 1, s[2:3]
	v_cmp_ne_u32_e32 vcc, 0, v48
	v_and_b32_e32 v48, 48, v136
	s_waitcnt lgkmcnt(1)
	v_add_u32_e32 v72, s13, v48
	v_mad_u32_u24 v68, v80, s88, v72
	ds_read_b128 v[48:51], v68
	ds_read_b128 v[52:55], v68 offset:64
	ds_read_b128 v[56:59], v68 offset:2304
	ds_read_b128 v[60:63], v68 offset:2368
	ds_read_b128 v[64:67], v68 offset:4608
	ds_read_b128 v[68:71], v68 offset:4672
	v_and_b32_e32 v92, 63, v136
	v_or_b32_e32 v81, 48, v92
	s_waitcnt lgkmcnt(6)
	v_mad_u32_u24 v76, v81, s88, v72
	ds_read_b128 v[72:75], v76
	ds_read_b128 v[76:79], v76 offset:64
	s_cmp_lg_u64 vcc, exec
	v_mul_u32_u24_e32 v137, 0x90, v80
	v_mul_u32_u24_e32 v134, 0x90, v81
	s_mov_b64 s[2:3], -1
	s_cbranch_scc0 .LBB0_1410
	s_waitcnt lgkmcnt(7)
	v_mfma_f32_16x16x32_bf16 v[80:83], v[48:51], v[104:107], 0
	v_lshrrev_b32_e32 v139, 4, v92
	v_lshl_or_b32 v92, v139, 2, s14
	v_cmp_ge_i32_e32 vcc, v92, v131
	s_waitcnt lgkmcnt(5)
	v_mfma_f32_16x16x32_bf16 v[84:87], v[56:59], v[104:107], 0
	v_cmp_le_i32_e64 s[2:3], v92, v154
	s_and_b64 vcc, vcc, s[2:3]
	v_or_b32_e32 v135, 1, v92
	s_waitcnt lgkmcnt(3)
	v_mfma_f32_16x16x32_bf16 v[88:91], v[64:67], v[104:107], 0
	v_cmp_lt_i32_e64 s[2:3], v92, v154
	v_or_b32_e32 v138, 2, v92
	s_waitcnt lgkmcnt(1)
	v_mfma_f32_16x16x32_bf16 v[112:115], v[72:75], v[104:107], 0
	v_mfma_f32_16x16x32_bf16 v[80:83], v[52:55], v[108:111], v[80:83]
	v_mfma_f32_16x16x32_bf16 v[84:87], v[60:63], v[108:111], v[84:87]
	v_mfma_f32_16x16x32_bf16 v[88:91], v[68:71], v[108:111], v[88:91]
	s_waitcnt lgkmcnt(0)
	v_mfma_f32_16x16x32_bf16 v[112:115], v[76:79], v[108:111], v[112:115]
	s_nop 7
	s_nop 7
	s_nop 3
	v_cndmask_b32_e32 v80, v158, v80, vcc
	v_cmp_ge_i32_e32 vcc, v135, v131
	s_and_b64 vcc, s[2:3], vcc
	v_cmp_le_i32_e64 s[2:3], v92, v152
	v_cndmask_b32_e32 v81, v158, v81, vcc
	v_cmp_ge_i32_e32 vcc, v138, v131
	s_and_b64 vcc, s[2:3], vcc
	v_or_b32_e32 v138, 3, v92
	v_cndmask_b32_e32 v82, v158, v82, vcc
	v_cmp_ge_i32_e32 vcc, v138, v131
	v_cmp_le_i32_e64 s[2:3], v138, v154
	s_and_b64 vcc, vcc, s[2:3]
	v_or_b32_e32 v138, 16, v92
	v_cndmask_b32_e32 v83, v158, v83, vcc
	v_cmp_ge_i32_e32 vcc, v138, v131
	v_cmp_le_i32_e64 s[2:3], v138, v154
	s_and_b64 vcc, vcc, s[2:3]
	v_or_b32_e32 v138, 17, v92
	v_cndmask_b32_e32 v84, v158, v84, vcc
	v_cmp_ge_i32_e32 vcc, v138, v131
	v_cmp_le_i32_e64 s[2:3], v138, v154
	s_and_b64 vcc, vcc, s[2:3]
	v_or_b32_e32 v138, 18, v92
	v_cndmask_b32_e32 v85, v158, v85, vcc
	v_cmp_ge_i32_e32 vcc, v138, v131
	v_cmp_le_i32_e64 s[2:3], v138, v154
	s_and_b64 vcc, vcc, s[2:3]
	v_or_b32_e32 v138, 19, v92
	v_cndmask_b32_e32 v86, v158, v86, vcc
	v_cmp_ge_i32_e32 vcc, v138, v131
	v_cmp_le_i32_e64 s[2:3], v138, v154
	s_and_b64 vcc, vcc, s[2:3]
	v_or_b32_e32 v138, 32, v92
	v_cndmask_b32_e32 v87, v158, v87, vcc
	v_cmp_ge_i32_e32 vcc, v138, v131
	v_cmp_le_i32_e64 s[2:3], v138, v154
	s_and_b64 vcc, vcc, s[2:3]
	v_or_b32_e32 v138, 33, v92
	v_cndmask_b32_e32 v88, v158, v88, vcc
	v_cmp_ge_i32_e32 vcc, v138, v131
	v_cmp_le_i32_e64 s[2:3], v138, v154
	s_and_b64 vcc, vcc, s[2:3]
	v_or_b32_e32 v138, 34, v92
	v_cndmask_b32_e32 v89, v158, v89, vcc
	v_cmp_ge_i32_e32 vcc, v138, v131
	v_cmp_le_i32_e64 s[2:3], v138, v154
	s_and_b64 vcc, vcc, s[2:3]
	v_or_b32_e32 v138, 35, v92
	v_cndmask_b32_e32 v90, v158, v90, vcc
	v_cmp_ge_i32_e32 vcc, v138, v131
	v_cmp_le_i32_e64 s[2:3], v138, v154
	s_and_b64 vcc, vcc, s[2:3]
	v_or_b32_e32 v138, 48, v92
	v_cndmask_b32_e32 v91, v158, v91, vcc
	v_cmp_ge_i32_e32 vcc, v138, v131
	v_cmp_le_i32_e64 s[2:3], v138, v154
	s_and_b64 vcc, vcc, s[2:3]
	v_or_b32_e32 v138, 49, v92
	v_max3_f32 v135, v80, s87, v81
	v_cndmask_b32_e32 v112, v158, v112, vcc
	v_cmp_ge_i32_e32 vcc, v138, v131
	v_cmp_le_i32_e64 s[2:3], v138, v154
	v_max3_f32 v135, v135, v82, v83
	s_and_b64 vcc, vcc, s[2:3]
	v_or_b32_e32 v138, 50, v92
	v_max3_f32 v135, v135, v84, v85
	v_cndmask_b32_e32 v113, v158, v113, vcc
	v_cmp_ge_i32_e32 vcc, v138, v131
	v_cmp_le_i32_e64 s[2:3], v138, v154
	v_max3_f32 v135, v135, v86, v87
	s_and_b64 vcc, vcc, s[2:3]
	v_or_b32_e32 v92, 51, v92
	v_max3_f32 v135, v135, v88, v89
	v_cndmask_b32_e32 v114, v158, v114, vcc
	v_cmp_ge_i32_e32 vcc, v92, v131
	v_cmp_le_i32_e64 s[2:3], v92, v154
	v_max3_f32 v135, v135, v90, v91
	s_and_b64 vcc, vcc, s[2:3]
	v_max3_f32 v135, v135, v112, v113
	v_cndmask_b32_e32 v92, v158, v115, vcc
	v_max3_f32 v115, v135, v114, v92
	v_mov_b32_e32 v135, v115
	s_nop 1
	v_permlane16_swap_b32_e32 v135, v115
	s_waitcnt lgkmcnt(0)
	v_max3_f32 v115, v115, v135, v158
	v_mov_b32_e32 v135, v115
	s_nop 1
	v_permlane32_swap_b32_e32 v135, v115
	s_waitcnt lgkmcnt(0)
	v_max3_f32 v115, v115, v135, v158
	v_cmp_lt_f32_e32 vcc, s86, v80
	v_max3_f32 v135, v95, v115, v158
	s_nop 0
	v_sub_f32_e32 v115, v80, v135
	v_exp_f32_e32 v115, v115
	v_sub_f32_e32 v138, v81, v135
	v_exp_f32_e32 v138, v138
	v_cndmask_b32_e32 v146, 0, v115, vcc
	v_cmp_lt_f32_e32 vcc, s86, v81
	v_sub_f32_e32 v81, v82, v135
	v_exp_f32_e32 v81, v81
	v_cndmask_b32_e32 v153, 0, v138, vcc
	v_sub_f32_e32 v115, v83, v135
	v_cmp_lt_f32_e32 vcc, s86, v82
	v_exp_f32_e32 v115, v115
	v_sub_f32_e32 v82, v85, v135
	v_cndmask_b32_e32 v162, 0, v81, vcc
	v_sub_f32_e32 v81, v84, v135
	v_exp_f32_e32 v81, v81
	v_exp_f32_e32 v82, v82
	v_cmp_lt_f32_e32 vcc, s86, v83
	v_add_f32_e32 v80, 0, v146
	v_add_f32_e32 v80, v153, v80
	v_cndmask_b32_e32 v163, 0, v115, vcc
	v_cmp_lt_f32_e32 vcc, s86, v84
	v_add_f32_e32 v80, v162, v80
	v_add_f32_e32 v80, v163, v80
	v_cndmask_b32_e32 v164, 0, v81, vcc
	v_cmp_lt_f32_e32 vcc, s86, v85
	v_sub_f32_e32 v81, v86, v135
	v_exp_f32_e32 v81, v81
	v_cndmask_b32_e32 v165, 0, v82, vcc
	v_sub_f32_e32 v82, v87, v135
	v_exp_f32_e32 v82, v82
	v_cmp_lt_f32_e32 vcc, s86, v86
	v_add_f32_e32 v80, v164, v80
	v_add_f32_e32 v80, v165, v80
	v_cndmask_b32_e32 v166, 0, v81, vcc
	v_cmp_lt_f32_e32 vcc, s86, v87
	v_sub_f32_e32 v81, v88, v135
	v_exp_f32_e32 v81, v81
	v_cndmask_b32_e32 v167, 0, v82, vcc
	v_sub_f32_e32 v82, v89, v135
	v_exp_f32_e32 v82, v82
	v_cmp_lt_f32_e32 vcc, s86, v88
	v_add_f32_e32 v80, v166, v80
	v_add_f32_e32 v80, v167, v80
	v_cndmask_b32_e32 v140, 0, v81, vcc
	v_cmp_lt_f32_e32 vcc, s86, v89
	v_sub_f32_e32 v81, v90, v135
	v_exp_f32_e32 v81, v81
	v_cndmask_b32_e32 v141, 0, v82, vcc
	v_sub_f32_e32 v82, v91, v135
	v_exp_f32_e32 v82, v82
	v_cmp_lt_f32_e32 vcc, s86, v90
	v_add_f32_e32 v80, v140, v80
	v_add_f32_e32 v80, v141, v80
	v_cndmask_b32_e32 v142, 0, v81, vcc
	v_cmp_lt_f32_e32 vcc, s86, v91
	v_sub_f32_e32 v81, v112, v135
	v_exp_f32_e32 v81, v81
	v_cndmask_b32_e32 v143, 0, v82, vcc
	v_sub_f32_e32 v82, v113, v135
	v_exp_f32_e32 v82, v82
	v_cmp_lt_f32_e32 vcc, s86, v112
	v_add_f32_e32 v80, v142, v80
	v_add_f32_e32 v80, v143, v80
	v_cndmask_b32_e32 v144, 0, v81, vcc
	v_cmp_lt_f32_e32 vcc, s86, v113
	v_sub_f32_e32 v81, v114, v135
	v_exp_f32_e32 v81, v81
	v_cndmask_b32_e32 v145, 0, v82, vcc
	v_sub_f32_e32 v82, v92, v135
	v_exp_f32_e32 v82, v82
	v_add_f32_e32 v80, v144, v80
	v_cmp_lt_f32_e32 vcc, s86, v114
	v_add_f32_e32 v80, v145, v80
	v_mov_b64_e32 v[86:87], v[10:11]
	v_cndmask_b32_e32 v147, 0, v81, vcc
	v_cmp_lt_f32_e32 vcc, s86, v92
	v_add_f32_e32 v80, v147, v80
	v_mov_b64_e32 v[90:91], v[18:19]
	v_cndmask_b32_e32 v155, 0, v82, vcc
	v_add_f32_e32 v80, v155, v80
	v_mov_b32_e32 v81, v80
	s_nop 1
	v_permlane16_swap_b32_e32 v81, v80
	v_sub_f32_e32 v82, v95, v135
	v_exp_f32_e32 v92, v82
	v_mov_b64_e32 v[114:115], v[42:43]
	v_mov_b64_e32 v[84:85], v[8:9]
	s_waitcnt lgkmcnt(0)
	v_add_f32_e32 v138, v80, v81
	v_mov_b32_e32 v168, v138
	s_nop 1
	v_permlane32_swap_b32_e32 v168, v138
	v_cmp_eq_f32_e32 vcc, 1.0, v92
	v_mov_b64_e32 v[82:83], v[2:3]
	s_cmp_eq_u64 vcc, exec
	v_mov_b64_e32 v[80:81], v[0:1]
	v_mov_b64_e32 v[88:89], v[16:17]
	v_mov_b64_e32 v[112:113], v[40:41]
	s_cbranch_scc1 .LBB0_1409
	v_pk_mul_f32 v[114:115], v[42:43], v[92:93] op_sel_hi:[1,0]
	v_pk_mul_f32 v[112:113], v[40:41], v[92:93] op_sel_hi:[1,0]
	v_pk_mul_f32 v[90:91], v[18:19], v[92:93] op_sel_hi:[1,0]
	v_pk_mul_f32 v[88:89], v[16:17], v[92:93] op_sel_hi:[1,0]
	v_pk_mul_f32 v[86:87], v[10:11], v[92:93] op_sel_hi:[1,0]
	v_pk_mul_f32 v[84:85], v[8:9], v[92:93] op_sel_hi:[1,0]
	v_pk_mul_f32 v[82:83], v[2:3], v[92:93] op_sel_hi:[1,0]
	v_pk_mul_f32 v[80:81], v[0:1], v[92:93] op_sel_hi:[1,0]

.LBB0_1415:
	s_cmp_lt_i32 s74, 0
	s_cbranch_scc1 .LBB0_1436
	s_lshl_b32 s14, s74, 6
	s_or_b32 s15, s14, 63
	s_cmp_lt_i32 s15, s0
	s_cselect_b64 s[2:3], -1, 0
	s_cmp_gt_i32 s14, s76
	s_cselect_b64 s[74:75], -1, 0
	s_or_b64 s[2:3], s[74:75], s[2:3]
	v_mov_b32_e32 v136, v196
	s_and_b64 vcc, exec, s[2:3]
	s_cbranch_vccnz .LBB0_1426
	v_cmp_ge_i32_e32 vcc, s14, v130
	v_cmp_le_i32_e64 s[2:3], s15, v152
	s_and_b64 s[2:3], vcc, s[2:3]
	v_and_b32_e32 v80, 15, v136
	s_waitcnt lgkmcnt(7)
	v_cndmask_b32_e64 v48, 0, 1, s[2:3]
	v_cmp_ne_u32_e32 vcc, 0, v48
	v_and_b32_e32 v48, 48, v136
	s_waitcnt lgkmcnt(1)
	v_add_u32_e32 v72, s13, v48
	v_mad_u32_u24 v68, v80, s88, v72
	ds_read_b128 v[48:51], v68 offset:9216
	ds_read_b128 v[52:55], v68 offset:9280
	ds_read_b128 v[56:59], v68 offset:11520
	ds_read_b128 v[60:63], v68 offset:11584
	ds_read_b128 v[64:67], v68 offset:13824
	ds_read_b128 v[68:71], v68 offset:13888
	v_and_b32_e32 v92, 63, v136
	v_or_b32_e32 v81, 48, v92
	s_waitcnt lgkmcnt(6)
	v_mad_u32_u24 v76, v81, s88, v72
	ds_read_b128 v[72:75], v76 offset:9216
	ds_read_b128 v[76:79], v76 offset:9280
	s_cmp_lg_u64 vcc, exec
	v_mul_u32_u24_e32 v137, 0x90, v80
	v_mul_u32_u24_e32 v134, 0x90, v81
	s_mov_b64 s[2:3], -1
	s_cbranch_scc0 .LBB0_1421
	s_waitcnt lgkmcnt(7)
	v_mfma_f32_16x16x32_bf16 v[80:83], v[48:51], v[96:99], 0
	v_lshrrev_b32_e32 v139, 4, v92
	v_lshl_or_b32 v92, v139, 2, s14
	v_cmp_ge_i32_e32 vcc, v92, v130
	s_waitcnt lgkmcnt(5)
	v_mfma_f32_16x16x32_bf16 v[84:87], v[56:59], v[96:99], 0
	v_cmp_le_i32_e64 s[2:3], v92, v152
	s_and_b64 vcc, vcc, s[2:3]
	v_or_b32_e32 v135, 1, v92
	s_waitcnt lgkmcnt(3)
	v_mfma_f32_16x16x32_bf16 v[88:91], v[64:67], v[96:99], 0
	v_cmp_lt_i32_e64 s[2:3], v92, v152
	v_or_b32_e32 v138, 2, v92
	s_waitcnt lgkmcnt(1)
	v_mfma_f32_16x16x32_bf16 v[112:115], v[72:75], v[96:99], 0
	v_mfma_f32_16x16x32_bf16 v[80:83], v[52:55], v[100:103], v[80:83]
	v_mfma_f32_16x16x32_bf16 v[84:87], v[60:63], v[100:103], v[84:87]
	v_mfma_f32_16x16x32_bf16 v[88:91], v[68:71], v[100:103], v[88:91]
	s_waitcnt lgkmcnt(0)
	v_mfma_f32_16x16x32_bf16 v[112:115], v[76:79], v[100:103], v[112:115]
	s_nop 7
	s_nop 7
	s_nop 3
	v_cndmask_b32_e32 v80, v158, v80, vcc
	v_cmp_ge_i32_e32 vcc, v135, v130
	s_and_b64 vcc, s[2:3], vcc
	v_cmp_le_i32_e64 s[2:3], v138, v152
	v_cndmask_b32_e32 v81, v158, v81, vcc
	v_cmp_ge_i32_e32 vcc, v138, v130
	s_and_b64 vcc, vcc, s[2:3]
	v_or_b32_e32 v138, 3, v92
	v_cndmask_b32_e32 v82, v158, v82, vcc
	v_cmp_ge_i32_e32 vcc, v138, v130
	v_cmp_le_i32_e64 s[2:3], v138, v152
	s_and_b64 vcc, vcc, s[2:3]
	v_or_b32_e32 v138, 16, v92
	v_cndmask_b32_e32 v83, v158, v83, vcc
	v_cmp_ge_i32_e32 vcc, v138, v130
	v_cmp_le_i32_e64 s[2:3], v138, v152
	s_and_b64 vcc, vcc, s[2:3]
	v_or_b32_e32 v138, 17, v92
	v_cndmask_b32_e32 v84, v158, v84, vcc
	v_cmp_ge_i32_e32 vcc, v138, v130
	v_cmp_le_i32_e64 s[2:3], v138, v152
	s_and_b64 vcc, vcc, s[2:3]
	v_or_b32_e32 v138, 18, v92
	v_cndmask_b32_e32 v85, v158, v85, vcc
	v_cmp_ge_i32_e32 vcc, v138, v130
	v_cmp_le_i32_e64 s[2:3], v138, v152
	s_and_b64 vcc, vcc, s[2:3]
	v_or_b32_e32 v138, 19, v92
	v_cndmask_b32_e32 v86, v158, v86, vcc
	v_cmp_ge_i32_e32 vcc, v138, v130
	v_cmp_le_i32_e64 s[2:3], v138, v152
	s_and_b64 vcc, vcc, s[2:3]
	v_or_b32_e32 v138, 32, v92
	v_cndmask_b32_e32 v87, v158, v87, vcc
	v_cmp_ge_i32_e32 vcc, v138, v130
	v_cmp_le_i32_e64 s[2:3], v138, v152
	s_and_b64 vcc, vcc, s[2:3]
	v_or_b32_e32 v138, 33, v92
	v_cndmask_b32_e32 v88, v158, v88, vcc
	v_cmp_ge_i32_e32 vcc, v138, v130
	v_cmp_le_i32_e64 s[2:3], v138, v152
	s_and_b64 vcc, vcc, s[2:3]
	v_or_b32_e32 v138, 34, v92
	v_cndmask_b32_e32 v89, v158, v89, vcc
	v_cmp_ge_i32_e32 vcc, v138, v130
	v_cmp_le_i32_e64 s[2:3], v138, v152
	s_and_b64 vcc, vcc, s[2:3]
	v_or_b32_e32 v138, 35, v92
	v_cndmask_b32_e32 v90, v158, v90, vcc
	v_cmp_ge_i32_e32 vcc, v138, v130
	v_cmp_le_i32_e64 s[2:3], v138, v152
	s_and_b64 vcc, vcc, s[2:3]
	v_or_b32_e32 v138, 48, v92
	v_cndmask_b32_e32 v91, v158, v91, vcc
	v_cmp_ge_i32_e32 vcc, v138, v130
	v_cmp_le_i32_e64 s[2:3], v138, v152
	s_and_b64 vcc, vcc, s[2:3]
	v_or_b32_e32 v138, 49, v92
	v_max3_f32 v135, v80, s87, v81
	v_cndmask_b32_e32 v112, v158, v112, vcc
	v_cmp_ge_i32_e32 vcc, v138, v130
	v_cmp_le_i32_e64 s[2:3], v138, v152
	v_max3_f32 v135, v135, v82, v83
	s_and_b64 vcc, vcc, s[2:3]
	v_or_b32_e32 v138, 50, v92
	v_max3_f32 v135, v135, v84, v85
	v_cndmask_b32_e32 v113, v158, v113, vcc
	v_cmp_ge_i32_e32 vcc, v138, v130
	v_cmp_le_i32_e64 s[2:3], v138, v152
	v_max3_f32 v135, v135, v86, v87
	s_and_b64 vcc, vcc, s[2:3]
	v_or_b32_e32 v92, 51, v92
	v_max3_f32 v135, v135, v88, v89
	v_cndmask_b32_e32 v114, v158, v114, vcc
	v_cmp_ge_i32_e32 vcc, v92, v130
	v_cmp_le_i32_e64 s[2:3], v92, v152
	v_max3_f32 v135, v135, v90, v91
	s_and_b64 vcc, vcc, s[2:3]
	v_max3_f32 v135, v135, v112, v113
	v_cndmask_b32_e32 v92, v158, v115, vcc
	v_max3_f32 v115, v135, v114, v92
	v_mov_b32_e32 v135, v115
	s_nop 1
	v_permlane16_swap_b32_e32 v135, v115
	s_waitcnt lgkmcnt(0)
	v_max3_f32 v115, v115, v135, v158
	v_mov_b32_e32 v135, v115
	s_nop 1
	v_permlane32_swap_b32_e32 v135, v115
	s_waitcnt lgkmcnt(0)
	v_max3_f32 v115, v115, v135, v158
	v_cmp_lt_f32_e32 vcc, s86, v80
	v_max3_f32 v135, v133, v115, v158
	s_nop 0
	v_sub_f32_e32 v115, v80, v135
	v_exp_f32_e32 v115, v115
	v_sub_f32_e32 v138, v81, v135
	v_exp_f32_e32 v138, v138
	v_cndmask_b32_e32 v146, 0, v115, vcc
	v_cmp_lt_f32_e32 vcc, s86, v81
	v_sub_f32_e32 v81, v82, v135
	v_exp_f32_e32 v81, v81
	v_cndmask_b32_e32 v153, 0, v138, vcc
	v_sub_f32_e32 v115, v83, v135
	v_cmp_lt_f32_e32 vcc, s86, v82
	v_exp_f32_e32 v115, v115
	v_sub_f32_e32 v82, v85, v135
	v_cndmask_b32_e32 v162, 0, v81, vcc
	v_sub_f32_e32 v81, v84, v135
	v_exp_f32_e32 v81, v81
	v_exp_f32_e32 v82, v82
	v_cmp_lt_f32_e32 vcc, s86, v83
	v_add_f32_e32 v80, 0, v146
	v_add_f32_e32 v80, v153, v80
	v_cndmask_b32_e32 v163, 0, v115, vcc
	v_cmp_lt_f32_e32 vcc, s86, v84
	v_add_f32_e32 v80, v162, v80
	v_add_f32_e32 v80, v163, v80
	v_cndmask_b32_e32 v164, 0, v81, vcc
	v_cmp_lt_f32_e32 vcc, s86, v85
	v_sub_f32_e32 v81, v86, v135
	v_exp_f32_e32 v81, v81
	v_cndmask_b32_e32 v165, 0, v82, vcc
	v_sub_f32_e32 v82, v87, v135
	v_exp_f32_e32 v82, v82
	v_cmp_lt_f32_e32 vcc, s86, v86
	v_add_f32_e32 v80, v164, v80
	v_add_f32_e32 v80, v165, v80
	v_cndmask_b32_e32 v166, 0, v81, vcc
	v_cmp_lt_f32_e32 vcc, s86, v87
	v_sub_f32_e32 v81, v88, v135
	v_exp_f32_e32 v81, v81
	v_cndmask_b32_e32 v167, 0, v82, vcc
	v_sub_f32_e32 v82, v89, v135
	v_exp_f32_e32 v82, v82
	v_cmp_lt_f32_e32 vcc, s86, v88
	v_add_f32_e32 v80, v166, v80
	v_add_f32_e32 v80, v167, v80
	v_cndmask_b32_e32 v140, 0, v81, vcc
	v_cmp_lt_f32_e32 vcc, s86, v89
	v_sub_f32_e32 v81, v90, v135
	v_exp_f32_e32 v81, v81
	v_cndmask_b32_e32 v141, 0, v82, vcc
	v_sub_f32_e32 v82, v91, v135
	v_exp_f32_e32 v82, v82
	v_cmp_lt_f32_e32 vcc, s86, v90
	v_add_f32_e32 v80, v140, v80
	v_add_f32_e32 v80, v141, v80
	v_cndmask_b32_e32 v142, 0, v81, vcc
	v_cmp_lt_f32_e32 vcc, s86, v91
	v_sub_f32_e32 v81, v112, v135
	v_exp_f32_e32 v81, v81
	v_cndmask_b32_e32 v143, 0, v82, vcc
	v_sub_f32_e32 v82, v113, v135
	v_exp_f32_e32 v82, v82
	v_cmp_lt_f32_e32 vcc, s86, v112
	v_add_f32_e32 v80, v142, v80
	v_add_f32_e32 v80, v143, v80
	v_cndmask_b32_e32 v144, 0, v81, vcc
	v_cmp_lt_f32_e32 vcc, s86, v113
	v_sub_f32_e32 v81, v114, v135
	v_exp_f32_e32 v81, v81
	v_cndmask_b32_e32 v145, 0, v82, vcc
	v_sub_f32_e32 v82, v92, v135
	v_exp_f32_e32 v82, v82
	v_add_f32_e32 v80, v144, v80
	v_cmp_lt_f32_e32 vcc, s86, v114
	v_add_f32_e32 v80, v145, v80
	v_mov_b64_e32 v[86:87], v[14:15]
	v_cndmask_b32_e32 v147, 0, v81, vcc
	v_cmp_lt_f32_e32 vcc, s86, v92
	v_add_f32_e32 v80, v147, v80
	v_mov_b64_e32 v[90:91], v[22:23]
	v_cndmask_b32_e32 v155, 0, v82, vcc
	v_add_f32_e32 v80, v155, v80
	v_mov_b32_e32 v81, v80
	s_nop 1
	v_permlane16_swap_b32_e32 v81, v80
	v_sub_f32_e32 v82, v133, v135
	v_exp_f32_e32 v92, v82
	v_mov_b64_e32 v[114:115], v[46:47]
	v_mov_b64_e32 v[84:85], v[12:13]
	s_waitcnt lgkmcnt(0)
	v_add_f32_e32 v138, v80, v81
	v_mov_b32_e32 v168, v138
	s_nop 1
	v_permlane32_swap_b32_e32 v168, v138
	v_cmp_eq_f32_e32 vcc, 1.0, v92
	v_mov_b64_e32 v[82:83], v[6:7]
	s_cmp_eq_u64 vcc, exec
	v_mov_b64_e32 v[80:81], v[4:5]
	v_mov_b64_e32 v[88:89], v[20:21]
	v_mov_b64_e32 v[112:113], v[44:45]
	s_cbranch_scc1 .LBB0_1420
	v_pk_mul_f32 v[114:115], v[46:47], v[92:93] op_sel_hi:[1,0]
	v_pk_mul_f32 v[112:113], v[44:45], v[92:93] op_sel_hi:[1,0]
	v_pk_mul_f32 v[90:91], v[22:23], v[92:93] op_sel_hi:[1,0]
	v_pk_mul_f32 v[88:89], v[20:21], v[92:93] op_sel_hi:[1,0]
	v_pk_mul_f32 v[86:87], v[14:15], v[92:93] op_sel_hi:[1,0]
	v_pk_mul_f32 v[84:85], v[12:13], v[92:93] op_sel_hi:[1,0]
	v_pk_mul_f32 v[82:83], v[6:7], v[92:93] op_sel_hi:[1,0]
	v_pk_mul_f32 v[80:81], v[4:5], v[92:93] op_sel_hi:[1,0]

.LBB0_1426:
	s_cmp_lt_i32 s15, s78
	s_cselect_b64 s[2:3], -1, 0
	s_cmp_gt_i32 s14, s77
	s_cselect_b64 s[74:75], -1, 0
	s_or_b64 s[2:3], s[74:75], s[2:3]
	v_mov_b32_e32 v136, v196
	s_and_b64 vcc, exec, s[2:3]
	s_cbranch_vccnz .LBB0_1436
	v_cmp_ge_i32_e32 vcc, s14, v131
	v_cmp_le_i32_e64 s[2:3], s15, v154
	s_and_b64 s[2:3], vcc, s[2:3]
	v_and_b32_e32 v80, 15, v136
	s_waitcnt lgkmcnt(7)
	v_cndmask_b32_e64 v48, 0, 1, s[2:3]
	v_cmp_ne_u32_e32 vcc, 0, v48
	v_and_b32_e32 v48, 48, v136
	s_waitcnt lgkmcnt(1)
	v_add_u32_e32 v72, s13, v48
	v_mad_u32_u24 v68, v80, s88, v72
	ds_read_b128 v[48:51], v68 offset:9216
	ds_read_b128 v[52:55], v68 offset:9280
	ds_read_b128 v[56:59], v68 offset:11520
	ds_read_b128 v[60:63], v68 offset:11584
	ds_read_b128 v[64:67], v68 offset:13824
	ds_read_b128 v[68:71], v68 offset:13888
	v_and_b32_e32 v92, 63, v136
	v_or_b32_e32 v81, 48, v92
	s_waitcnt lgkmcnt(6)
	v_mad_u32_u24 v76, v81, s88, v72
	ds_read_b128 v[72:75], v76 offset:9216
	ds_read_b128 v[76:79], v76 offset:9280
	s_cmp_lg_u64 vcc, exec
	v_mul_u32_u24_e32 v137, 0x90, v80
	v_mul_u32_u24_e32 v134, 0x90, v81
	s_mov_b64 s[2:3], -1
	s_cbranch_scc0 .LBB0_1431
	s_waitcnt lgkmcnt(7)
	v_mfma_f32_16x16x32_bf16 v[80:83], v[48:51], v[104:107], 0
	v_lshrrev_b32_e32 v139, 4, v92
	v_lshl_or_b32 v92, v139, 2, s14
	v_cmp_ge_i32_e32 vcc, v92, v131
	s_waitcnt lgkmcnt(5)
	v_mfma_f32_16x16x32_bf16 v[84:87], v[56:59], v[104:107], 0
	v_cmp_le_i32_e64 s[2:3], v92, v154
	s_and_b64 vcc, vcc, s[2:3]
	v_or_b32_e32 v135, 1, v92
	s_waitcnt lgkmcnt(3)
	v_mfma_f32_16x16x32_bf16 v[88:91], v[64:67], v[104:107], 0
	v_cmp_lt_i32_e64 s[2:3], v92, v154
	v_or_b32_e32 v138, 2, v92
	s_waitcnt lgkmcnt(1)
	v_mfma_f32_16x16x32_bf16 v[112:115], v[72:75], v[104:107], 0
	v_mfma_f32_16x16x32_bf16 v[80:83], v[52:55], v[108:111], v[80:83]
	v_mfma_f32_16x16x32_bf16 v[84:87], v[60:63], v[108:111], v[84:87]
	v_mfma_f32_16x16x32_bf16 v[88:91], v[68:71], v[108:111], v[88:91]
	s_waitcnt lgkmcnt(0)
	v_mfma_f32_16x16x32_bf16 v[112:115], v[76:79], v[108:111], v[112:115]
	s_nop 7
	s_nop 7
	s_nop 3
	v_cndmask_b32_e32 v80, v158, v80, vcc
	v_cmp_ge_i32_e32 vcc, v135, v131
	s_and_b64 vcc, s[2:3], vcc
	v_cmp_le_i32_e64 s[2:3], v92, v152
	v_cndmask_b32_e32 v81, v158, v81, vcc
	v_cmp_ge_i32_e32 vcc, v138, v131
	s_and_b64 vcc, s[2:3], vcc
	v_or_b32_e32 v138, 3, v92
	v_cndmask_b32_e32 v82, v158, v82, vcc
	v_cmp_ge_i32_e32 vcc, v138, v131
	v_cmp_le_i32_e64 s[2:3], v138, v154
	s_and_b64 vcc, vcc, s[2:3]
	v_or_b32_e32 v138, 16, v92
	v_cndmask_b32_e32 v83, v158, v83, vcc
	v_cmp_ge_i32_e32 vcc, v138, v131
	v_cmp_le_i32_e64 s[2:3], v138, v154
	s_and_b64 vcc, vcc, s[2:3]
	v_or_b32_e32 v138, 17, v92
	v_cndmask_b32_e32 v84, v158, v84, vcc
	v_cmp_ge_i32_e32 vcc, v138, v131
	v_cmp_le_i32_e64 s[2:3], v138, v154
	s_and_b64 vcc, vcc, s[2:3]
	v_or_b32_e32 v138, 18, v92
	v_cndmask_b32_e32 v85, v158, v85, vcc
	v_cmp_ge_i32_e32 vcc, v138, v131
	v_cmp_le_i32_e64 s[2:3], v138, v154
	s_and_b64 vcc, vcc, s[2:3]
	v_or_b32_e32 v138, 19, v92
	v_cndmask_b32_e32 v86, v158, v86, vcc
	v_cmp_ge_i32_e32 vcc, v138, v131
	v_cmp_le_i32_e64 s[2:3], v138, v154
	s_and_b64 vcc, vcc, s[2:3]
	v_or_b32_e32 v138, 32, v92
	v_cndmask_b32_e32 v87, v158, v87, vcc
	v_cmp_ge_i32_e32 vcc, v138, v131
	v_cmp_le_i32_e64 s[2:3], v138, v154
	s_and_b64 vcc, vcc, s[2:3]
	v_or_b32_e32 v138, 33, v92
	v_cndmask_b32_e32 v88, v158, v88, vcc
	v_cmp_ge_i32_e32 vcc, v138, v131
	v_cmp_le_i32_e64 s[2:3], v138, v154
	s_and_b64 vcc, vcc, s[2:3]
	v_or_b32_e32 v138, 34, v92
	v_cndmask_b32_e32 v89, v158, v89, vcc
	v_cmp_ge_i32_e32 vcc, v138, v131
	v_cmp_le_i32_e64 s[2:3], v138, v154
	s_and_b64 vcc, vcc, s[2:3]
	v_or_b32_e32 v138, 35, v92
	v_cndmask_b32_e32 v90, v158, v90, vcc
	v_cmp_ge_i32_e32 vcc, v138, v131
	v_cmp_le_i32_e64 s[2:3], v138, v154
	s_and_b64 vcc, vcc, s[2:3]
	v_or_b32_e32 v138, 48, v92
	v_cndmask_b32_e32 v91, v158, v91, vcc
	v_cmp_ge_i32_e32 vcc, v138, v131
	v_cmp_le_i32_e64 s[2:3], v138, v154
	s_and_b64 vcc, vcc, s[2:3]
	v_or_b32_e32 v138, 49, v92
	v_max3_f32 v135, v80, s87, v81
	v_cndmask_b32_e32 v112, v158, v112, vcc
	v_cmp_ge_i32_e32 vcc, v138, v131
	v_cmp_le_i32_e64 s[2:3], v138, v154
	v_max3_f32 v135, v135, v82, v83
	s_and_b64 vcc, vcc, s[2:3]
	v_or_b32_e32 v138, 50, v92
	v_max3_f32 v135, v135, v84, v85
	v_cndmask_b32_e32 v113, v158, v113, vcc
	v_cmp_ge_i32_e32 vcc, v138, v131
	v_cmp_le_i32_e64 s[2:3], v138, v154
	v_max3_f32 v135, v135, v86, v87
	s_and_b64 vcc, vcc, s[2:3]
	v_or_b32_e32 v92, 51, v92
	v_max3_f32 v135, v135, v88, v89
	v_cndmask_b32_e32 v114, v158, v114, vcc
	v_cmp_ge_i32_e32 vcc, v92, v131
	v_cmp_le_i32_e64 s[2:3], v92, v154
	v_max3_f32 v135, v135, v90, v91
	s_and_b64 vcc, vcc, s[2:3]
	v_max3_f32 v135, v135, v112, v113
	v_cndmask_b32_e32 v92, v158, v115, vcc
	v_max3_f32 v115, v135, v114, v92
	v_mov_b32_e32 v135, v115
	s_nop 1
	v_permlane16_swap_b32_e32 v135, v115
	s_waitcnt lgkmcnt(0)
	v_max3_f32 v115, v115, v135, v158
	v_mov_b32_e32 v135, v115
	s_nop 1
	v_permlane32_swap_b32_e32 v135, v115
	s_waitcnt lgkmcnt(0)
	v_max3_f32 v115, v115, v135, v158
	v_cmp_lt_f32_e32 vcc, s86, v80
	v_max3_f32 v135, v95, v115, v158
	s_nop 0
	v_sub_f32_e32 v115, v80, v135
	v_exp_f32_e32 v115, v115
	v_sub_f32_e32 v138, v81, v135
	v_exp_f32_e32 v138, v138
	v_cndmask_b32_e32 v146, 0, v115, vcc
	v_cmp_lt_f32_e32 vcc, s86, v81
	v_sub_f32_e32 v81, v82, v135
	v_exp_f32_e32 v81, v81
	v_cndmask_b32_e32 v153, 0, v138, vcc
	v_sub_f32_e32 v115, v83, v135
	v_cmp_lt_f32_e32 vcc, s86, v82
	v_exp_f32_e32 v115, v115
	v_sub_f32_e32 v82, v85, v135
	v_cndmask_b32_e32 v162, 0, v81, vcc
	v_sub_f32_e32 v81, v84, v135
	v_exp_f32_e32 v81, v81
	v_exp_f32_e32 v82, v82
	v_cmp_lt_f32_e32 vcc, s86, v83
	v_add_f32_e32 v80, 0, v146
	v_add_f32_e32 v80, v153, v80
	v_cndmask_b32_e32 v163, 0, v115, vcc
	v_cmp_lt_f32_e32 vcc, s86, v84
	v_add_f32_e32 v80, v162, v80
	v_add_f32_e32 v80, v163, v80
	v_cndmask_b32_e32 v164, 0, v81, vcc
	v_cmp_lt_f32_e32 vcc, s86, v85
	v_sub_f32_e32 v81, v86, v135
	v_exp_f32_e32 v81, v81
	v_cndmask_b32_e32 v165, 0, v82, vcc
	v_sub_f32_e32 v82, v87, v135
	v_exp_f32_e32 v82, v82
	v_cmp_lt_f32_e32 vcc, s86, v86
	v_add_f32_e32 v80, v164, v80
	v_add_f32_e32 v80, v165, v80
	v_cndmask_b32_e32 v166, 0, v81, vcc
	v_cmp_lt_f32_e32 vcc, s86, v87
	v_sub_f32_e32 v81, v88, v135
	v_exp_f32_e32 v81, v81
	v_cndmask_b32_e32 v167, 0, v82, vcc
	v_sub_f32_e32 v82, v89, v135
	v_exp_f32_e32 v82, v82
	v_cmp_lt_f32_e32 vcc, s86, v88
	v_add_f32_e32 v80, v166, v80
	v_add_f32_e32 v80, v167, v80
	v_cndmask_b32_e32 v140, 0, v81, vcc
	v_cmp_lt_f32_e32 vcc, s86, v89
	v_sub_f32_e32 v81, v90, v135
	v_exp_f32_e32 v81, v81
	v_cndmask_b32_e32 v141, 0, v82, vcc
	v_sub_f32_e32 v82, v91, v135
	v_exp_f32_e32 v82, v82
	v_cmp_lt_f32_e32 vcc, s86, v90
	v_add_f32_e32 v80, v140, v80
	v_add_f32_e32 v80, v141, v80
	v_cndmask_b32_e32 v142, 0, v81, vcc
	v_cmp_lt_f32_e32 vcc, s86, v91
	v_sub_f32_e32 v81, v112, v135
	v_exp_f32_e32 v81, v81
	v_cndmask_b32_e32 v143, 0, v82, vcc
	v_sub_f32_e32 v82, v113, v135
	v_exp_f32_e32 v82, v82
	v_cmp_lt_f32_e32 vcc, s86, v112
	v_add_f32_e32 v80, v142, v80
	v_add_f32_e32 v80, v143, v80
	v_cndmask_b32_e32 v144, 0, v81, vcc
	v_cmp_lt_f32_e32 vcc, s86, v113
	v_sub_f32_e32 v81, v114, v135
	v_exp_f32_e32 v81, v81
	v_cndmask_b32_e32 v145, 0, v82, vcc
	v_sub_f32_e32 v82, v92, v135
	v_exp_f32_e32 v82, v82
	v_add_f32_e32 v80, v144, v80
	v_cmp_lt_f32_e32 vcc, s86, v114
	v_add_f32_e32 v80, v145, v80
	v_mov_b64_e32 v[86:87], v[10:11]
	v_cndmask_b32_e32 v147, 0, v81, vcc
	v_cmp_lt_f32_e32 vcc, s86, v92
	v_add_f32_e32 v80, v147, v80
	v_mov_b64_e32 v[90:91], v[18:19]
	v_cndmask_b32_e32 v155, 0, v82, vcc
	v_add_f32_e32 v80, v155, v80
	v_mov_b32_e32 v81, v80
	s_nop 1
	v_permlane16_swap_b32_e32 v81, v80
	v_sub_f32_e32 v82, v95, v135
	v_exp_f32_e32 v92, v82
	v_mov_b64_e32 v[114:115], v[42:43]
	v_mov_b64_e32 v[84:85], v[8:9]
	s_waitcnt lgkmcnt(0)
	v_add_f32_e32 v138, v80, v81
	v_mov_b32_e32 v168, v138
	s_nop 1
	v_permlane32_swap_b32_e32 v168, v138
	v_cmp_eq_f32_e32 vcc, 1.0, v92
	v_mov_b64_e32 v[82:83], v[2:3]
	s_cmp_eq_u64 vcc, exec
	v_mov_b64_e32 v[80:81], v[0:1]
	v_mov_b64_e32 v[88:89], v[16:17]
	v_mov_b64_e32 v[112:113], v[40:41]
	s_cbranch_scc1 .LBB0_1430
	v_pk_mul_f32 v[114:115], v[42:43], v[92:93] op_sel_hi:[1,0]
	v_pk_mul_f32 v[112:113], v[40:41], v[92:93] op_sel_hi:[1,0]
	v_pk_mul_f32 v[90:91], v[18:19], v[92:93] op_sel_hi:[1,0]
	v_pk_mul_f32 v[88:89], v[16:17], v[92:93] op_sel_hi:[1,0]
	v_pk_mul_f32 v[86:87], v[10:11], v[92:93] op_sel_hi:[1,0]
	v_pk_mul_f32 v[84:85], v[8:9], v[92:93] op_sel_hi:[1,0]
	v_pk_mul_f32 v[82:83], v[2:3], v[92:93] op_sel_hi:[1,0]
	v_pk_mul_f32 v[80:81], v[0:1], v[92:93] op_sel_hi:[1,0]

.LBB0_1979:
	v_cndmask_b32_e32 v146, v146, v158, vcc
	v_cmp_le_i32_e32 vcc, v228, v180
	v_cmp_le_i32_e64 s[2:3], v175, v180
	s_nop 0
	v_cndmask_b32_e32 v147, v158, v147, vcc
	v_cmp_le_i32_e32 vcc, v229, v180
	v_cndmask_b32_e64 v142, v158, v142, s[2:3]
	v_cmp_lt_i32_e64 s[2:3], v175, v180
	v_cndmask_b32_e32 v148, v158, v148, vcc
	v_cmp_le_i32_e32 vcc, v230, v180
	v_cndmask_b32_e64 v143, v158, v143, s[2:3]
	v_cmp_le_i32_e64 s[2:3], v178, v180
	v_cndmask_b32_e32 v149, v158, v149, vcc
	v_cmp_le_i32_e32 vcc, v231, v180
	v_cndmask_b32_e64 v144, v158, v144, s[2:3]
	v_cmp_le_i32_e64 s[2:3], v227, v180
	v_cndmask_b32_e32 v150, v158, v150, vcc
	v_cmp_le_i32_e32 vcc, v232, v180
	v_max3_f32 v175, v142, s87, v143
	v_cndmask_b32_e64 v145, v158, v145, s[2:3]
	v_cndmask_b32_e32 v151, v158, v151, vcc
	v_cmp_le_i32_e32 vcc, v233, v180
	v_max3_f32 v175, v175, v144, v145
	v_max3_f32 v175, v175, v146, v147
	v_cndmask_b32_e32 v152, v158, v152, vcc
	v_cmp_le_i32_e32 vcc, v234, v180
	v_max3_f32 v175, v175, v148, v149
	v_max3_f32 v175, v175, v150, v151
	v_cndmask_b32_e32 v153, v158, v153, vcc
	v_cmp_le_i32_e32 vcc, v235, v180
	v_max3_f32 v175, v175, v152, v153
	s_nop 0
	v_cndmask_b32_e32 v154, v158, v154, vcc
	v_cmp_le_i32_e32 vcc, v236, v180
	s_nop 1
	v_cndmask_b32_e32 v155, v158, v155, vcc
	v_cmp_le_i32_e32 vcc, v237, v180
	v_max3_f32 v175, v175, v154, v155
	s_nop 0
	v_cndmask_b32_e32 v156, v158, v156, vcc
	v_cmp_le_i32_e32 vcc, v238, v180
	s_nop 1
	v_cndmask_b32_e32 v157, v158, v157, vcc
	v_max3_f32 v175, v175, v156, v157
	v_mov_b32_e32 v178, v175
	s_nop 1
	v_permlane16_swap_b32_e32 v178, v175
	s_waitcnt lgkmcnt(0)
	v_max3_f32 v175, v175, v178, v158
	v_mov_b32_e32 v178, v175
	s_nop 1
	v_permlane32_swap_b32_e32 v178, v175
	s_waitcnt lgkmcnt(0)
	v_max3_f32 v175, v175, v178, v158
	v_cmp_lt_f32_e32 vcc, s86, v142
	v_max3_f32 v175, v173, v175, v158
	s_nop 0
	v_sub_f32_e32 v178, v142, v175
	v_exp_f32_e32 v178, v178
	v_sub_f32_e32 v227, v143, v175
	v_exp_f32_e32 v227, v227
	v_cndmask_b32_e32 v235, 0, v178, vcc
	v_cmp_lt_f32_e32 vcc, s86, v143
	v_sub_f32_e32 v143, v144, v175
	v_exp_f32_e32 v143, v143
	v_cndmask_b32_e32 v236, 0, v227, vcc
	v_sub_f32_e32 v178, v145, v175
	v_cmp_lt_f32_e32 vcc, s86, v144
	v_exp_f32_e32 v178, v178
	v_sub_f32_e32 v144, v147, v175
	v_cndmask_b32_e32 v237, 0, v143, vcc
	v_sub_f32_e32 v143, v146, v175
	v_exp_f32_e32 v143, v143
	v_exp_f32_e32 v144, v144
	v_cmp_lt_f32_e32 vcc, s86, v145
	v_add_f32_e32 v142, 0, v235
	v_add_f32_e32 v142, v236, v142
	v_cndmask_b32_e32 v238, 0, v178, vcc
	v_cmp_lt_f32_e32 vcc, s86, v146
	v_add_f32_e32 v142, v237, v142
	v_add_f32_e32 v142, v238, v142
	v_cndmask_b32_e32 v239, 0, v143, vcc
	v_cmp_lt_f32_e32 vcc, s86, v147
	v_sub_f32_e32 v143, v148, v175
	v_exp_f32_e32 v143, v143
	v_cndmask_b32_e32 v240, 0, v144, vcc
	v_sub_f32_e32 v144, v149, v175
	v_exp_f32_e32 v144, v144
	v_cmp_lt_f32_e32 vcc, s86, v148
	v_add_f32_e32 v142, v239, v142
	v_add_f32_e32 v142, v240, v142
	v_cndmask_b32_e32 v241, 0, v143, vcc
	v_cmp_lt_f32_e32 vcc, s86, v149
	v_sub_f32_e32 v143, v150, v175
	v_exp_f32_e32 v143, v143
	v_cndmask_b32_e32 v242, 0, v144, vcc
	v_sub_f32_e32 v144, v151, v175
	v_exp_f32_e32 v144, v144
	v_cmp_lt_f32_e32 vcc, s86, v150
	v_add_f32_e32 v142, v241, v142
	v_add_f32_e32 v142, v242, v142
	v_cndmask_b32_e32 v227, 0, v143, vcc
	v_cmp_lt_f32_e32 vcc, s86, v151
	v_sub_f32_e32 v143, v152, v175
	v_exp_f32_e32 v143, v143
	v_cndmask_b32_e32 v228, 0, v144, vcc
	v_sub_f32_e32 v144, v153, v175
	v_exp_f32_e32 v144, v144
	v_cmp_lt_f32_e32 vcc, s86, v152
	v_add_f32_e32 v142, v227, v142
	v_add_f32_e32 v142, v228, v142
	v_cndmask_b32_e32 v229, 0, v143, vcc
	v_cmp_lt_f32_e32 vcc, s86, v153
	v_sub_f32_e32 v143, v154, v175
	v_exp_f32_e32 v143, v143
	v_cndmask_b32_e32 v230, 0, v144, vcc
	v_sub_f32_e32 v144, v155, v175
	v_exp_f32_e32 v144, v144
	v_cmp_lt_f32_e32 vcc, s86, v154
	v_add_f32_e32 v142, v229, v142
	v_add_f32_e32 v142, v230, v142
	v_cndmask_b32_e32 v231, 0, v143, vcc
	v_cmp_lt_f32_e32 vcc, s86, v155
	v_sub_f32_e32 v143, v156, v175
	v_exp_f32_e32 v143, v143
	v_cndmask_b32_e32 v232, 0, v144, vcc
	v_sub_f32_e32 v144, v157, v175
	v_exp_f32_e32 v144, v144
	v_add_f32_e32 v142, v231, v142
	v_cmp_lt_f32_e32 vcc, s86, v156
	v_add_f32_e32 v142, v232, v142
	v_mov_b64_e32 v[148:149], v[22:23]
	v_cndmask_b32_e32 v233, 0, v143, vcc
	v_cmp_lt_f32_e32 vcc, s86, v157
	v_add_f32_e32 v142, v233, v142
	v_mov_b64_e32 v[152:153], v[26:27]
	v_cndmask_b32_e32 v234, 0, v144, vcc
	v_add_f32_e32 v142, v234, v142
	v_mov_b32_e32 v143, v142
	s_nop 1
	v_permlane16_swap_b32_e32 v143, v142
	v_sub_f32_e32 v144, v173, v175
	v_exp_f32_e32 v178, v144
	v_mov_b64_e32 v[156:157], v[66:67]
	v_mov_b64_e32 v[146:147], v[20:21]
	s_waitcnt lgkmcnt(0)
	v_add_f32_e32 v243, v142, v143
	v_mov_b32_e32 v177, v243
	s_nop 1
	v_permlane32_swap_b32_e32 v177, v243
	v_cmp_eq_f32_e32 vcc, 1.0, v178
	v_mov_b64_e32 v[144:145], v[18:19]
	s_cmp_eq_u64 vcc, exec
	v_mov_b64_e32 v[142:143], v[16:17]
	v_mov_b64_e32 v[150:151], v[24:25]
	v_mov_b64_e32 v[154:155], v[64:65]
	s_cbranch_scc1 .LBB0_1981
	v_pk_mul_f32 v[156:157], v[66:67], v[178:179] op_sel_hi:[1,0]
	v_pk_mul_f32 v[154:155], v[64:65], v[178:179] op_sel_hi:[1,0]
	v_pk_mul_f32 v[152:153], v[26:27], v[178:179] op_sel_hi:[1,0]
	v_pk_mul_f32 v[150:151], v[24:25], v[178:179] op_sel_hi:[1,0]
	v_pk_mul_f32 v[148:149], v[22:23], v[178:179] op_sel_hi:[1,0]
	v_pk_mul_f32 v[146:147], v[20:21], v[178:179] op_sel_hi:[1,0]
	v_pk_mul_f32 v[144:145], v[18:19], v[178:179] op_sel_hi:[1,0]
	v_pk_mul_f32 v[142:143], v[16:17], v[178:179] op_sel_hi:[1,0]

.LBB0_1982:
	s_and_b64 vcc, exec, s[2:3]
	s_cbranch_vccz .LBB0_1988
	s_waitcnt lgkmcnt(10)
	v_mfma_f32_16x16x32_bf16 v[126:129], v[122:125], v[32:35], 0
	v_cmp_lt_i32_e32 vcc, v205, v198
	v_mfma_f32_16x16x32_bf16 v[122:125], v[122:125], v[44:47], 0
	s_waitcnt lgkmcnt(9)
	v_mfma_f32_16x16x32_bf16 v[126:129], v[118:121], v[36:39], v[126:129]
	v_mfma_f32_16x16x32_bf16 v[118:121], v[118:121], v[48:51], v[122:125]
	s_waitcnt lgkmcnt(8)
	v_mfma_f32_16x16x32_bf16 v[122:125], v[114:117], v[40:43], v[126:129]
	v_mfma_f32_16x16x32_bf16 v[114:117], v[114:117], v[52:55], v[118:121]
	s_waitcnt lgkmcnt(7)
	v_mfma_f32_16x16x32_bf16 v[118:121], v[110:113], v[32:35], 0
	v_mfma_f32_16x16x32_bf16 v[110:113], v[110:113], v[44:47], 0
	s_waitcnt lgkmcnt(6)
	v_mfma_f32_16x16x32_bf16 v[118:121], v[106:109], v[36:39], v[118:121]
	v_mfma_f32_16x16x32_bf16 v[106:109], v[106:109], v[48:51], v[110:113]
	s_waitcnt lgkmcnt(5)
	v_mfma_f32_16x16x32_bf16 v[110:113], v[102:105], v[40:43], v[118:121]
	v_mfma_f32_16x16x32_bf16 v[102:105], v[102:105], v[52:55], v[106:109]
	s_waitcnt lgkmcnt(4)
	v_mfma_f32_16x16x32_bf16 v[106:109], v[98:101], v[32:35], 0
	v_mfma_f32_16x16x32_bf16 v[98:101], v[98:101], v[44:47], 0
	s_waitcnt lgkmcnt(3)
	v_mfma_f32_16x16x32_bf16 v[106:109], v[94:97], v[36:39], v[106:109]
	v_mfma_f32_16x16x32_bf16 v[94:97], v[94:97], v[48:51], v[98:101]
	s_waitcnt lgkmcnt(2)
	v_mfma_f32_16x16x32_bf16 v[126:129], v[88:91], v[40:43], v[106:109]
	v_mfma_f32_16x16x32_bf16 v[88:91], v[88:91], v[52:55], v[94:97]
	s_waitcnt lgkmcnt(1)
	v_mfma_f32_16x16x32_bf16 v[94:97], v[84:87], v[32:35], 0
	v_mfma_f32_16x16x32_bf16 v[84:87], v[84:87], v[44:47], 0
	s_waitcnt lgkmcnt(0)
	v_mfma_f32_16x16x32_bf16 v[94:97], v[80:83], v[36:39], v[94:97]
	v_mfma_f32_16x16x32_bf16 v[80:83], v[80:83], v[48:51], v[84:87]
	s_nop 4
	ds_read_b128 v[84:87], v190 offset:128
	s_waitcnt lgkmcnt(0)
	v_mfma_f32_16x16x32_bf16 v[94:97], v[84:87], v[40:43], v[94:97]
	s_nop 7
	s_nop 7
	v_mfma_f32_16x16x32_bf16 v[80:83], v[84:87], v[52:55], v[80:83]
	v_max3_f32 v84, v158, v122, v123
	v_cndmask_b32_e32 v85, v197, v205, vcc
	v_max3_f32 v84, v84, v124, v125
	v_lshlrev_b32_e32 v118, 2, v85
	v_max3_f32 v84, v84, v110, v111
	v_cmp_lt_i32_e32 vcc, v204, v198
	v_max3_f32 v84, v84, v112, v113
	s_nop 0
	v_max3_f32 v84, v84, v126, v127
	s_nop 0
	v_max3_f32 v84, v84, v128, v129
	s_nop 0
	v_max3_f32 v84, v84, v94, v95
	s_nop 0
	v_max3_f32 v84, v84, v96, v97
	v_mov_b32_e32 v85, v84
	s_nop 1
	v_permlane16_swap_b32_e32 v85, v84
	s_waitcnt lgkmcnt(0)
	v_max3_f32 v84, v84, v85, v158
	v_cndmask_b32_e32 v85, v197, v204, vcc
	v_lshlrev_b32_e32 v119, 2, v85
	v_mov_b32_e32 v85, v84
	s_nop 1
	v_permlane32_swap_b32_e32 v85, v84
	s_waitcnt lgkmcnt(0)
	v_max3_f32 v84, v84, v85, v158
	s_nop 0
	v_max3_f32 v174, v172, v84, v158
	s_nop 0
	v_sub_f32_e32 v84, v125, v174
	v_sub_f32_e32 v85, v124, v174
	v_sub_f32_e32 v86, v123, v174
	v_sub_f32_e32 v87, v122, v174
	v_exp_f32_e32 v98, v87
	v_exp_f32_e32 v99, v86
	v_exp_f32_e32 v100, v85
	v_exp_f32_e32 v101, v84
	v_sub_f32_e32 v109, v113, v174
	v_sub_f32_e32 v108, v112, v174
	v_sub_f32_e32 v107, v111, v174
	v_sub_f32_e32 v106, v110, v174
	v_exp_f32_e32 v106, v106
	v_exp_f32_e32 v107, v107
	v_exp_f32_e32 v108, v108
	v_exp_f32_e32 v109, v109
	v_pk_add_f32 v[84:85], v[98:99], 0 op_sel_hi:[1,0]
	v_pk_add_f32 v[86:87], v[100:101], 0 op_sel_hi:[1,0]
	v_pk_add_f32 v[112:113], v[106:107], v[84:85]
	v_pk_add_f32 v[110:111], v[108:109], v[86:87]
	v_sub_f32_e32 v87, v129, v174
	v_sub_f32_e32 v86, v128, v174
	v_sub_f32_e32 v85, v127, v174
	v_sub_f32_e32 v84, v126, v174
	v_exp_f32_e32 v84, v84
	v_exp_f32_e32 v85, v85
	v_exp_f32_e32 v86, v86
	v_exp_f32_e32 v87, v87
	v_sub_f32_e32 v97, v97, v174
	v_sub_f32_e32 v96, v96, v174
	v_sub_f32_e32 v95, v95, v174
	v_sub_f32_e32 v94, v94, v174
	v_exp_f32_e32 v94, v94
	v_exp_f32_e32 v95, v95
	v_exp_f32_e32 v96, v96
	v_exp_f32_e32 v97, v97
	v_pk_add_f32 v[112:113], v[84:85], v[112:113]
	v_pk_add_f32 v[110:111], v[86:87], v[110:111]
	v_pk_add_f32 v[112:113], v[94:95], v[112:113]
	v_pk_add_f32 v[110:111], v[96:97], v[110:111]
	v_sub_f32_e32 v92, v172, v174
	v_pk_mov_b32 v[120:121], v[112:113], v[110:111] op_sel:[1,0]
	v_mov_b32_e32 v113, v111
	v_pk_add_f32 v[110:111], v[120:121], v[112:113]
	v_exp_f32_e32 v92, v92
	v_add_f32_e32 v110, v110, v111
	v_mov_b32_e32 v111, v110
	s_nop 1
	v_permlane16_swap_b32_e32 v111, v110
	v_cmp_eq_f32_e32 vcc, 1.0, v92
	s_cmp_eq_u64 vcc, exec
	s_waitcnt lgkmcnt(0)
	v_add_f32_e32 v120, v110, v111
	v_mov_b32_e32 v121, v120
	s_nop 1
	v_permlane32_swap_b32_e32 v121, v120
	s_cbranch_scc1 .LBB0_1985
	v_pk_mul_f32 v[78:79], v[78:79], v[92:93] op_sel_hi:[1,0]
	v_pk_mul_f32 v[76:77], v[76:77], v[92:93] op_sel_hi:[1,0]
	v_pk_mul_f32 v[74:75], v[74:75], v[92:93] op_sel_hi:[1,0]
	v_pk_mul_f32 v[72:73], v[72:73], v[92:93] op_sel_hi:[1,0]
	v_pk_mul_f32 v[70:71], v[70:71], v[92:93] op_sel_hi:[1,0]
	v_pk_mul_f32 v[68:69], v[68:69], v[92:93] op_sel_hi:[1,0]
	v_pk_mul_f32 v[30:31], v[30:31], v[92:93] op_sel_hi:[1,0]
	v_pk_mul_f32 v[28:29], v[28:29], v[92:93] op_sel_hi:[1,0]
